# conv tap-loop LDS reads pipelined; G1: half of the workgroups run their half-tile first (staggered epilogue bursts); Q1 queue ticket order interleaves item types
# speedup vs baseline: 1.3705x; 1.3705x over previous
.LBB0_287:
	s_or_b64 exec, exec, s[0:1]
	v_readlane_b32 s0, v254, 23
	v_readlane_b32 s1, v254, 24
	s_andn2_b64 vcc, exec, s[0:1]
	s_mul_i32 s4, s46, 0xb00000
	s_waitcnt lgkmcnt(0)
	s_barrier
	v_readlane_b32 s98, v254, 0
	s_bfe_u32 s98, s98, 0x10003
	s_cmp_eq_u32 s98, 1
	s_cbranch_scc1 .LBB0_408
	s_cbranch_vccnz .Lg1_after_full
.Lg1_full_entry:
	s_mov_b32 s5, s85
	s_lshl_b64 s[0:1], s[4:5], 1
	v_readlane_b32 s2, v254, 25
	s_add_u32 s5, s2, s0
	v_readlane_b32 s0, v254, 26
	s_addc_u32 s47, s0, s1
	s_lshl_b32 s76, s46, 2
	v_readlane_b32 s77, v254, 0
	s_branch .LBB0_290

.Lg1_after_full:
	s_cmp_eq_u32 s98, 2
	s_cbranch_scc1 .LBB0_429
	s_branch .LBB0_408
.Lg1_after_half:
	s_cmp_eq_u32 s98, 1
	s_cbranch_scc0 .LBB0_429
	s_mov_b32 s98, 2
	s_mul_i32 s4, s46, 0xb00000
	s_branch .Lg1_full_entry

.LBB0_489:
	s_or_b64 exec, exec, s[0:1]
	s_waitcnt lgkmcnt(0)
	s_barrier
	ds_read_b32 v0, v1
	s_movk_i32 s0, 0x4ff
	s_waitcnt lgkmcnt(0)
	v_cmp_lt_i32_e32 vcc, s0, v0
	v_readfirstlane_b32 s30, v0
	s_mov_b64 s[0:1], -1
	s_cbranch_vccnz .LBB0_484
	s_cmpk_gt_u32 s30, 0x1ff
	s_cbranch_scc1 .Lq1_perm_hi
	s_and_b32 s2, s30, 1
	s_lshr_b32 s30, s30, 1
	s_lshl_b32 s2, s2, 9
	s_add_i32 s30, s30, s2
	s_branch .Lq1_perm_done
.Lq1_perm_hi:
	s_sub_u32 s2, s30, 0x200
	s_mul_hi_u32 s3, s2, 0xaaaaaaab
	s_lshr_b32 s3, s3, 1
	s_mul_i32 s30, s3, 3
	s_sub_u32 s2, s2, s30
	s_lshl_b32 s30, s2, 9
	s_add_i32 s30, s30, 0x100
	s_cmp_eq_u32 s2, 2
	s_cselect_b32 s2, 0x100, 0
	s_sub_u32 s30, s30, s2
	s_add_i32 s30, s30, s3
.Lq1_perm_done:
	v_mov_b32_e32 v0, v200
	s_cmpk_gt_i32 s30, 0xff
	v_ashrrev_i32_e32 v159, 8, v0
	s_cbranch_scc0 .LBB0_612
	s_cmpk_gt_u32 s30, 0x1ff
	s_cbranch_scc0 .LBB0_600
	s_cmpk_gt_u32 s30, 0x2ff
	s_cbranch_scc0 .LBB0_521
	s_lshl_b32 s31, s30, 1
	s_cmpk_gt_u32 s30, 0x3ff
	s_cbranch_scc0 .LBB0_509
	s_add_i32 s0, s31, 0xfffff800
	v_add_u32_e32 v0, s0, v159
	s_movk_i32 s0, 0x100
	v_lshlrev_b32_e32 v5, 5, v0
	v_cmp_gt_i32_e32 vcc, s0, v0
	v_mov_b32_e32 v0, 0x7ffffc00
	v_mov_b32_e32 v2, 0xffffff00
	v_mov_b32_e32 v4, v200
	v_cndmask_b32_e32 v0, v0, v2, vcc
	v_mov_b32_e32 v2, 0x400
	v_mov_b32_e32 v3, 0x100
	v_cndmask_b32_e32 v131, v2, v3, vcc
	v_lshrrev_b32_e32 v2, 1, v4
	v_and_b32_e32 v0, v0, v5
	v_and_b32_e32 v7, 24, v2
	v_mov_b64_e32 v[2:3], s[22:23]
	v_sub_u32_e32 v181, v5, v0
	v_mad_i64_i32 v[2:3], s[0:1], v0, s72, v[2:3]
	v_lshlrev_b32_e32 v0, 4, v4
	v_bfe_u32 v6, v4, 6, 2
	v_and_b32_e32 v0, 0xf0, v0
	v_lshl_or_b32 v0, v6, 8, v0
	v_lshl_add_u64 v[2:3], v[2:3], 0, v[0:1]
	s_mov_b64 s[0:1], 0x73800
	v_lshl_add_u64 v[32:33], v[2:3], 0, s[0:1]
	v_or_b32_e32 v2, v7, v5
	v_ashrrev_i32_e32 v3, 31, v2
	v_readlane_b32 s0, v254, 31
	v_lshlrev_b64 v[2:3], 10, v[2:3]
	v_readlane_b32 s1, v254, 32
	v_or_b32_e32 v167, v7, v181
	v_add_u32_e32 v179, -1, v131
	v_lshl_add_u64 v[2:3], s[0:1], 0, v[2:3]
	v_lshl_add_u64 v[30:31], v[2:3], 0, v[0:1]
	v_mov_b32_e32 v0, 63
	v_cmp_gt_u32_sdwa s[0:1], v4, v0 src0_sel:BYTE_0 src1_sel:DWORD
	s_and_saveexec_b64 s[2:3], s[0:1]
	s_xor_b64 s[88:89], exec, s[2:3]
	s_cbranch_execz .LBB0_506
	v_cmp_le_i32_e64 s[4:5], v167, v131
	v_cmp_lt_i32_e32 vcc, 1, v6
	s_mov_b64 s[74:75], 0
	s_mov_b64 s[0:1], 0
	s_and_saveexec_b64 s[2:3], vcc
	s_xor_b64 s[80:81], exec, s[2:3]
	s_cbranch_execz .LBB0_499
	v_cmp_eq_u32_e32 vcc, 2, v6
	s_mov_b64 s[0:1], -1
	s_and_saveexec_b64 s[82:83], vcc
	s_cbranch_execz .LBB0_498
	v_max_i32_e32 v0, 4, v167
	v_add_u32_e32 v2, -4, v0
	v_min_u32_e32 v2, v2, v179
	v_mad_u64_u32 v[2:3], s[0:1], v2, s72, v[32:33]
	global_load_dwordx4 v[2:5], v[2:3], off
	v_cmp_lt_i32_e32 vcc, 3, v167
	s_and_b64 vcc, vcc, s[4:5]
	v_or_b32_e32 v35, 1, v167
	v_or_b32_e32 v34, 2, v167
	v_or_b32_e32 v23, 3, v167
	v_or_b32_e32 v97, 4, v167
	v_or_b32_e32 v22, 5, v167
	v_or_b32_e32 v14, 6, v167
	v_or_b32_e32 v83, 7, v167
	v_add_u32_e32 v110, 8, v167
	v_add_u32_e32 v116, 9, v167
	v_add_u32_e32 v105, 10, v167
	s_waitcnt vmcnt(0)
	v_cndmask_b32_e32 v8, 0, v2, vcc
	v_add_u32_e32 v2, -3, v167
	v_cmp_lt_i32_e64 s[0:1], v2, v131
	v_max_i32_e32 v2, 0, v2
	v_cndmask_b32_e32 v9, 0, v3, vcc
	v_cndmask_b32_e32 v7, 0, v4, vcc
	v_cndmask_b32_e32 v6, 0, v5, vcc
	v_cmp_lt_i32_e32 vcc, 2, v167
	v_min_u32_e32 v2, v2, v179
	s_and_b64 vcc, vcc, s[0:1]
	v_mad_u64_u32 v[2:3], s[0:1], v2, s72, v[32:33]
	global_load_dwordx4 v[2:5], v[2:3], off
	v_lshlrev_b32_e32 v26, 16, v6
	v_and_b32_e32 v27, 0xffff0000, v6
	v_min_i32_e32 v6, v97, v131
	v_sub_u32_e32 v0, v6, v0
	v_add_u32_e32 v0, 4, v0
	v_cvt_f32_i32_e32 v0, v0
	s_waitcnt vmcnt(0)
	v_cndmask_b32_e32 v11, 0, v2, vcc
	v_max_i32_e32 v2, 2, v167
	v_add_u32_e32 v2, -2, v2
	v_min_u32_e32 v2, v2, v179
	v_cndmask_b32_e32 v12, 0, v3, vcc
	v_mad_u64_u32 v[2:3], s[0:1], v2, s72, v[32:33]
	v_cndmask_b32_e32 v13, 0, v4, vcc
	v_cndmask_b32_e32 v15, 0, v5, vcc
	global_load_dwordx4 v[2:5], v[2:3], off
	v_cmp_lt_i32_e32 vcc, 1, v167
	s_and_b64 vcc, vcc, s[4:5]
	v_lshlrev_b32_e32 v28, 16, v15
	v_and_b32_e32 v29, 0xffff0000, v15
	v_lshlrev_b32_e32 v10, 16, v11
	v_and_b32_e32 v11, 0xffff0000, v11
	v_lshlrev_b32_e32 v16, 16, v12
	v_and_b32_e32 v17, 0xffff0000, v12
	v_lshlrev_b32_e32 v12, 16, v13
	v_and_b32_e32 v13, 0xffff0000, v13
	s_waitcnt vmcnt(0)
	v_cndmask_b32_e32 v21, 0, v2, vcc
	v_max_i32_e32 v2, 1, v167
	v_add_u32_e32 v2, -1, v2
	v_min_u32_e32 v2, v2, v179
	v_cndmask_b32_e32 v20, 0, v3, vcc
	v_mad_u64_u32 v[2:3], s[0:1], v2, s72, v[32:33]
	v_cndmask_b32_e32 v19, 0, v4, vcc
	v_cndmask_b32_e32 v18, 0, v5, vcc
	global_load_dwordx4 v[2:5], v[2:3], off
	v_cmp_lt_i32_e32 vcc, 0, v167
	s_and_b64 vcc, vcc, s[4:5]
	v_cmp_lt_i32_e64 s[0:1], v167, v131
	v_lshlrev_b32_e32 v42, 16, v21
	v_and_b32_e32 v43, 0xffff0000, v21
	v_lshlrev_b32_e32 v24, 16, v20
	v_and_b32_e32 v25, 0xffff0000, v20
	v_lshlrev_b32_e32 v20, 16, v19
	v_and_b32_e32 v21, 0xffff0000, v19
	v_lshlrev_b32_e32 v46, 16, v18
	v_and_b32_e32 v47, 0xffff0000, v18
	s_waitcnt vmcnt(0)
	v_cndmask_b32_e32 v39, 0, v2, vcc
	v_max_i32_e32 v2, 0, v167
	v_cndmask_b32_e32 v38, 0, v3, vcc
	v_cndmask_b32_e32 v37, 0, v4, vcc
	v_cndmask_b32_e32 v36, 0, v5, vcc
	v_cmp_lt_i32_e32 vcc, -1, v181
	v_min_u32_e32 v2, v2, v179
	s_and_b64 vcc, vcc, s[0:1]
	v_mad_u64_u32 v[2:3], s[0:1], v2, s72, v[32:33]
	global_load_dwordx4 v[2:5], v[2:3], off
	v_cmp_lt_i32_e64 s[0:1], v35, v131
	v_lshlrev_b32_e32 v48, 16, v36
	v_and_b32_e32 v49, 0xffff0000, v36
	v_lshlrev_b32_e32 v58, 16, v37
	v_and_b32_e32 v59, 0xffff0000, v37
	v_lshlrev_b32_e32 v18, 16, v39
	v_and_b32_e32 v19, 0xffff0000, v39
	v_lshlrev_b32_e32 v44, 16, v38
	v_and_b32_e32 v45, 0xffff0000, v38
	s_waitcnt vmcnt(0)
	v_cndmask_b32_e32 v51, 0, v2, vcc
	v_max_i32_e32 v2, 0, v35
	v_cndmask_b32_e32 v50, 0, v3, vcc
	v_cndmask_b32_e32 v41, 0, v4, vcc
	v_cndmask_b32_e32 v40, 0, v5, vcc
	v_cmp_lt_i32_e32 vcc, -2, v167
	v_min_u32_e32 v2, v2, v179
	s_and_b64 vcc, vcc, s[0:1]
	v_mad_u64_u32 v[2:3], s[0:1], v2, s72, v[32:33]
	global_load_dwordx4 v[2:5], v[2:3], off
	v_cmp_lt_i32_e64 s[0:1], v34, v131
	v_lshlrev_b32_e32 v84, 16, v51
	v_and_b32_e32 v85, 0xffff0000, v51
	v_lshlrev_b32_e32 v70, 16, v50
	v_and_b32_e32 v71, 0xffff0000, v50
	v_lshlrev_b32_e32 v60, 16, v41
	v_and_b32_e32 v61, 0xffff0000, v41
	v_lshlrev_b32_e32 v50, 16, v40
	v_and_b32_e32 v51, 0xffff0000, v40
	s_waitcnt vmcnt(0)
	v_cndmask_b32_e32 v55, 0, v2, vcc
	v_max_i32_e32 v2, 0, v34
	v_cndmask_b32_e32 v54, 0, v3, vcc
	v_cndmask_b32_e32 v52, 0, v4, vcc
	v_cndmask_b32_e32 v53, 0, v5, vcc
	v_cmp_lt_i32_e32 vcc, -3, v167
	v_min_u32_e32 v2, v2, v179
	s_and_b64 vcc, vcc, s[0:1]
	v_mad_u64_u32 v[2:3], s[0:1], v2, s72, v[32:33]
	global_load_dwordx4 v[2:5], v[2:3], off
	v_cmp_lt_i32_e64 s[0:1], v23, v131
	v_lshlrev_b32_e32 v86, 16, v55
	v_and_b32_e32 v87, 0xffff0000, v55
	v_lshlrev_b32_e32 v72, 16, v54
	v_and_b32_e32 v73, 0xffff0000, v54
	v_lshlrev_b32_e32 v62, 16, v52
	v_and_b32_e32 v63, 0xffff0000, v52
	v_lshlrev_b32_e32 v52, 16, v53
	v_and_b32_e32 v53, 0xffff0000, v53
	s_waitcnt vmcnt(0)
	v_cndmask_b32_e32 v65, 0, v2, vcc
	v_max_i32_e32 v2, 0, v23
	v_cndmask_b32_e32 v64, 0, v3, vcc
	v_cndmask_b32_e32 v57, 0, v4, vcc
	v_cndmask_b32_e32 v56, 0, v5, vcc
	v_cmp_lt_i32_e32 vcc, -4, v167
	v_min_u32_e32 v2, v2, v179
	s_and_b64 vcc, vcc, s[0:1]
	v_mad_u64_u32 v[2:3], s[0:1], v2, s72, v[32:33]
	global_load_dwordx4 v[2:5], v[2:3], off
	v_cmp_lt_i32_e64 s[0:1], v97, v131
	v_lshlrev_b32_e32 v88, 16, v65
	v_and_b32_e32 v89, 0xffff0000, v65
	v_lshlrev_b32_e32 v74, 16, v64
	v_and_b32_e32 v75, 0xffff0000, v64
	v_lshlrev_b32_e32 v64, 16, v57
	v_and_b32_e32 v65, 0xffff0000, v57
	v_lshlrev_b32_e32 v54, 16, v56
	v_and_b32_e32 v55, 0xffff0000, v56
	s_waitcnt vmcnt(0)
	v_cndmask_b32_e32 v69, 0, v2, vcc
	v_max_i32_e32 v2, 0, v97
	v_cndmask_b32_e32 v68, 0, v3, vcc
	v_cndmask_b32_e32 v67, 0, v4, vcc
	v_cndmask_b32_e32 v66, 0, v5, vcc
	v_cmp_lt_i32_e32 vcc, -5, v167
	v_min_u32_e32 v2, v2, v179
	s_and_b64 vcc, vcc, s[0:1]
	v_mad_u64_u32 v[2:3], s[0:1], v2, s72, v[32:33]
	global_load_dwordx4 v[2:5], v[2:3], off
	v_cmp_lt_i32_e64 s[0:1], v22, v131
	v_lshlrev_b32_e32 v98, 16, v69
	v_and_b32_e32 v99, 0xffff0000, v69
	v_lshlrev_b32_e32 v80, 16, v68
	v_and_b32_e32 v81, 0xffff0000, v68
	v_lshlrev_b32_e32 v68, 16, v67
	v_and_b32_e32 v69, 0xffff0000, v67
	v_lshlrev_b32_e32 v56, 16, v66
	v_and_b32_e32 v57, 0xffff0000, v66
	s_waitcnt vmcnt(0)
	v_cndmask_b32_e32 v94, 0, v2, vcc
	v_max_i32_e32 v2, 0, v22
	v_cndmask_b32_e32 v76, 0, v3, vcc
	v_cndmask_b32_e32 v77, 0, v4, vcc
	v_cndmask_b32_e32 v82, 0, v5, vcc
	v_cmp_lt_i32_e32 vcc, -6, v167
	v_min_u32_e32 v2, v2, v179
	s_and_b64 vcc, vcc, s[0:1]
	v_mad_u64_u32 v[2:3], s[0:1], v2, s72, v[32:33]
	global_load_dwordx4 v[2:5], v[2:3], off
	v_cmp_lt_i32_e64 s[0:1], v14, v131
	v_lshlrev_b32_e32 v66, 16, v82
	v_and_b32_e32 v67, 0xffff0000, v82
	v_lshlrev_b32_e32 v106, 16, v94
	v_and_b32_e32 v107, 0xffff0000, v94
	v_lshlrev_b32_e32 v94, 16, v76
	v_and_b32_e32 v95, 0xffff0000, v76
	v_lshlrev_b32_e32 v76, 16, v77
	v_and_b32_e32 v77, 0xffff0000, v77
	s_waitcnt vmcnt(0)
	v_cndmask_b32_e32 v93, 0, v2, vcc
	v_max_i32_e32 v2, 0, v14
	v_cndmask_b32_e32 v92, 0, v3, vcc
	v_cndmask_b32_e32 v78, 0, v4, vcc
	v_cndmask_b32_e32 v79, 0, v5, vcc
	v_cmp_lt_i32_e32 vcc, -7, v167
	v_min_u32_e32 v2, v2, v179
	s_and_b64 vcc, vcc, s[0:1]
	v_mad_u64_u32 v[2:3], s[0:1], v2, s72, v[32:33]
	global_load_dwordx4 v[2:5], v[2:3], off
	v_cmp_lt_i32_e64 s[0:1], v83, v131
	v_lshlrev_b32_e32 v112, 16, v93
	v_and_b32_e32 v113, 0xffff0000, v93
	v_lshlrev_b32_e32 v102, 16, v92
	v_and_b32_e32 v103, 0xffff0000, v92
	v_lshlrev_b32_e32 v92, 16, v78
	v_and_b32_e32 v93, 0xffff0000, v78
	v_lshlrev_b32_e32 v78, 16, v79
	v_and_b32_e32 v79, 0xffff0000, v79
	s_waitcnt vmcnt(0)
	v_cndmask_b32_e32 v101, 0, v2, vcc
	v_max_i32_e32 v2, 0, v83
	v_cndmask_b32_e32 v100, 0, v3, vcc
	v_cndmask_b32_e32 v90, 0, v4, vcc
	v_cndmask_b32_e32 v91, 0, v5, vcc
	v_cmp_lt_i32_e32 vcc, -8, v167
	v_min_u32_e32 v2, v2, v179
	s_and_b64 vcc, vcc, s[0:1]
	v_mad_u64_u32 v[2:3], s[0:1], v2, s72, v[32:33]
	global_load_dwordx4 v[2:5], v[2:3], off
	v_cmp_lt_i32_e64 s[0:1], v110, v131
	v_lshlrev_b32_e32 v118, 16, v101
	v_and_b32_e32 v119, 0xffff0000, v101
	v_lshlrev_b32_e32 v108, 16, v100
	v_and_b32_e32 v109, 0xffff0000, v100
	v_lshlrev_b32_e32 v100, 16, v90
	v_and_b32_e32 v101, 0xffff0000, v90
	v_lshlrev_b32_e32 v90, 16, v91
	v_and_b32_e32 v91, 0xffff0000, v91
	s_waitcnt vmcnt(0)
	v_cndmask_b32_e32 v127, 0, v2, vcc
	v_max_i32_e32 v2, 0, v110
	v_cndmask_b32_e32 v126, 0, v3, vcc
	v_cndmask_b32_e32 v125, 0, v4, vcc
	v_cndmask_b32_e32 v124, 0, v5, vcc
	v_cmp_lt_i32_e32 vcc, -9, v167
	v_min_u32_e32 v2, v2, v179
	s_and_b64 vcc, vcc, s[0:1]
	v_mad_u64_u32 v[2:3], s[0:1], v2, s72, v[32:33]
	global_load_dwordx4 v[2:5], v[2:3], off
	v_cmp_lt_i32_e64 s[0:1], v116, v131
	v_lshlrev_b32_e32 v38, 16, v126
	v_and_b32_e32 v39, 0xffff0000, v126
	v_lshlrev_b32_e32 v40, 16, v125
	v_and_b32_e32 v41, 0xffff0000, v125
	s_waitcnt vmcnt(0)
	v_cndmask_b32_e32 v123, 0, v2, vcc
	v_max_i32_e32 v2, 0, v116
	v_cndmask_b32_e32 v122, 0, v3, vcc
	v_cndmask_b32_e32 v114, 0, v4, vcc
	v_cndmask_b32_e32 v115, 0, v5, vcc
	v_cmp_lt_i32_e32 vcc, -10, v167
	v_min_u32_e32 v2, v2, v179
	s_and_b64 vcc, vcc, s[0:1]
	v_mad_u64_u32 v[2:3], s[0:1], v2, s72, v[32:33]
	global_load_dwordx4 v[2:5], v[2:3], off
	v_cmp_lt_i32_e64 s[0:1], v105, v131
	v_lshlrev_b32_e32 v140, 16, v123
	v_and_b32_e32 v141, 0xffff0000, v123
	v_lshlrev_b32_e32 v132, 16, v122
	v_and_b32_e32 v133, 0xffff0000, v122
	v_lshlrev_b32_e32 v122, 16, v114
	v_and_b32_e32 v123, 0xffff0000, v114
	v_lshlrev_b32_e32 v114, 16, v115
	v_and_b32_e32 v115, 0xffff0000, v115
	s_waitcnt vmcnt(0)
	v_cndmask_b32_e32 v121, 0, v2, vcc
	v_max_i32_e32 v2, 0, v105
	v_cndmask_b32_e32 v120, 0, v3, vcc
	v_cndmask_b32_e32 v117, 0, v4, vcc
	v_cndmask_b32_e32 v111, 0, v5, vcc
	v_cmp_lt_i32_e32 vcc, -11, v167
	v_min_u32_e32 v2, v2, v179
	s_and_b64 vcc, vcc, s[0:1]
	v_mad_u64_u32 v[2:3], s[0:1], v2, s72, v[32:33]
	global_load_dwordx4 v[2:5], v[2:3], off
	v_div_scale_f32 v6, s[0:1], v0, v0, 1.0
	v_lshlrev_b32_e32 v142, 16, v121
	v_and_b32_e32 v143, 0xffff0000, v121
	v_lshlrev_b32_e32 v144, 16, v120
	v_and_b32_e32 v145, 0xffff0000, v120
	v_lshlrev_b32_e32 v128, 16, v117
	v_and_b32_e32 v129, 0xffff0000, v117
	v_lshlrev_b32_e32 v120, 16, v111
	v_and_b32_e32 v121, 0xffff0000, v111
	s_waitcnt vmcnt(0)
	v_cndmask_b32_e32 v135, 0, v4, vcc
	v_cndmask_b32_e32 v134, 0, v5, vcc
	v_lshlrev_b32_e32 v4, 16, v7
	v_and_b32_e32 v5, 0xffff0000, v7
	v_rcp_f32_e32 v7, v6
	v_cndmask_b32_e32 v137, 0, v2, vcc
	v_cndmask_b32_e32 v136, 0, v3, vcc
	v_lshlrev_b32_e32 v2, 16, v8
	v_fma_f32 v15, -v6, v7, 1.0
	v_fmac_f32_e32 v7, v15, v7
	v_div_scale_f32 v15, vcc, 1.0, v0, 1.0
	v_mul_f32_e32 v36, v15, v7
	v_fma_f32 v37, -v6, v36, v15
	v_fmac_f32_e32 v36, v37, v7
	v_fma_f32 v6, -v6, v36, v15
	v_div_fmas_f32 v6, v6, v7, v36
	v_div_fixup_f32 v0, v6, v0, 1.0
	v_max_i32_e32 v6, 4, v35
	v_min_i32_e32 v7, v22, v131
	v_sub_u32_e32 v6, v7, v6
	v_add_u32_e32 v6, 4, v6
	v_cvt_f32_i32_e32 v6, v6
	v_and_b32_e32 v3, 0xffff0000, v8
	v_lshlrev_b32_e32 v8, 16, v9
	v_and_b32_e32 v9, 0xffff0000, v9
	v_div_scale_f32 v7, s[0:1], v6, v6, 1.0
	v_rcp_f32_e32 v15, v7
	v_lshlrev_b32_e32 v146, 16, v137
	v_and_b32_e32 v147, 0xffff0000, v137
	v_and_b32_e32 v125, 0xffff0000, v134
	v_fma_f32 v35, -v7, v15, 1.0
	v_fmac_f32_e32 v15, v35, v15
	v_div_scale_f32 v35, vcc, 1.0, v6, 1.0
	v_mul_f32_e32 v36, v35, v15
	v_fma_f32 v37, -v7, v36, v35
	v_fmac_f32_e32 v36, v37, v15
	v_fma_f32 v7, -v7, v36, v35
	v_div_fmas_f32 v7, v7, v15, v36
	v_div_fixup_f32 v82, v7, v6, 1.0
	v_max_i32_e32 v6, 4, v34
	v_min_i32_e32 v7, v14, v131
	v_sub_u32_e32 v6, v7, v6
	v_add_u32_e32 v6, 4, v6
	v_cvt_f32_i32_e32 v6, v6
	v_and_b32_e32 v37, 0xffff0000, v124
	v_div_scale_f32 v7, s[0:1], v6, v6, 1.0
	v_rcp_f32_e32 v15, v7
	s_nop 0
	v_fma_f32 v34, -v7, v15, 1.0
	v_fmac_f32_e32 v15, v34, v15
	v_div_scale_f32 v34, vcc, 1.0, v6, 1.0
	v_mul_f32_e32 v35, v34, v15
	v_fma_f32 v36, -v7, v35, v34
	v_fmac_f32_e32 v35, v36, v15
	v_fma_f32 v7, -v7, v35, v34
	v_div_fmas_f32 v7, v7, v15, v35
	v_div_fixup_f32 v96, v7, v6, 1.0
	v_max_i32_e32 v6, 4, v23
	v_min_i32_e32 v7, v83, v131
	v_sub_u32_e32 v6, v7, v6
	v_add_u32_e32 v6, 4, v6
	v_cvt_f32_i32_e32 v6, v6
	v_lshlrev_b32_e32 v36, 16, v124
	v_lshlrev_b32_e32 v124, 16, v134
	v_div_scale_f32 v7, s[0:1], v6, v6, 1.0
	v_rcp_f32_e32 v15, v7
	s_nop 0
	v_fma_f32 v23, -v7, v15, 1.0
	v_fmac_f32_e32 v15, v23, v15
	v_div_scale_f32 v23, vcc, 1.0, v6, 1.0
	v_mul_f32_e32 v34, v23, v15
	v_fma_f32 v35, -v7, v34, v23
	v_fmac_f32_e32 v34, v35, v15
	v_fma_f32 v7, -v7, v34, v23
	v_div_fmas_f32 v7, v7, v15, v34
	v_div_fixup_f32 v104, v7, v6, 1.0
	v_max_i32_e32 v6, 4, v97
	v_min_i32_e32 v7, v110, v131
	v_sub_u32_e32 v6, v7, v6
	v_add_u32_e32 v6, 4, v6
	v_cvt_f32_i32_e32 v6, v6
	v_lshlrev_b32_e32 v34, 16, v127
	v_and_b32_e32 v35, 0xffff0000, v127
	v_div_scale_f32 v7, s[0:1], v6, v6, 1.0
	v_rcp_f32_e32 v15, v7
	s_nop 0
	v_fma_f32 v23, -v7, v15, 1.0
	v_fmac_f32_e32 v15, v23, v15
	v_div_scale_f32 v23, vcc, 1.0, v6, 1.0
	v_mul_f32_e32 v97, v23, v15
	v_fma_f32 v110, -v7, v97, v23
	v_fmac_f32_e32 v97, v110, v15
	v_fma_f32 v7, -v7, v97, v23
	v_div_fmas_f32 v7, v7, v15, v97
	v_div_fixup_f32 v110, v7, v6, 1.0
	v_max_i32_e32 v6, 4, v22
	v_min_i32_e32 v7, v116, v131
	v_sub_u32_e32 v6, v7, v6
	v_add_u32_e32 v6, 4, v6
	v_cvt_f32_i32_e32 v6, v6
	v_div_scale_f32 v7, s[0:1], v6, v6, 1.0
	v_rcp_f32_e32 v15, v7
	s_nop 0
	v_fma_f32 v22, -v7, v15, 1.0
	v_fmac_f32_e32 v15, v22, v15
	v_div_scale_f32 v22, vcc, 1.0, v6, 1.0
	v_mul_f32_e32 v23, v22, v15
	v_fma_f32 v97, -v7, v23, v22
	v_fmac_f32_e32 v23, v97, v15
	v_fma_f32 v7, -v7, v23, v22
	v_div_fmas_f32 v7, v7, v15, v23
	v_div_fixup_f32 v116, v7, v6, 1.0
	v_max_i32_e32 v6, 4, v14
	v_min_i32_e32 v7, v105, v131
	v_sub_u32_e32 v6, v7, v6
	v_add_u32_e32 v6, 4, v6
	v_cvt_f32_i32_e32 v6, v6
	v_div_scale_f32 v7, s[0:1], v6, v6, 1.0
	v_rcp_f32_e32 v14, v7
	s_xor_b64 s[0:1], exec, -1
	v_fma_f32 v15, -v7, v14, 1.0
	v_fmac_f32_e32 v14, v15, v14
	v_div_scale_f32 v15, vcc, 1.0, v6, 1.0
	v_mul_f32_e32 v22, v15, v14
	v_fma_f32 v23, -v7, v22, v15
	v_fmac_f32_e32 v22, v23, v14
	v_fma_f32 v7, -v7, v22, v15
	v_div_fmas_f32 v7, v7, v14, v22
	v_div_fixup_f32 v126, v7, v6, 1.0
	v_pk_add_f32 v[6:7], v[2:3], 0 op_sel_hi:[1,0]
	v_pk_add_f32 v[2:3], v[106:107], v[2:3] neg_lo:[0,1] neg_hi:[0,1]
	v_pk_add_f32 v[6:7], v[6:7], v[10:11]
	v_pk_add_f32 v[10:11], v[112:113], v[10:11] neg_lo:[0,1] neg_hi:[0,1]
	v_pk_add_f32 v[6:7], v[6:7], v[42:43]
	s_nop 0
	v_pk_add_f32 v[6:7], v[6:7], v[18:19]
	s_nop 0
	v_pk_add_f32 v[6:7], v[6:7], v[84:85]
	s_nop 0
	v_pk_add_f32 v[6:7], v[6:7], v[86:87]
	s_nop 0
	v_pk_add_f32 v[6:7], v[6:7], v[88:89]
	s_nop 0
	v_pk_add_f32 v[14:15], v[6:7], v[98:99]
	s_nop 0
	v_pk_add_f32 v[2:3], v[14:15], v[2:3]
	v_pk_fma_f32 v[6:7], v[0:1], v[14:15], v[84:85] op_sel_hi:[0,1,1] neg_lo:[0,0,1] neg_hi:[0,0,1]
	v_pk_fma_f32 v[14:15], v[82:83], v[2:3], v[86:87] op_sel_hi:[0,1,1] neg_lo:[0,0,1] neg_hi:[0,0,1]
	v_pk_add_f32 v[2:3], v[2:3], v[10:11]
	v_cvt_pk_bf16_f32 v6, v6, v7
	v_pk_fma_f32 v[10:11], v[96:97], v[2:3], v[88:89] op_sel_hi:[0,1,1] neg_lo:[0,0,1] neg_hi:[0,0,1]
	v_cvt_pk_bf16_f32 v22, v10, v11
	v_pk_add_f32 v[10:11], v[118:119], v[42:43] neg_lo:[0,1] neg_hi:[0,1]
	v_pk_add_f32 v[42:43], v[142:143], v[86:87] neg_lo:[0,1] neg_hi:[0,1]
	v_pk_add_f32 v[86:87], v[8:9], 0 op_sel_hi:[1,0]
	v_pk_add_f32 v[2:3], v[2:3], v[10:11]
	v_pk_add_f32 v[86:87], v[86:87], v[16:17]
	v_pk_add_f32 v[8:9], v[94:95], v[8:9] neg_lo:[0,1] neg_hi:[0,1]
	v_pk_add_f32 v[86:87], v[86:87], v[24:25]
	v_pk_fma_f32 v[10:11], v[104:105], v[2:3], v[98:99] op_sel_hi:[0,1,1] neg_lo:[0,0,1] neg_hi:[0,0,1]
	v_pk_add_f32 v[86:87], v[86:87], v[44:45]
	v_pk_add_f32 v[16:17], v[102:103], v[16:17] neg_lo:[0,1] neg_hi:[0,1]
	v_pk_add_f32 v[86:87], v[86:87], v[70:71]
	v_cvt_pk_bf16_f32 v138, v10, v11
	v_pk_add_f32 v[86:87], v[86:87], v[72:73]
	v_pk_add_f32 v[10:11], v[34:35], v[18:19] neg_lo:[0,1] neg_hi:[0,1]
	v_pk_add_f32 v[86:87], v[86:87], v[74:75]
	v_pk_add_f32 v[18:19], v[140:141], v[84:85] neg_lo:[0,1] neg_hi:[0,1]
	v_pk_add_f32 v[86:87], v[86:87], v[80:81]
	v_pk_add_f32 v[84:85], v[146:147], v[88:89] neg_lo:[0,1] neg_hi:[0,1]
	v_pk_add_f32 v[8:9], v[86:87], v[8:9]
	v_pk_fma_f32 v[88:89], v[0:1], v[86:87], v[70:71] op_sel_hi:[0,1,1] neg_lo:[0,0,1] neg_hi:[0,0,1]
	v_pk_fma_f32 v[86:87], v[82:83], v[8:9], v[72:73] op_sel_hi:[0,1,1] neg_lo:[0,0,1] neg_hi:[0,0,1]
	v_pk_add_f32 v[8:9], v[8:9], v[16:17]
	v_pk_add_f32 v[10:11], v[2:3], v[10:11]
	v_pk_fma_f32 v[16:17], v[96:97], v[8:9], v[74:75] op_sel_hi:[0,1,1] neg_lo:[0,0,1] neg_hi:[0,0,1]
	v_cvt_pk_bf16_f32 v23, v16, v17
	v_pk_add_f32 v[16:17], v[108:109], v[24:25] neg_lo:[0,1] neg_hi:[0,1]
	v_pk_fma_f32 v[2:3], v[110:111], v[10:11], v[106:107] op_sel_hi:[0,1,1] neg_lo:[0,0,1] neg_hi:[0,0,1]
	v_pk_add_f32 v[8:9], v[8:9], v[16:17]
	v_cvt_pk_bf16_f32 v2, v2, v3
	v_pk_fma_f32 v[16:17], v[104:105], v[8:9], v[80:81] op_sel_hi:[0,1,1] neg_lo:[0,0,1] neg_hi:[0,0,1]
	v_cvt_pk_bf16_f32 v139, v16, v17
	v_pk_add_f32 v[16:17], v[38:39], v[44:45] neg_lo:[0,1] neg_hi:[0,1]
	v_pk_add_f32 v[18:19], v[10:11], v[18:19]
	v_pk_add_f32 v[8:9], v[8:9], v[16:17]
	v_pk_fma_f32 v[10:11], v[116:117], v[18:19], v[112:113] op_sel_hi:[0,1,1] neg_lo:[0,0,1] neg_hi:[0,0,1]
	v_pk_fma_f32 v[16:17], v[110:111], v[8:9], v[94:95] op_sel_hi:[0,1,1] neg_lo:[0,0,1] neg_hi:[0,0,1]
	v_cvt_pk_bf16_f32 v3, v16, v17
	v_pk_add_f32 v[16:17], v[132:133], v[70:71] neg_lo:[0,1] neg_hi:[0,1]
	v_cvt_pk_bf16_f32 v10, v10, v11
	v_pk_add_f32 v[8:9], v[8:9], v[16:17]
	v_pk_add_f32 v[42:43], v[18:19], v[42:43]
	v_pk_fma_f32 v[16:17], v[116:117], v[8:9], v[102:103] op_sel_hi:[0,1,1] neg_lo:[0,0,1] neg_hi:[0,0,1]
	v_cvt_pk_bf16_f32 v11, v16, v17
	v_pk_add_f32 v[16:17], v[144:145], v[72:73] neg_lo:[0,1] neg_hi:[0,1]
	v_pk_fma_f32 v[18:19], v[126:127], v[42:43], v[118:119] op_sel_hi:[0,1,1] neg_lo:[0,0,1] neg_hi:[0,0,1]
	v_pk_add_f32 v[8:9], v[8:9], v[16:17]
	v_pk_add_f32 v[42:43], v[42:43], v[84:85]
	v_lshlrev_b32_e32 v84, 16, v136
	v_and_b32_e32 v85, 0xffff0000, v136
	v_pk_fma_f32 v[16:17], v[126:127], v[8:9], v[108:109] op_sel_hi:[0,1,1] neg_lo:[0,0,1] neg_hi:[0,0,1]
	v_cvt_pk_bf16_f32 v18, v18, v19
	v_cvt_pk_bf16_f32 v19, v16, v17
	v_pk_add_f32 v[16:17], v[84:85], v[74:75] neg_lo:[0,1] neg_hi:[0,1]
	v_lshlrev_b32_e32 v70, 16, v135
	v_pk_add_f32 v[44:45], v[8:9], v[16:17]
	v_pk_add_f32 v[8:9], v[4:5], 0 op_sel_hi:[1,0]
	v_pk_add_f32 v[4:5], v[76:77], v[4:5] neg_lo:[0,1] neg_hi:[0,1]
	v_pk_add_f32 v[8:9], v[8:9], v[12:13]
	v_pk_add_f32 v[12:13], v[92:93], v[12:13] neg_lo:[0,1] neg_hi:[0,1]
	v_pk_add_f32 v[8:9], v[8:9], v[20:21]
	v_and_b32_e32 v71, 0xffff0000, v135
	v_pk_add_f32 v[8:9], v[8:9], v[58:59]
	v_cvt_pk_bf16_f32 v7, v88, v89
	v_pk_add_f32 v[8:9], v[8:9], v[60:61]
	v_cvt_pk_bf16_f32 v14, v14, v15
	v_pk_add_f32 v[8:9], v[8:9], v[62:63]
	v_cvt_pk_bf16_f32 v15, v86, v87
	v_pk_add_f32 v[8:9], v[8:9], v[64:65]
	s_nop 0
	v_pk_add_f32 v[16:17], v[8:9], v[68:69]
	s_nop 0
	v_pk_add_f32 v[4:5], v[16:17], v[4:5]
	v_pk_fma_f32 v[8:9], v[0:1], v[16:17], v[60:61] op_sel_hi:[0,1,1] neg_lo:[0,0,1] neg_hi:[0,0,1]
	v_pk_fma_f32 v[16:17], v[82:83], v[4:5], v[62:63] op_sel_hi:[0,1,1] neg_lo:[0,0,1] neg_hi:[0,0,1]
	v_pk_add_f32 v[4:5], v[4:5], v[12:13]
	v_cvt_pk_bf16_f32 v8, v8, v9
	v_pk_fma_f32 v[12:13], v[96:97], v[4:5], v[64:65] op_sel_hi:[0,1,1] neg_lo:[0,0,1] neg_hi:[0,0,1]
	v_cvt_pk_bf16_f32 v24, v12, v13
	v_pk_add_f32 v[12:13], v[100:101], v[20:21] neg_lo:[0,1] neg_hi:[0,1]
	v_pk_add_f32 v[20:21], v[122:123], v[60:61] neg_lo:[0,1] neg_hi:[0,1]
	v_pk_add_f32 v[4:5], v[4:5], v[12:13]
	v_pk_add_f32 v[60:61], v[70:71], v[64:65] neg_lo:[0,1] neg_hi:[0,1]
	v_pk_fma_f32 v[12:13], v[104:105], v[4:5], v[68:69] op_sel_hi:[0,1,1] neg_lo:[0,0,1] neg_hi:[0,0,1]
	v_cvt_pk_bf16_f32 v140, v12, v13
	v_pk_add_f32 v[12:13], v[40:41], v[58:59] neg_lo:[0,1] neg_hi:[0,1]
	v_pk_add_f32 v[58:59], v[128:129], v[62:63] neg_lo:[0,1] neg_hi:[0,1]
	v_pk_add_f32 v[12:13], v[4:5], v[12:13]
	v_cvt_pk_bf16_f32 v16, v16, v17
	v_pk_add_f32 v[20:21], v[12:13], v[20:21]
	v_pk_fma_f32 v[4:5], v[110:111], v[12:13], v[76:77] op_sel_hi:[0,1,1] neg_lo:[0,0,1] neg_hi:[0,0,1]
	v_pk_add_f32 v[58:59], v[20:21], v[58:59]
	v_pk_fma_f32 v[12:13], v[116:117], v[20:21], v[92:93] op_sel_hi:[0,1,1] neg_lo:[0,0,1] neg_hi:[0,0,1]
	v_pk_fma_f32 v[20:21], v[126:127], v[58:59], v[100:101] op_sel_hi:[0,1,1] neg_lo:[0,0,1] neg_hi:[0,0,1]
	v_pk_add_f32 v[76:77], v[58:59], v[60:61]
	v_pk_add_f32 v[58:59], v[26:27], 0 op_sel_hi:[1,0]
	v_pk_add_f32 v[26:27], v[66:67], v[26:27] neg_lo:[0,1] neg_hi:[0,1]
	v_pk_add_f32 v[58:59], v[58:59], v[28:29]
	v_pk_add_f32 v[28:29], v[78:79], v[28:29] neg_lo:[0,1] neg_hi:[0,1]
	v_pk_add_f32 v[58:59], v[58:59], v[46:47]
	v_cvt_pk_bf16_f32 v4, v4, v5
	v_pk_add_f32 v[58:59], v[58:59], v[48:49]
	v_cvt_pk_bf16_f32 v12, v12, v13
	v_pk_add_f32 v[58:59], v[58:59], v[50:51]
	v_cvt_pk_bf16_f32 v20, v20, v21
	v_pk_add_f32 v[58:59], v[58:59], v[52:53]
	s_nop 0
	v_pk_add_f32 v[58:59], v[58:59], v[54:55]
	s_nop 0
	v_pk_add_f32 v[58:59], v[58:59], v[56:57]
	s_nop 0
	v_pk_add_f32 v[26:27], v[58:59], v[26:27]
	v_pk_fma_f32 v[60:61], v[0:1], v[58:59], v[50:51] op_sel_hi:[0,1,1] neg_lo:[0,0,1] neg_hi:[0,0,1]
	v_pk_fma_f32 v[58:59], v[82:83], v[26:27], v[52:53] op_sel_hi:[0,1,1] neg_lo:[0,0,1] neg_hi:[0,0,1]
	v_pk_add_f32 v[26:27], v[26:27], v[28:29]
	v_cvt_pk_bf16_f32 v9, v60, v61
	v_pk_fma_f32 v[28:29], v[96:97], v[26:27], v[54:55] op_sel_hi:[0,1,1] neg_lo:[0,0,1] neg_hi:[0,0,1]
	v_cvt_pk_bf16_f32 v25, v28, v29
	v_pk_add_f32 v[28:29], v[90:91], v[46:47] neg_lo:[0,1] neg_hi:[0,1]
	v_cvt_pk_bf16_f32 v17, v58, v59
	v_pk_add_f32 v[26:27], v[26:27], v[28:29]
	v_max_i32_e32 v0, 4, v83
	v_pk_fma_f32 v[28:29], v[104:105], v[26:27], v[56:57] op_sel_hi:[0,1,1] neg_lo:[0,0,1] neg_hi:[0,0,1]
	v_cvt_pk_bf16_f32 v141, v28, v29
	v_pk_add_f32 v[28:29], v[36:37], v[48:49] neg_lo:[0,1] neg_hi:[0,1]
	global_store_dwordx4 v[30:31], v[6:9], off
	global_store_dwordx4 v[30:31], v[14:17], off offset:1024
	global_store_dwordx4 v[30:31], v[22:25], off offset:2048
	global_store_dwordx4 v[30:31], v[138:141], off offset:3072
	v_pk_add_f32 v[26:27], v[26:27], v[28:29]
	v_add_co_u32_e32 v6, vcc, 0x1000, v30
	v_pk_fma_f32 v[28:29], v[110:111], v[26:27], v[66:67] op_sel_hi:[0,1,1] neg_lo:[0,0,1] neg_hi:[0,0,1]
	v_cvt_pk_bf16_f32 v5, v28, v29
	v_pk_add_f32 v[28:29], v[114:115], v[50:51] neg_lo:[0,1] neg_hi:[0,1]
	v_addc_co_u32_e32 v7, vcc, 0, v31, vcc
	v_pk_add_f32 v[26:27], v[26:27], v[28:29]
	s_nop 0
	v_pk_fma_f32 v[28:29], v[116:117], v[26:27], v[78:79] op_sel_hi:[0,1,1] neg_lo:[0,0,1] neg_hi:[0,0,1]
	v_cvt_pk_bf16_f32 v13, v28, v29
	v_pk_add_f32 v[28:29], v[120:121], v[52:53] neg_lo:[0,1] neg_hi:[0,1]
	s_nop 0
	v_pk_add_f32 v[26:27], v[26:27], v[28:29]
	s_nop 0
	v_pk_fma_f32 v[28:29], v[126:127], v[26:27], v[90:91] op_sel_hi:[0,1,1] neg_lo:[0,0,1] neg_hi:[0,0,1]
	v_cvt_pk_bf16_f32 v21, v28, v29
	v_pk_add_f32 v[28:29], v[124:125], v[54:55] neg_lo:[0,1] neg_hi:[0,1]
	global_store_dwordx4 v[6:7], v[2:5], off
	global_store_dwordx4 v[6:7], v[10:13], off offset:1024
	global_store_dwordx4 v[6:7], v[18:21], off offset:2048
	v_pk_add_f32 v[2:3], v[26:27], v[28:29]

.LBB0_533:
	v_cvt_pk_bf16_f32 v6, v8, v9
	v_add_u32_e32 v8, s0, v34
	ds_read2st64_b32 v[36:37], v8 offset1:4
	ds_read2st64_b32 v[84:85], v8 offset0:8 offset1:12
	ds_read2st64_b32 v[86:87], v8 offset0:16 offset1:20
	ds_read2st64_b32 v[88:89], v8 offset0:24 offset1:28
	ds_read2st64_b32 v[90:91], v8 offset0:32 offset1:36
	ds_read2st64_b32 v[92:93], v8 offset0:40 offset1:44
	ds_read2st64_b32 v[94:95], v8 offset0:48 offset1:52
	ds_read2st64_b32 v[96:97], v8 offset0:56 offset1:60
	v_and_b32_e32 v7, 0xffff, v6
	v_and_b32_e32 v6, 0xffff0000, v6
	s_addk_i32 s0, 0x400
	s_mov_b64 s[2:3], 0x800
	v_lshl_add_u64 v[2:3], v[2:3], 0, s[2:3]
	s_cmpk_eq_i32 s0, 0x7c00
	s_waitcnt lgkmcnt(7)
	v_dot2c_f32_bf16_e32 v80, v36, v7
	v_dot2c_f32_bf16_e32 v81, v36, v6
	v_dot2c_f32_bf16_e32 v78, v37, v7
	v_dot2c_f32_bf16_e32 v79, v37, v6
	ds_read2st64_b32 v[36:37], v8 offset0:64 offset1:68
	s_waitcnt lgkmcnt(7)
	v_dot2c_f32_bf16_e32 v76, v84, v7
	v_dot2c_f32_bf16_e32 v77, v84, v6
	v_dot2c_f32_bf16_e32 v74, v85, v7
	v_dot2c_f32_bf16_e32 v75, v85, v6
	ds_read2st64_b32 v[84:85], v8 offset0:72 offset1:76
	s_waitcnt lgkmcnt(7)
	v_dot2c_f32_bf16_e32 v72, v86, v7
	v_dot2c_f32_bf16_e32 v73, v86, v6
	v_dot2c_f32_bf16_e32 v70, v87, v7
	v_dot2c_f32_bf16_e32 v71, v87, v6
	ds_read2st64_b32 v[86:87], v8 offset0:80 offset1:84
	s_waitcnt lgkmcnt(7)
	v_dot2c_f32_bf16_e32 v68, v88, v7
	v_dot2c_f32_bf16_e32 v69, v88, v6
	v_dot2c_f32_bf16_e32 v66, v89, v7
	v_dot2c_f32_bf16_e32 v67, v89, v6
	ds_read2st64_b32 v[88:89], v8 offset0:88 offset1:92
	s_waitcnt lgkmcnt(7)
	v_dot2c_f32_bf16_e32 v64, v90, v7
	v_dot2c_f32_bf16_e32 v65, v90, v6
	v_dot2c_f32_bf16_e32 v62, v91, v7
	v_dot2c_f32_bf16_e32 v63, v91, v6
	ds_read2st64_b32 v[90:91], v8 offset0:96 offset1:100
	s_waitcnt lgkmcnt(7)
	v_dot2c_f32_bf16_e32 v60, v92, v7
	v_dot2c_f32_bf16_e32 v61, v92, v6
	v_dot2c_f32_bf16_e32 v58, v93, v7
	v_dot2c_f32_bf16_e32 v59, v93, v6
	ds_read2st64_b32 v[92:93], v8 offset0:104 offset1:108
	s_waitcnt lgkmcnt(7)
	v_dot2c_f32_bf16_e32 v56, v94, v7
	v_dot2c_f32_bf16_e32 v57, v94, v6
	v_dot2c_f32_bf16_e32 v54, v95, v7
	v_dot2c_f32_bf16_e32 v55, v95, v6
	ds_read2st64_b32 v[94:95], v8 offset0:112 offset1:116
	s_waitcnt lgkmcnt(7)
	v_dot2c_f32_bf16_e32 v52, v96, v7
	v_dot2c_f32_bf16_e32 v53, v96, v6
	v_dot2c_f32_bf16_e32 v50, v97, v7
	v_dot2c_f32_bf16_e32 v51, v97, v6
	ds_read2st64_b32 v[8:9], v8 offset0:120 offset1:124
	s_waitcnt lgkmcnt(7)
	v_dot2c_f32_bf16_e32 v48, v36, v7
	v_dot2c_f32_bf16_e32 v49, v36, v6
	v_dot2c_f32_bf16_e32 v46, v37, v7
	v_dot2c_f32_bf16_e32 v47, v37, v6
	s_waitcnt lgkmcnt(6)
	v_dot2c_f32_bf16_e32 v44, v84, v7
	v_dot2c_f32_bf16_e32 v45, v84, v6
	v_dot2c_f32_bf16_e32 v42, v85, v7
	v_dot2c_f32_bf16_e32 v43, v85, v6
	s_waitcnt lgkmcnt(5)
	v_dot2c_f32_bf16_e32 v40, v86, v7
	v_dot2c_f32_bf16_e32 v41, v86, v6
	v_dot2c_f32_bf16_e32 v38, v87, v7
	v_dot2c_f32_bf16_e32 v39, v87, v6
	s_waitcnt lgkmcnt(4)
	v_dot2c_f32_bf16_e32 v30, v88, v7
	v_dot2c_f32_bf16_e32 v31, v88, v6
	v_dot2c_f32_bf16_e32 v28, v89, v7
	v_dot2c_f32_bf16_e32 v29, v89, v6
	s_waitcnt lgkmcnt(3)
	v_dot2c_f32_bf16_e32 v26, v90, v7
	v_dot2c_f32_bf16_e32 v27, v90, v6
	v_dot2c_f32_bf16_e32 v24, v91, v7
	v_dot2c_f32_bf16_e32 v25, v91, v6
	s_waitcnt lgkmcnt(2)
	v_dot2c_f32_bf16_e32 v22, v92, v7
	v_dot2c_f32_bf16_e32 v23, v92, v6
	v_dot2c_f32_bf16_e32 v20, v93, v7
	v_dot2c_f32_bf16_e32 v21, v93, v6
	s_waitcnt lgkmcnt(1)
	v_dot2c_f32_bf16_e32 v18, v94, v7
	v_dot2c_f32_bf16_e32 v19, v94, v6
	v_dot2c_f32_bf16_e32 v16, v95, v7
	v_dot2c_f32_bf16_e32 v17, v95, v6
	s_waitcnt lgkmcnt(0)
	v_dot2c_f32_bf16_e32 v14, v8, v7
	v_dot2c_f32_bf16_e32 v15, v8, v6
	v_dot2c_f32_bf16_e32 v12, v9, v7
	v_dot2c_f32_bf16_e32 v13, v9, v6
	s_cbranch_scc0 .LBB0_531
	v_add_f32_e32 v3, v80, v81
	s_waitcnt vmcnt(0)
	v_mov_b32_e32 v4, v1
	v_lshlrev_b32_e32 v2, 8, v32
	v_add_f32_dpp v3, v3, v3 row_shr:1 row_mask:0xf bank_mask:0xf bound_ctrl:1
	v_and_b32_e32 v2, 0xffff0000, v2
	v_add_u32_e32 v82, 16, v2
	v_add_f32_dpp v3, v3, v3 row_shr:2 row_mask:0xf bank_mask:0xf bound_ctrl:1
	v_cmp_eq_u32_e32 vcc, 0, v33
	v_lshl_add_u32 v2, v11, 2, v82
	v_add_f32_dpp v3, v3, v3 row_shr:4 row_mask:0xf bank_mask:0xf bound_ctrl:1
	s_nop 1
	v_add_f32_dpp v3, v3, v3 row_shr:8 row_mask:0xf bank_mask:0xf bound_ctrl:1
	s_nop 1
	v_mov_b32_dpp v4, v3 row_bcast:15 row_mask:0xa bank_mask:0xf
	v_add_f32_e32 v3, v3, v4
	v_mov_b32_e32 v4, v1
	s_nop 1
	v_mov_b32_dpp v4, v3 row_bcast:31 row_mask:0xc bank_mask:0xf
	v_add_f32_e32 v3, v3, v4
	v_mov_b32_e32 v4, v1
	v_readlane_b32 s2, v3, 63
	v_mul_f32_e32 v3, v81, v81
	v_fmac_f32_e32 v3, v80, v80
	s_nop 1
	v_add_f32_dpp v3, v3, v3 row_shr:1 row_mask:0xf bank_mask:0xf bound_ctrl:1
	s_nop 1
	v_add_f32_dpp v3, v3, v3 row_shr:2 row_mask:0xf bank_mask:0xf bound_ctrl:1
	s_nop 1
	v_add_f32_dpp v3, v3, v3 row_shr:4 row_mask:0xf bank_mask:0xf bound_ctrl:1
	s_nop 1
	v_add_f32_dpp v3, v3, v3 row_shr:8 row_mask:0xf bank_mask:0xf bound_ctrl:1
	s_nop 1
	v_mov_b32_dpp v4, v3 row_bcast:15 row_mask:0xa bank_mask:0xf
	v_add_f32_e32 v3, v3, v4
	v_mov_b32_e32 v4, v1
	s_nop 1
	v_mov_b32_dpp v4, v3 row_bcast:31 row_mask:0xc bank_mask:0xf
	v_add_f32_e32 v3, v3, v4
	s_nop 0
	v_readlane_b32 s3, v3, 63
	s_and_saveexec_b64 s[0:1], vcc
	v_add_u32_e32 v3, 0xf800, v2
	v_mov_b32_e32 v4, s2
	v_mov_b32_e32 v5, s3
	ds_write2_b32 v3, v4, v5 offset1:1
	s_or_b64 exec, exec, s[0:1]
	v_add_f32_e32 v3, v78, v79
	v_mov_b32_e32 v4, v1
	s_nop 0
	v_add_f32_dpp v3, v3, v3 row_shr:1 row_mask:0xf bank_mask:0xf bound_ctrl:1
	s_nop 1
	v_add_f32_dpp v3, v3, v3 row_shr:2 row_mask:0xf bank_mask:0xf bound_ctrl:1
	s_nop 1
	v_add_f32_dpp v3, v3, v3 row_shr:4 row_mask:0xf bank_mask:0xf bound_ctrl:1
	s_nop 1
	v_add_f32_dpp v3, v3, v3 row_shr:8 row_mask:0xf bank_mask:0xf bound_ctrl:1
	s_nop 1
	v_mov_b32_dpp v4, v3 row_bcast:15 row_mask:0xa bank_mask:0xf
	v_add_f32_e32 v3, v3, v4
	v_mov_b32_e32 v4, v1
	s_nop 1
	v_mov_b32_dpp v4, v3 row_bcast:31 row_mask:0xc bank_mask:0xf
	v_add_f32_e32 v3, v3, v4
	v_mov_b32_e32 v4, v1
	v_readlane_b32 s2, v3, 63
	v_mul_f32_e32 v3, v79, v79
	v_fmac_f32_e32 v3, v78, v78
	s_nop 1
	v_add_f32_dpp v3, v3, v3 row_shr:1 row_mask:0xf bank_mask:0xf bound_ctrl:1
	s_nop 1
	v_add_f32_dpp v3, v3, v3 row_shr:2 row_mask:0xf bank_mask:0xf bound_ctrl:1
	s_nop 1
	v_add_f32_dpp v3, v3, v3 row_shr:4 row_mask:0xf bank_mask:0xf bound_ctrl:1
	s_nop 1
	v_add_f32_dpp v3, v3, v3 row_shr:8 row_mask:0xf bank_mask:0xf bound_ctrl:1
	s_nop 1
	v_mov_b32_dpp v4, v3 row_bcast:15 row_mask:0xa bank_mask:0xf
	v_add_f32_e32 v3, v3, v4
	v_mov_b32_e32 v4, v1
	s_nop 1
	v_mov_b32_dpp v4, v3 row_bcast:31 row_mask:0xc bank_mask:0xf
	v_add_f32_e32 v3, v3, v4
	s_nop 0
	v_readlane_b32 s3, v3, 63
	s_and_saveexec_b64 s[0:1], vcc
	v_add_u32_e32 v3, 0xf808, v2
	v_mov_b32_e32 v4, s2
	v_mov_b32_e32 v5, s3
	ds_write2_b32 v3, v4, v5 offset1:1
	s_or_b64 exec, exec, s[0:1]
	v_add_f32_e32 v3, v76, v77
	v_mov_b32_e32 v4, v1
	s_nop 0
	v_add_f32_dpp v3, v3, v3 row_shr:1 row_mask:0xf bank_mask:0xf bound_ctrl:1
	s_nop 1
	v_add_f32_dpp v3, v3, v3 row_shr:2 row_mask:0xf bank_mask:0xf bound_ctrl:1
	s_nop 1
	v_add_f32_dpp v3, v3, v3 row_shr:4 row_mask:0xf bank_mask:0xf bound_ctrl:1
	s_nop 1
	v_add_f32_dpp v3, v3, v3 row_shr:8 row_mask:0xf bank_mask:0xf bound_ctrl:1
	s_nop 1
	v_mov_b32_dpp v4, v3 row_bcast:15 row_mask:0xa bank_mask:0xf
	v_add_f32_e32 v3, v3, v4
	v_mov_b32_e32 v4, v1
	s_nop 1
	v_mov_b32_dpp v4, v3 row_bcast:31 row_mask:0xc bank_mask:0xf
	v_add_f32_e32 v3, v3, v4
	v_mov_b32_e32 v4, v1
	v_readlane_b32 s2, v3, 63
	v_mul_f32_e32 v3, v77, v77
	v_fmac_f32_e32 v3, v76, v76
	s_nop 1
	v_add_f32_dpp v3, v3, v3 row_shr:1 row_mask:0xf bank_mask:0xf bound_ctrl:1
	s_nop 1
	v_add_f32_dpp v3, v3, v3 row_shr:2 row_mask:0xf bank_mask:0xf bound_ctrl:1
	s_nop 1
	v_add_f32_dpp v3, v3, v3 row_shr:4 row_mask:0xf bank_mask:0xf bound_ctrl:1
	s_nop 1
	v_add_f32_dpp v3, v3, v3 row_shr:8 row_mask:0xf bank_mask:0xf bound_ctrl:1
	s_nop 1
	v_mov_b32_dpp v4, v3 row_bcast:15 row_mask:0xa bank_mask:0xf
	v_add_f32_e32 v3, v3, v4
	v_mov_b32_e32 v4, v1
	s_nop 1
	v_mov_b32_dpp v4, v3 row_bcast:31 row_mask:0xc bank_mask:0xf
	v_add_f32_e32 v3, v3, v4
	s_nop 0
	v_readlane_b32 s3, v3, 63
	s_and_saveexec_b64 s[0:1], vcc
	v_add_u32_e32 v3, 0xf810, v2
	v_mov_b32_e32 v4, s2
	v_mov_b32_e32 v5, s3
	ds_write2_b32 v3, v4, v5 offset1:1
	s_or_b64 exec, exec, s[0:1]
	v_add_f32_e32 v3, v74, v75
	v_mov_b32_e32 v4, v1
	s_nop 0
	v_add_f32_dpp v3, v3, v3 row_shr:1 row_mask:0xf bank_mask:0xf bound_ctrl:1
	s_nop 1
	v_add_f32_dpp v3, v3, v3 row_shr:2 row_mask:0xf bank_mask:0xf bound_ctrl:1
	s_nop 1
	v_add_f32_dpp v3, v3, v3 row_shr:4 row_mask:0xf bank_mask:0xf bound_ctrl:1
	s_nop 1
	v_add_f32_dpp v3, v3, v3 row_shr:8 row_mask:0xf bank_mask:0xf bound_ctrl:1
	s_nop 1
	v_mov_b32_dpp v4, v3 row_bcast:15 row_mask:0xa bank_mask:0xf
	v_add_f32_e32 v3, v3, v4
	v_mov_b32_e32 v4, v1
	s_nop 1
	v_mov_b32_dpp v4, v3 row_bcast:31 row_mask:0xc bank_mask:0xf
	v_add_f32_e32 v3, v3, v4
	v_mov_b32_e32 v4, v1
	v_readlane_b32 s2, v3, 63
	v_mul_f32_e32 v3, v75, v75
	v_fmac_f32_e32 v3, v74, v74
	s_nop 1
	v_add_f32_dpp v3, v3, v3 row_shr:1 row_mask:0xf bank_mask:0xf bound_ctrl:1
	s_nop 1
	v_add_f32_dpp v3, v3, v3 row_shr:2 row_mask:0xf bank_mask:0xf bound_ctrl:1
	s_nop 1
	v_add_f32_dpp v3, v3, v3 row_shr:4 row_mask:0xf bank_mask:0xf bound_ctrl:1
	s_nop 1
	v_add_f32_dpp v3, v3, v3 row_shr:8 row_mask:0xf bank_mask:0xf bound_ctrl:1
	s_nop 1
	v_mov_b32_dpp v4, v3 row_bcast:15 row_mask:0xa bank_mask:0xf
	v_add_f32_e32 v3, v3, v4
	v_mov_b32_e32 v4, v1
	s_nop 1
	v_mov_b32_dpp v4, v3 row_bcast:31 row_mask:0xc bank_mask:0xf
	v_add_f32_e32 v3, v3, v4
	s_nop 0
	v_readlane_b32 s3, v3, 63
	s_and_saveexec_b64 s[0:1], vcc
	v_add_u32_e32 v3, 0xf818, v2
	v_mov_b32_e32 v4, s2
	v_mov_b32_e32 v5, s3
	ds_write2_b32 v3, v4, v5 offset1:1
	s_or_b64 exec, exec, s[0:1]
	v_add_f32_e32 v3, v72, v73
	v_mov_b32_e32 v4, v1
	s_nop 0
	v_add_f32_dpp v3, v3, v3 row_shr:1 row_mask:0xf bank_mask:0xf bound_ctrl:1
	s_nop 1
	v_add_f32_dpp v3, v3, v3 row_shr:2 row_mask:0xf bank_mask:0xf bound_ctrl:1
	s_nop 1
	v_add_f32_dpp v3, v3, v3 row_shr:4 row_mask:0xf bank_mask:0xf bound_ctrl:1
	s_nop 1
	v_add_f32_dpp v3, v3, v3 row_shr:8 row_mask:0xf bank_mask:0xf bound_ctrl:1
	s_nop 1
	v_mov_b32_dpp v4, v3 row_bcast:15 row_mask:0xa bank_mask:0xf
	v_add_f32_e32 v3, v3, v4
	v_mov_b32_e32 v4, v1
	s_nop 1
	v_mov_b32_dpp v4, v3 row_bcast:31 row_mask:0xc bank_mask:0xf
	v_add_f32_e32 v3, v3, v4
	v_mov_b32_e32 v4, v1
	v_readlane_b32 s2, v3, 63
	v_mul_f32_e32 v3, v73, v73
	v_fmac_f32_e32 v3, v72, v72
	s_nop 1
	v_add_f32_dpp v3, v3, v3 row_shr:1 row_mask:0xf bank_mask:0xf bound_ctrl:1
	s_nop 1
	v_add_f32_dpp v3, v3, v3 row_shr:2 row_mask:0xf bank_mask:0xf bound_ctrl:1
	s_nop 1
	v_add_f32_dpp v3, v3, v3 row_shr:4 row_mask:0xf bank_mask:0xf bound_ctrl:1
	s_nop 1
	v_add_f32_dpp v3, v3, v3 row_shr:8 row_mask:0xf bank_mask:0xf bound_ctrl:1
	s_nop 1
	v_mov_b32_dpp v4, v3 row_bcast:15 row_mask:0xa bank_mask:0xf
	v_add_f32_e32 v3, v3, v4
	v_mov_b32_e32 v4, v1
	s_nop 1
	v_mov_b32_dpp v4, v3 row_bcast:31 row_mask:0xc bank_mask:0xf
	v_add_f32_e32 v3, v3, v4
	s_nop 0
	v_readlane_b32 s3, v3, 63
	s_and_saveexec_b64 s[0:1], vcc
	v_add_u32_e32 v3, 0xf820, v2
	v_mov_b32_e32 v4, s2
	v_mov_b32_e32 v5, s3
	ds_write2_b32 v3, v4, v5 offset1:1
	s_or_b64 exec, exec, s[0:1]
	v_add_f32_e32 v3, v70, v71
	v_mov_b32_e32 v4, v1
	s_nop 0
	v_add_f32_dpp v3, v3, v3 row_shr:1 row_mask:0xf bank_mask:0xf bound_ctrl:1
	s_nop 1
	v_add_f32_dpp v3, v3, v3 row_shr:2 row_mask:0xf bank_mask:0xf bound_ctrl:1
	s_nop 1
	v_add_f32_dpp v3, v3, v3 row_shr:4 row_mask:0xf bank_mask:0xf bound_ctrl:1
	s_nop 1
	v_add_f32_dpp v3, v3, v3 row_shr:8 row_mask:0xf bank_mask:0xf bound_ctrl:1
	s_nop 1
	v_mov_b32_dpp v4, v3 row_bcast:15 row_mask:0xa bank_mask:0xf
	v_add_f32_e32 v3, v3, v4
	v_mov_b32_e32 v4, v1
	s_nop 1
	v_mov_b32_dpp v4, v3 row_bcast:31 row_mask:0xc bank_mask:0xf
	v_add_f32_e32 v3, v3, v4
	v_mov_b32_e32 v4, v1
	v_readlane_b32 s2, v3, 63
	v_mul_f32_e32 v3, v71, v71
	v_fmac_f32_e32 v3, v70, v70
	s_nop 1
	v_add_f32_dpp v3, v3, v3 row_shr:1 row_mask:0xf bank_mask:0xf bound_ctrl:1
	s_nop 1
	v_add_f32_dpp v3, v3, v3 row_shr:2 row_mask:0xf bank_mask:0xf bound_ctrl:1
	s_nop 1
	v_add_f32_dpp v3, v3, v3 row_shr:4 row_mask:0xf bank_mask:0xf bound_ctrl:1
	s_nop 1
	v_add_f32_dpp v3, v3, v3 row_shr:8 row_mask:0xf bank_mask:0xf bound_ctrl:1
	s_nop 1
	v_mov_b32_dpp v4, v3 row_bcast:15 row_mask:0xa bank_mask:0xf
	v_add_f32_e32 v3, v3, v4
	v_mov_b32_e32 v4, v1
	s_nop 1
	v_mov_b32_dpp v4, v3 row_bcast:31 row_mask:0xc bank_mask:0xf
	v_add_f32_e32 v3, v3, v4
	s_nop 0
	v_readlane_b32 s3, v3, 63
	s_and_saveexec_b64 s[0:1], vcc
	v_add_u32_e32 v3, 0xf828, v2
	v_mov_b32_e32 v4, s2
	v_mov_b32_e32 v5, s3
	ds_write2_b32 v3, v4, v5 offset1:1
	s_or_b64 exec, exec, s[0:1]
	v_add_f32_e32 v3, v68, v69
	v_mov_b32_e32 v4, v1
	s_nop 0
	v_add_f32_dpp v3, v3, v3 row_shr:1 row_mask:0xf bank_mask:0xf bound_ctrl:1
	s_nop 1
	v_add_f32_dpp v3, v3, v3 row_shr:2 row_mask:0xf bank_mask:0xf bound_ctrl:1
	s_nop 1
	v_add_f32_dpp v3, v3, v3 row_shr:4 row_mask:0xf bank_mask:0xf bound_ctrl:1
	s_nop 1
	v_add_f32_dpp v3, v3, v3 row_shr:8 row_mask:0xf bank_mask:0xf bound_ctrl:1
	s_nop 1
	v_mov_b32_dpp v4, v3 row_bcast:15 row_mask:0xa bank_mask:0xf
	v_add_f32_e32 v3, v3, v4
	v_mov_b32_e32 v4, v1
	s_nop 1
	v_mov_b32_dpp v4, v3 row_bcast:31 row_mask:0xc bank_mask:0xf
	v_add_f32_e32 v3, v3, v4
	v_mov_b32_e32 v4, v1
	v_readlane_b32 s2, v3, 63
	v_mul_f32_e32 v3, v69, v69
	v_fmac_f32_e32 v3, v68, v68
	s_nop 1
	v_add_f32_dpp v3, v3, v3 row_shr:1 row_mask:0xf bank_mask:0xf bound_ctrl:1
	s_nop 1
	v_add_f32_dpp v3, v3, v3 row_shr:2 row_mask:0xf bank_mask:0xf bound_ctrl:1
	s_nop 1
	v_add_f32_dpp v3, v3, v3 row_shr:4 row_mask:0xf bank_mask:0xf bound_ctrl:1
	s_nop 1
	v_add_f32_dpp v3, v3, v3 row_shr:8 row_mask:0xf bank_mask:0xf bound_ctrl:1
	s_nop 1
	v_mov_b32_dpp v4, v3 row_bcast:15 row_mask:0xa bank_mask:0xf
	v_add_f32_e32 v3, v3, v4
	v_mov_b32_e32 v4, v1
	s_nop 1
	v_mov_b32_dpp v4, v3 row_bcast:31 row_mask:0xc bank_mask:0xf
	v_add_f32_e32 v3, v3, v4
	s_nop 0
	v_readlane_b32 s3, v3, 63
	s_and_saveexec_b64 s[0:1], vcc
	v_add_u32_e32 v3, 0xf830, v2
	v_mov_b32_e32 v4, s2
	v_mov_b32_e32 v5, s3
	ds_write2_b32 v3, v4, v5 offset1:1
	s_or_b64 exec, exec, s[0:1]
	v_add_f32_e32 v3, v66, v67
	v_mov_b32_e32 v4, v1
	s_nop 0
	v_add_f32_dpp v3, v3, v3 row_shr:1 row_mask:0xf bank_mask:0xf bound_ctrl:1
	s_nop 1
	v_add_f32_dpp v3, v3, v3 row_shr:2 row_mask:0xf bank_mask:0xf bound_ctrl:1
	s_nop 1
	v_add_f32_dpp v3, v3, v3 row_shr:4 row_mask:0xf bank_mask:0xf bound_ctrl:1
	s_nop 1
	v_add_f32_dpp v3, v3, v3 row_shr:8 row_mask:0xf bank_mask:0xf bound_ctrl:1
	s_nop 1
	v_mov_b32_dpp v4, v3 row_bcast:15 row_mask:0xa bank_mask:0xf
	v_add_f32_e32 v3, v3, v4
	v_mov_b32_e32 v4, v1
	s_nop 1
	v_mov_b32_dpp v4, v3 row_bcast:31 row_mask:0xc bank_mask:0xf
	v_add_f32_e32 v3, v3, v4
	v_mov_b32_e32 v4, v1
	v_readlane_b32 s2, v3, 63
	v_mul_f32_e32 v3, v67, v67
	v_fmac_f32_e32 v3, v66, v66
	s_nop 1
	v_add_f32_dpp v3, v3, v3 row_shr:1 row_mask:0xf bank_mask:0xf bound_ctrl:1
	s_nop 1
	v_add_f32_dpp v3, v3, v3 row_shr:2 row_mask:0xf bank_mask:0xf bound_ctrl:1
	s_nop 1
	v_add_f32_dpp v3, v3, v3 row_shr:4 row_mask:0xf bank_mask:0xf bound_ctrl:1
	s_nop 1
	v_add_f32_dpp v3, v3, v3 row_shr:8 row_mask:0xf bank_mask:0xf bound_ctrl:1
	s_nop 1
	v_mov_b32_dpp v4, v3 row_bcast:15 row_mask:0xa bank_mask:0xf
	v_add_f32_e32 v3, v3, v4
	v_mov_b32_e32 v4, v1
	s_nop 1
	v_mov_b32_dpp v4, v3 row_bcast:31 row_mask:0xc bank_mask:0xf
	v_add_f32_e32 v3, v3, v4
	s_nop 0
	v_readlane_b32 s3, v3, 63
	s_and_saveexec_b64 s[0:1], vcc
	v_add_u32_e32 v3, 0xf838, v2
	v_mov_b32_e32 v4, s2
	v_mov_b32_e32 v5, s3
	ds_write2_b32 v3, v4, v5 offset1:1
	s_or_b64 exec, exec, s[0:1]
	v_add_f32_e32 v3, v64, v65
	v_mov_b32_e32 v4, v1
	s_nop 0
	v_add_f32_dpp v3, v3, v3 row_shr:1 row_mask:0xf bank_mask:0xf bound_ctrl:1
	s_nop 1
	v_add_f32_dpp v3, v3, v3 row_shr:2 row_mask:0xf bank_mask:0xf bound_ctrl:1
	s_nop 1
	v_add_f32_dpp v3, v3, v3 row_shr:4 row_mask:0xf bank_mask:0xf bound_ctrl:1
	s_nop 1
	v_add_f32_dpp v3, v3, v3 row_shr:8 row_mask:0xf bank_mask:0xf bound_ctrl:1
	s_nop 1
	v_mov_b32_dpp v4, v3 row_bcast:15 row_mask:0xa bank_mask:0xf
	v_add_f32_e32 v3, v3, v4
	v_mov_b32_e32 v4, v1
	s_nop 1
	v_mov_b32_dpp v4, v3 row_bcast:31 row_mask:0xc bank_mask:0xf
	v_add_f32_e32 v3, v3, v4
	v_mov_b32_e32 v4, v1
	v_readlane_b32 s2, v3, 63
	v_mul_f32_e32 v3, v65, v65
	v_fmac_f32_e32 v3, v64, v64
	s_nop 1
	v_add_f32_dpp v3, v3, v3 row_shr:1 row_mask:0xf bank_mask:0xf bound_ctrl:1
	s_nop 1
	v_add_f32_dpp v3, v3, v3 row_shr:2 row_mask:0xf bank_mask:0xf bound_ctrl:1
	s_nop 1
	v_add_f32_dpp v3, v3, v3 row_shr:4 row_mask:0xf bank_mask:0xf bound_ctrl:1
	s_nop 1
	v_add_f32_dpp v3, v3, v3 row_shr:8 row_mask:0xf bank_mask:0xf bound_ctrl:1
	s_nop 1
	v_mov_b32_dpp v4, v3 row_bcast:15 row_mask:0xa bank_mask:0xf
	v_add_f32_e32 v3, v3, v4
	v_mov_b32_e32 v4, v1
	s_nop 1
	v_mov_b32_dpp v4, v3 row_bcast:31 row_mask:0xc bank_mask:0xf
	v_add_f32_e32 v3, v3, v4
	s_nop 0
	v_readlane_b32 s3, v3, 63
	s_and_saveexec_b64 s[0:1], vcc
	v_add_u32_e32 v3, 0xf840, v2
	v_mov_b32_e32 v4, s2
	v_mov_b32_e32 v5, s3
	ds_write2_b32 v3, v4, v5 offset1:1
	s_or_b64 exec, exec, s[0:1]
	v_add_f32_e32 v3, v62, v63
	v_mov_b32_e32 v4, v1
	s_nop 0
	v_add_f32_dpp v3, v3, v3 row_shr:1 row_mask:0xf bank_mask:0xf bound_ctrl:1
	s_nop 1
	v_add_f32_dpp v3, v3, v3 row_shr:2 row_mask:0xf bank_mask:0xf bound_ctrl:1
	s_nop 1
	v_add_f32_dpp v3, v3, v3 row_shr:4 row_mask:0xf bank_mask:0xf bound_ctrl:1
	s_nop 1
	v_add_f32_dpp v3, v3, v3 row_shr:8 row_mask:0xf bank_mask:0xf bound_ctrl:1
	s_nop 1
	v_mov_b32_dpp v4, v3 row_bcast:15 row_mask:0xa bank_mask:0xf
	v_add_f32_e32 v3, v3, v4
	v_mov_b32_e32 v4, v1
	s_nop 1
	v_mov_b32_dpp v4, v3 row_bcast:31 row_mask:0xc bank_mask:0xf
	v_add_f32_e32 v3, v3, v4
	v_mov_b32_e32 v4, v1
	v_readlane_b32 s2, v3, 63
	v_mul_f32_e32 v3, v63, v63
	v_fmac_f32_e32 v3, v62, v62
	s_nop 1
	v_add_f32_dpp v3, v3, v3 row_shr:1 row_mask:0xf bank_mask:0xf bound_ctrl:1
	s_nop 1
	v_add_f32_dpp v3, v3, v3 row_shr:2 row_mask:0xf bank_mask:0xf bound_ctrl:1
	s_nop 1
	v_add_f32_dpp v3, v3, v3 row_shr:4 row_mask:0xf bank_mask:0xf bound_ctrl:1
	s_nop 1
	v_add_f32_dpp v3, v3, v3 row_shr:8 row_mask:0xf bank_mask:0xf bound_ctrl:1
	s_nop 1
	v_mov_b32_dpp v4, v3 row_bcast:15 row_mask:0xa bank_mask:0xf
	v_add_f32_e32 v3, v3, v4
	v_mov_b32_e32 v4, v1
	s_nop 1
	v_mov_b32_dpp v4, v3 row_bcast:31 row_mask:0xc bank_mask:0xf
	v_add_f32_e32 v3, v3, v4
	s_nop 0
	v_readlane_b32 s3, v3, 63
	s_and_saveexec_b64 s[0:1], vcc
	v_add_u32_e32 v3, 0xf848, v2
	v_mov_b32_e32 v4, s2
	v_mov_b32_e32 v5, s3
	ds_write2_b32 v3, v4, v5 offset1:1
	s_or_b64 exec, exec, s[0:1]
	v_add_f32_e32 v3, v60, v61
	v_mov_b32_e32 v4, v1
	s_nop 0
	v_add_f32_dpp v3, v3, v3 row_shr:1 row_mask:0xf bank_mask:0xf bound_ctrl:1
	s_nop 1
	v_add_f32_dpp v3, v3, v3 row_shr:2 row_mask:0xf bank_mask:0xf bound_ctrl:1
	s_nop 1
	v_add_f32_dpp v3, v3, v3 row_shr:4 row_mask:0xf bank_mask:0xf bound_ctrl:1
	s_nop 1
	v_add_f32_dpp v3, v3, v3 row_shr:8 row_mask:0xf bank_mask:0xf bound_ctrl:1
	s_nop 1
	v_mov_b32_dpp v4, v3 row_bcast:15 row_mask:0xa bank_mask:0xf
	v_add_f32_e32 v3, v3, v4
	v_mov_b32_e32 v4, v1
	s_nop 1
	v_mov_b32_dpp v4, v3 row_bcast:31 row_mask:0xc bank_mask:0xf
	v_add_f32_e32 v3, v3, v4
	v_mov_b32_e32 v4, v1
	v_readlane_b32 s2, v3, 63
	v_mul_f32_e32 v3, v61, v61
	v_fmac_f32_e32 v3, v60, v60
	s_nop 1
	v_add_f32_dpp v3, v3, v3 row_shr:1 row_mask:0xf bank_mask:0xf bound_ctrl:1
	s_nop 1
	v_add_f32_dpp v3, v3, v3 row_shr:2 row_mask:0xf bank_mask:0xf bound_ctrl:1
	s_nop 1
	v_add_f32_dpp v3, v3, v3 row_shr:4 row_mask:0xf bank_mask:0xf bound_ctrl:1
	s_nop 1
	v_add_f32_dpp v3, v3, v3 row_shr:8 row_mask:0xf bank_mask:0xf bound_ctrl:1
	s_nop 1
	v_mov_b32_dpp v4, v3 row_bcast:15 row_mask:0xa bank_mask:0xf
	v_add_f32_e32 v3, v3, v4
	v_mov_b32_e32 v4, v1
	s_nop 1
	v_mov_b32_dpp v4, v3 row_bcast:31 row_mask:0xc bank_mask:0xf
	v_add_f32_e32 v3, v3, v4
	s_nop 0
	v_readlane_b32 s3, v3, 63
	s_and_saveexec_b64 s[0:1], vcc
	v_add_u32_e32 v3, 0xf850, v2
	v_mov_b32_e32 v4, s2
	v_mov_b32_e32 v5, s3
	ds_write2_b32 v3, v4, v5 offset1:1
	s_or_b64 exec, exec, s[0:1]
	v_add_f32_e32 v3, v58, v59
	v_mov_b32_e32 v4, v1
	s_nop 0
	v_add_f32_dpp v3, v3, v3 row_shr:1 row_mask:0xf bank_mask:0xf bound_ctrl:1
	s_nop 1
	v_add_f32_dpp v3, v3, v3 row_shr:2 row_mask:0xf bank_mask:0xf bound_ctrl:1
	s_nop 1
	v_add_f32_dpp v3, v3, v3 row_shr:4 row_mask:0xf bank_mask:0xf bound_ctrl:1
	s_nop 1
	v_add_f32_dpp v3, v3, v3 row_shr:8 row_mask:0xf bank_mask:0xf bound_ctrl:1
	s_nop 1
	v_mov_b32_dpp v4, v3 row_bcast:15 row_mask:0xa bank_mask:0xf
	v_add_f32_e32 v3, v3, v4
	v_mov_b32_e32 v4, v1
	s_nop 1
	v_mov_b32_dpp v4, v3 row_bcast:31 row_mask:0xc bank_mask:0xf
	v_add_f32_e32 v3, v3, v4
	v_mov_b32_e32 v4, v1
	v_readlane_b32 s2, v3, 63
	v_mul_f32_e32 v3, v59, v59
	v_fmac_f32_e32 v3, v58, v58
	s_nop 1
	v_add_f32_dpp v3, v3, v3 row_shr:1 row_mask:0xf bank_mask:0xf bound_ctrl:1
	s_nop 1
	v_add_f32_dpp v3, v3, v3 row_shr:2 row_mask:0xf bank_mask:0xf bound_ctrl:1
	s_nop 1
	v_add_f32_dpp v3, v3, v3 row_shr:4 row_mask:0xf bank_mask:0xf bound_ctrl:1
	s_nop 1
	v_add_f32_dpp v3, v3, v3 row_shr:8 row_mask:0xf bank_mask:0xf bound_ctrl:1
	s_nop 1
	v_mov_b32_dpp v4, v3 row_bcast:15 row_mask:0xa bank_mask:0xf
	v_add_f32_e32 v3, v3, v4
	v_mov_b32_e32 v4, v1
	s_nop 1
	v_mov_b32_dpp v4, v3 row_bcast:31 row_mask:0xc bank_mask:0xf
	v_add_f32_e32 v3, v3, v4
	s_nop 0
	v_readlane_b32 s3, v3, 63
	s_and_saveexec_b64 s[0:1], vcc
	v_add_u32_e32 v3, 0xf858, v2
	v_mov_b32_e32 v4, s2
	v_mov_b32_e32 v5, s3
	ds_write2_b32 v3, v4, v5 offset1:1
	s_or_b64 exec, exec, s[0:1]
	v_add_f32_e32 v3, v56, v57
	v_mov_b32_e32 v4, v1
	s_nop 0
	v_add_f32_dpp v3, v3, v3 row_shr:1 row_mask:0xf bank_mask:0xf bound_ctrl:1
	s_nop 1
	v_add_f32_dpp v3, v3, v3 row_shr:2 row_mask:0xf bank_mask:0xf bound_ctrl:1
	s_nop 1
	v_add_f32_dpp v3, v3, v3 row_shr:4 row_mask:0xf bank_mask:0xf bound_ctrl:1
	s_nop 1
	v_add_f32_dpp v3, v3, v3 row_shr:8 row_mask:0xf bank_mask:0xf bound_ctrl:1
	s_nop 1
	v_mov_b32_dpp v4, v3 row_bcast:15 row_mask:0xa bank_mask:0xf
	v_add_f32_e32 v3, v3, v4
	v_mov_b32_e32 v4, v1
	s_nop 1
	v_mov_b32_dpp v4, v3 row_bcast:31 row_mask:0xc bank_mask:0xf
	v_add_f32_e32 v3, v3, v4
	v_mov_b32_e32 v4, v1
	v_readlane_b32 s2, v3, 63
	v_mul_f32_e32 v3, v57, v57
	v_fmac_f32_e32 v3, v56, v56
	s_nop 1
	v_add_f32_dpp v3, v3, v3 row_shr:1 row_mask:0xf bank_mask:0xf bound_ctrl:1
	s_nop 1
	v_add_f32_dpp v3, v3, v3 row_shr:2 row_mask:0xf bank_mask:0xf bound_ctrl:1
	s_nop 1
	v_add_f32_dpp v3, v3, v3 row_shr:4 row_mask:0xf bank_mask:0xf bound_ctrl:1
	s_nop 1
	v_add_f32_dpp v3, v3, v3 row_shr:8 row_mask:0xf bank_mask:0xf bound_ctrl:1
	s_nop 1
	v_mov_b32_dpp v4, v3 row_bcast:15 row_mask:0xa bank_mask:0xf
	v_add_f32_e32 v3, v3, v4
	v_mov_b32_e32 v4, v1
	s_nop 1
	v_mov_b32_dpp v4, v3 row_bcast:31 row_mask:0xc bank_mask:0xf
	v_add_f32_e32 v3, v3, v4
	s_nop 0
	v_readlane_b32 s3, v3, 63
	s_and_saveexec_b64 s[0:1], vcc
	v_add_u32_e32 v3, 0xf860, v2
	v_mov_b32_e32 v4, s2
	v_mov_b32_e32 v5, s3
	ds_write2_b32 v3, v4, v5 offset1:1
	s_or_b64 exec, exec, s[0:1]
	v_add_f32_e32 v3, v54, v55
	v_mov_b32_e32 v4, v1
	s_nop 0
	v_add_f32_dpp v3, v3, v3 row_shr:1 row_mask:0xf bank_mask:0xf bound_ctrl:1
	s_nop 1
	v_add_f32_dpp v3, v3, v3 row_shr:2 row_mask:0xf bank_mask:0xf bound_ctrl:1
	s_nop 1
	v_add_f32_dpp v3, v3, v3 row_shr:4 row_mask:0xf bank_mask:0xf bound_ctrl:1
	s_nop 1
	v_add_f32_dpp v3, v3, v3 row_shr:8 row_mask:0xf bank_mask:0xf bound_ctrl:1
	s_nop 1
	v_mov_b32_dpp v4, v3 row_bcast:15 row_mask:0xa bank_mask:0xf
	v_add_f32_e32 v3, v3, v4
	v_mov_b32_e32 v4, v1
	s_nop 1
	v_mov_b32_dpp v4, v3 row_bcast:31 row_mask:0xc bank_mask:0xf
	v_add_f32_e32 v3, v3, v4
	v_mov_b32_e32 v4, v1
	v_readlane_b32 s2, v3, 63
	v_mul_f32_e32 v3, v55, v55
	v_fmac_f32_e32 v3, v54, v54
	s_nop 1
	v_add_f32_dpp v3, v3, v3 row_shr:1 row_mask:0xf bank_mask:0xf bound_ctrl:1
	s_nop 1
	v_add_f32_dpp v3, v3, v3 row_shr:2 row_mask:0xf bank_mask:0xf bound_ctrl:1
	s_nop 1
	v_add_f32_dpp v3, v3, v3 row_shr:4 row_mask:0xf bank_mask:0xf bound_ctrl:1
	s_nop 1
	v_add_f32_dpp v3, v3, v3 row_shr:8 row_mask:0xf bank_mask:0xf bound_ctrl:1
	s_nop 1
	v_mov_b32_dpp v4, v3 row_bcast:15 row_mask:0xa bank_mask:0xf
	v_add_f32_e32 v3, v3, v4
	v_mov_b32_e32 v4, v1
	s_nop 1
	v_mov_b32_dpp v4, v3 row_bcast:31 row_mask:0xc bank_mask:0xf
	v_add_f32_e32 v3, v3, v4
	s_nop 0
	v_readlane_b32 s3, v3, 63
	s_and_saveexec_b64 s[0:1], vcc
	v_add_u32_e32 v3, 0xf868, v2
	v_mov_b32_e32 v4, s2
	v_mov_b32_e32 v5, s3
	ds_write2_b32 v3, v4, v5 offset1:1
	s_or_b64 exec, exec, s[0:1]
	v_add_f32_e32 v3, v52, v53
	v_mov_b32_e32 v4, v1
	s_nop 0
	v_add_f32_dpp v3, v3, v3 row_shr:1 row_mask:0xf bank_mask:0xf bound_ctrl:1
	s_nop 1
	v_add_f32_dpp v3, v3, v3 row_shr:2 row_mask:0xf bank_mask:0xf bound_ctrl:1
	s_nop 1
	v_add_f32_dpp v3, v3, v3 row_shr:4 row_mask:0xf bank_mask:0xf bound_ctrl:1
	s_nop 1
	v_add_f32_dpp v3, v3, v3 row_shr:8 row_mask:0xf bank_mask:0xf bound_ctrl:1
	s_nop 1
	v_mov_b32_dpp v4, v3 row_bcast:15 row_mask:0xa bank_mask:0xf
	v_add_f32_e32 v3, v3, v4
	v_mov_b32_e32 v4, v1
	s_nop 1
	v_mov_b32_dpp v4, v3 row_bcast:31 row_mask:0xc bank_mask:0xf
	v_add_f32_e32 v3, v3, v4
	v_mov_b32_e32 v4, v1
	v_readlane_b32 s2, v3, 63
	v_mul_f32_e32 v3, v53, v53
	v_fmac_f32_e32 v3, v52, v52
	s_nop 1
	v_add_f32_dpp v3, v3, v3 row_shr:1 row_mask:0xf bank_mask:0xf bound_ctrl:1
	s_nop 1
	v_add_f32_dpp v3, v3, v3 row_shr:2 row_mask:0xf bank_mask:0xf bound_ctrl:1
	s_nop 1
	v_add_f32_dpp v3, v3, v3 row_shr:4 row_mask:0xf bank_mask:0xf bound_ctrl:1
	s_nop 1
	v_add_f32_dpp v3, v3, v3 row_shr:8 row_mask:0xf bank_mask:0xf bound_ctrl:1
	s_nop 1
	v_mov_b32_dpp v4, v3 row_bcast:15 row_mask:0xa bank_mask:0xf
	v_add_f32_e32 v3, v3, v4
	v_mov_b32_e32 v4, v1
	s_nop 1
	v_mov_b32_dpp v4, v3 row_bcast:31 row_mask:0xc bank_mask:0xf
	v_add_f32_e32 v3, v3, v4
	s_nop 0
	v_readlane_b32 s3, v3, 63
	s_and_saveexec_b64 s[0:1], vcc
	v_add_u32_e32 v3, 0xf870, v2
	v_mov_b32_e32 v4, s2
	v_mov_b32_e32 v5, s3
	ds_write2_b32 v3, v4, v5 offset1:1
	s_or_b64 exec, exec, s[0:1]
	v_add_f32_e32 v3, v50, v51
	v_mov_b32_e32 v4, v1
	s_nop 0
	v_add_f32_dpp v3, v3, v3 row_shr:1 row_mask:0xf bank_mask:0xf bound_ctrl:1
	s_nop 1
	v_add_f32_dpp v3, v3, v3 row_shr:2 row_mask:0xf bank_mask:0xf bound_ctrl:1
	s_nop 1
	v_add_f32_dpp v3, v3, v3 row_shr:4 row_mask:0xf bank_mask:0xf bound_ctrl:1
	s_nop 1
	v_add_f32_dpp v3, v3, v3 row_shr:8 row_mask:0xf bank_mask:0xf bound_ctrl:1
	s_nop 1
	v_mov_b32_dpp v4, v3 row_bcast:15 row_mask:0xa bank_mask:0xf
	v_add_f32_e32 v3, v3, v4
	v_mov_b32_e32 v4, v1
	s_nop 1
	v_mov_b32_dpp v4, v3 row_bcast:31 row_mask:0xc bank_mask:0xf
	v_add_f32_e32 v3, v3, v4
	v_mov_b32_e32 v4, v1
	v_readlane_b32 s2, v3, 63
	v_mul_f32_e32 v3, v51, v51
	v_fmac_f32_e32 v3, v50, v50
	s_nop 1
	v_add_f32_dpp v3, v3, v3 row_shr:1 row_mask:0xf bank_mask:0xf bound_ctrl:1
	s_nop 1
	v_add_f32_dpp v3, v3, v3 row_shr:2 row_mask:0xf bank_mask:0xf bound_ctrl:1
	s_nop 1
	v_add_f32_dpp v3, v3, v3 row_shr:4 row_mask:0xf bank_mask:0xf bound_ctrl:1
	s_nop 1
	v_add_f32_dpp v3, v3, v3 row_shr:8 row_mask:0xf bank_mask:0xf bound_ctrl:1
	s_nop 1
	v_mov_b32_dpp v4, v3 row_bcast:15 row_mask:0xa bank_mask:0xf
	v_add_f32_e32 v3, v3, v4
	v_mov_b32_e32 v4, v1
	s_nop 1
	v_mov_b32_dpp v4, v3 row_bcast:31 row_mask:0xc bank_mask:0xf
	v_add_f32_e32 v3, v3, v4
	s_nop 0
	v_readlane_b32 s3, v3, 63
	s_and_saveexec_b64 s[0:1], vcc
	v_add_u32_e32 v3, 0xf878, v2
	v_mov_b32_e32 v4, s2
	v_mov_b32_e32 v5, s3
	ds_write2_b32 v3, v4, v5 offset1:1
	s_or_b64 exec, exec, s[0:1]
	v_add_f32_e32 v3, v48, v49
	v_mov_b32_e32 v4, v1
	s_nop 0
	v_add_f32_dpp v3, v3, v3 row_shr:1 row_mask:0xf bank_mask:0xf bound_ctrl:1
	s_nop 1
	v_add_f32_dpp v3, v3, v3 row_shr:2 row_mask:0xf bank_mask:0xf bound_ctrl:1
	s_nop 1
	v_add_f32_dpp v3, v3, v3 row_shr:4 row_mask:0xf bank_mask:0xf bound_ctrl:1
	s_nop 1
	v_add_f32_dpp v3, v3, v3 row_shr:8 row_mask:0xf bank_mask:0xf bound_ctrl:1
	s_nop 1
	v_mov_b32_dpp v4, v3 row_bcast:15 row_mask:0xa bank_mask:0xf
	v_add_f32_e32 v3, v3, v4
	v_mov_b32_e32 v4, v1
	s_nop 1
	v_mov_b32_dpp v4, v3 row_bcast:31 row_mask:0xc bank_mask:0xf
	v_add_f32_e32 v3, v3, v4
	v_mov_b32_e32 v4, v1
	v_readlane_b32 s2, v3, 63
	v_mul_f32_e32 v3, v49, v49
	v_fmac_f32_e32 v3, v48, v48
	s_nop 1
	v_add_f32_dpp v3, v3, v3 row_shr:1 row_mask:0xf bank_mask:0xf bound_ctrl:1
	s_nop 1
	v_add_f32_dpp v3, v3, v3 row_shr:2 row_mask:0xf bank_mask:0xf bound_ctrl:1
	s_nop 1
	v_add_f32_dpp v3, v3, v3 row_shr:4 row_mask:0xf bank_mask:0xf bound_ctrl:1
	s_nop 1
	v_add_f32_dpp v3, v3, v3 row_shr:8 row_mask:0xf bank_mask:0xf bound_ctrl:1
	s_nop 1
	v_mov_b32_dpp v4, v3 row_bcast:15 row_mask:0xa bank_mask:0xf
	v_add_f32_e32 v3, v3, v4
	v_mov_b32_e32 v4, v1
	s_nop 1
	v_mov_b32_dpp v4, v3 row_bcast:31 row_mask:0xc bank_mask:0xf
	v_add_f32_e32 v3, v3, v4
	s_nop 0
	v_readlane_b32 s3, v3, 63
	s_and_saveexec_b64 s[0:1], vcc
	v_add_u32_e32 v3, 0xf880, v2
	v_mov_b32_e32 v4, s2
	v_mov_b32_e32 v5, s3
	ds_write2_b32 v3, v4, v5 offset1:1
	s_or_b64 exec, exec, s[0:1]
	v_add_f32_e32 v3, v46, v47
	v_mov_b32_e32 v4, v1
	s_nop 0
	v_add_f32_dpp v3, v3, v3 row_shr:1 row_mask:0xf bank_mask:0xf bound_ctrl:1
	s_nop 1
	v_add_f32_dpp v3, v3, v3 row_shr:2 row_mask:0xf bank_mask:0xf bound_ctrl:1
	s_nop 1
	v_add_f32_dpp v3, v3, v3 row_shr:4 row_mask:0xf bank_mask:0xf bound_ctrl:1
	s_nop 1
	v_add_f32_dpp v3, v3, v3 row_shr:8 row_mask:0xf bank_mask:0xf bound_ctrl:1
	s_nop 1
	v_mov_b32_dpp v4, v3 row_bcast:15 row_mask:0xa bank_mask:0xf
	v_add_f32_e32 v3, v3, v4
	v_mov_b32_e32 v4, v1
	s_nop 1
	v_mov_b32_dpp v4, v3 row_bcast:31 row_mask:0xc bank_mask:0xf
	v_add_f32_e32 v3, v3, v4
	v_mov_b32_e32 v4, v1
	v_readlane_b32 s2, v3, 63
	v_mul_f32_e32 v3, v47, v47
	v_fmac_f32_e32 v3, v46, v46
	s_nop 1
	v_add_f32_dpp v3, v3, v3 row_shr:1 row_mask:0xf bank_mask:0xf bound_ctrl:1
	s_nop 1
	v_add_f32_dpp v3, v3, v3 row_shr:2 row_mask:0xf bank_mask:0xf bound_ctrl:1
	s_nop 1
	v_add_f32_dpp v3, v3, v3 row_shr:4 row_mask:0xf bank_mask:0xf bound_ctrl:1
	s_nop 1
	v_add_f32_dpp v3, v3, v3 row_shr:8 row_mask:0xf bank_mask:0xf bound_ctrl:1
	s_nop 1
	v_mov_b32_dpp v4, v3 row_bcast:15 row_mask:0xa bank_mask:0xf
	v_add_f32_e32 v3, v3, v4
	v_mov_b32_e32 v4, v1
	s_nop 1
	v_mov_b32_dpp v4, v3 row_bcast:31 row_mask:0xc bank_mask:0xf
	v_add_f32_e32 v3, v3, v4
	s_nop 0
	v_readlane_b32 s3, v3, 63
	s_and_saveexec_b64 s[0:1], vcc
	v_add_u32_e32 v3, 0xf888, v2
	v_mov_b32_e32 v4, s2
	v_mov_b32_e32 v5, s3
	ds_write2_b32 v3, v4, v5 offset1:1
	s_or_b64 exec, exec, s[0:1]
	v_add_f32_e32 v3, v44, v45
	v_mov_b32_e32 v4, v1
	s_nop 0
	v_add_f32_dpp v3, v3, v3 row_shr:1 row_mask:0xf bank_mask:0xf bound_ctrl:1
	s_nop 1
	v_add_f32_dpp v3, v3, v3 row_shr:2 row_mask:0xf bank_mask:0xf bound_ctrl:1
	s_nop 1
	v_add_f32_dpp v3, v3, v3 row_shr:4 row_mask:0xf bank_mask:0xf bound_ctrl:1
	s_nop 1
	v_add_f32_dpp v3, v3, v3 row_shr:8 row_mask:0xf bank_mask:0xf bound_ctrl:1
	s_nop 1
	v_mov_b32_dpp v4, v3 row_bcast:15 row_mask:0xa bank_mask:0xf
	v_add_f32_e32 v3, v3, v4
	v_mov_b32_e32 v4, v1
	s_nop 1
	v_mov_b32_dpp v4, v3 row_bcast:31 row_mask:0xc bank_mask:0xf
	v_add_f32_e32 v3, v3, v4
	v_mov_b32_e32 v4, v1
	v_readlane_b32 s2, v3, 63
	v_mul_f32_e32 v3, v45, v45
	v_fmac_f32_e32 v3, v44, v44
	s_nop 1
	v_add_f32_dpp v3, v3, v3 row_shr:1 row_mask:0xf bank_mask:0xf bound_ctrl:1
	s_nop 1
	v_add_f32_dpp v3, v3, v3 row_shr:2 row_mask:0xf bank_mask:0xf bound_ctrl:1
	s_nop 1
	v_add_f32_dpp v3, v3, v3 row_shr:4 row_mask:0xf bank_mask:0xf bound_ctrl:1
	s_nop 1
	v_add_f32_dpp v3, v3, v3 row_shr:8 row_mask:0xf bank_mask:0xf bound_ctrl:1
	s_nop 1
	v_mov_b32_dpp v4, v3 row_bcast:15 row_mask:0xa bank_mask:0xf
	v_add_f32_e32 v3, v3, v4
	v_mov_b32_e32 v4, v1
	s_nop 1
	v_mov_b32_dpp v4, v3 row_bcast:31 row_mask:0xc bank_mask:0xf
	v_add_f32_e32 v3, v3, v4
	s_nop 0
	v_readlane_b32 s3, v3, 63
	s_and_saveexec_b64 s[0:1], vcc
	v_add_u32_e32 v3, 0xf890, v2
	v_mov_b32_e32 v4, s2
	v_mov_b32_e32 v5, s3
	ds_write2_b32 v3, v4, v5 offset1:1
	s_or_b64 exec, exec, s[0:1]
	v_add_f32_e32 v3, v42, v43
	v_mov_b32_e32 v4, v1
	s_nop 0
	v_add_f32_dpp v3, v3, v3 row_shr:1 row_mask:0xf bank_mask:0xf bound_ctrl:1
	s_nop 1
	v_add_f32_dpp v3, v3, v3 row_shr:2 row_mask:0xf bank_mask:0xf bound_ctrl:1
	s_nop 1
	v_add_f32_dpp v3, v3, v3 row_shr:4 row_mask:0xf bank_mask:0xf bound_ctrl:1
	s_nop 1
	v_add_f32_dpp v3, v3, v3 row_shr:8 row_mask:0xf bank_mask:0xf bound_ctrl:1
	s_nop 1
	v_mov_b32_dpp v4, v3 row_bcast:15 row_mask:0xa bank_mask:0xf
	v_add_f32_e32 v3, v3, v4
	v_mov_b32_e32 v4, v1
	s_nop 1
	v_mov_b32_dpp v4, v3 row_bcast:31 row_mask:0xc bank_mask:0xf
	v_add_f32_e32 v3, v3, v4
	v_mov_b32_e32 v4, v1
	v_readlane_b32 s2, v3, 63
	v_mul_f32_e32 v3, v43, v43
	v_fmac_f32_e32 v3, v42, v42
	s_nop 1
	v_add_f32_dpp v3, v3, v3 row_shr:1 row_mask:0xf bank_mask:0xf bound_ctrl:1
	s_nop 1
	v_add_f32_dpp v3, v3, v3 row_shr:2 row_mask:0xf bank_mask:0xf bound_ctrl:1
	s_nop 1
	v_add_f32_dpp v3, v3, v3 row_shr:4 row_mask:0xf bank_mask:0xf bound_ctrl:1
	s_nop 1
	v_add_f32_dpp v3, v3, v3 row_shr:8 row_mask:0xf bank_mask:0xf bound_ctrl:1
	s_nop 1
	v_mov_b32_dpp v4, v3 row_bcast:15 row_mask:0xa bank_mask:0xf
	v_add_f32_e32 v3, v3, v4
	v_mov_b32_e32 v4, v1
	s_nop 1
	v_mov_b32_dpp v4, v3 row_bcast:31 row_mask:0xc bank_mask:0xf
	v_add_f32_e32 v3, v3, v4
	s_nop 0
	v_readlane_b32 s3, v3, 63
	s_and_saveexec_b64 s[0:1], vcc
	v_add_u32_e32 v3, 0xf898, v2
	v_mov_b32_e32 v4, s2
	v_mov_b32_e32 v5, s3
	ds_write2_b32 v3, v4, v5 offset1:1
	s_or_b64 exec, exec, s[0:1]
	v_add_f32_e32 v3, v40, v41
	v_mov_b32_e32 v4, v1
	s_nop 0
	v_add_f32_dpp v3, v3, v3 row_shr:1 row_mask:0xf bank_mask:0xf bound_ctrl:1
	s_nop 1
	v_add_f32_dpp v3, v3, v3 row_shr:2 row_mask:0xf bank_mask:0xf bound_ctrl:1
	s_nop 1
	v_add_f32_dpp v3, v3, v3 row_shr:4 row_mask:0xf bank_mask:0xf bound_ctrl:1
	s_nop 1
	v_add_f32_dpp v3, v3, v3 row_shr:8 row_mask:0xf bank_mask:0xf bound_ctrl:1
	s_nop 1
	v_mov_b32_dpp v4, v3 row_bcast:15 row_mask:0xa bank_mask:0xf
	v_add_f32_e32 v3, v3, v4
	v_mov_b32_e32 v4, v1
	s_nop 1
	v_mov_b32_dpp v4, v3 row_bcast:31 row_mask:0xc bank_mask:0xf
	v_add_f32_e32 v3, v3, v4
	v_mov_b32_e32 v4, v1
	v_readlane_b32 s2, v3, 63
	v_mul_f32_e32 v3, v41, v41
	v_fmac_f32_e32 v3, v40, v40
	s_nop 1
	v_add_f32_dpp v3, v3, v3 row_shr:1 row_mask:0xf bank_mask:0xf bound_ctrl:1
	s_nop 1
	v_add_f32_dpp v3, v3, v3 row_shr:2 row_mask:0xf bank_mask:0xf bound_ctrl:1
	s_nop 1
	v_add_f32_dpp v3, v3, v3 row_shr:4 row_mask:0xf bank_mask:0xf bound_ctrl:1
	s_nop 1
	v_add_f32_dpp v3, v3, v3 row_shr:8 row_mask:0xf bank_mask:0xf bound_ctrl:1
	s_nop 1
	v_mov_b32_dpp v4, v3 row_bcast:15 row_mask:0xa bank_mask:0xf
	v_add_f32_e32 v3, v3, v4
	v_mov_b32_e32 v4, v1
	s_nop 1
	v_mov_b32_dpp v4, v3 row_bcast:31 row_mask:0xc bank_mask:0xf
	v_add_f32_e32 v3, v3, v4
	s_nop 0
	v_readlane_b32 s3, v3, 63
	s_and_saveexec_b64 s[0:1], vcc
	v_add_u32_e32 v3, 0xf8a0, v2
	v_mov_b32_e32 v4, s2
	v_mov_b32_e32 v5, s3
	ds_write2_b32 v3, v4, v5 offset1:1
	s_or_b64 exec, exec, s[0:1]
	v_add_f32_e32 v3, v38, v39
	v_mov_b32_e32 v4, v1
	s_nop 0
	v_add_f32_dpp v3, v3, v3 row_shr:1 row_mask:0xf bank_mask:0xf bound_ctrl:1
	s_nop 1
	v_add_f32_dpp v3, v3, v3 row_shr:2 row_mask:0xf bank_mask:0xf bound_ctrl:1
	s_nop 1
	v_add_f32_dpp v3, v3, v3 row_shr:4 row_mask:0xf bank_mask:0xf bound_ctrl:1
	s_nop 1
	v_add_f32_dpp v3, v3, v3 row_shr:8 row_mask:0xf bank_mask:0xf bound_ctrl:1
	s_nop 1
	v_mov_b32_dpp v4, v3 row_bcast:15 row_mask:0xa bank_mask:0xf
	v_add_f32_e32 v3, v3, v4
	v_mov_b32_e32 v4, v1
	s_nop 1
	v_mov_b32_dpp v4, v3 row_bcast:31 row_mask:0xc bank_mask:0xf
	v_add_f32_e32 v3, v3, v4
	v_mov_b32_e32 v4, v1
	v_readlane_b32 s2, v3, 63
	v_mul_f32_e32 v3, v39, v39
	v_fmac_f32_e32 v3, v38, v38
	s_nop 1
	v_add_f32_dpp v3, v3, v3 row_shr:1 row_mask:0xf bank_mask:0xf bound_ctrl:1
	s_nop 1
	v_add_f32_dpp v3, v3, v3 row_shr:2 row_mask:0xf bank_mask:0xf bound_ctrl:1
	s_nop 1
	v_add_f32_dpp v3, v3, v3 row_shr:4 row_mask:0xf bank_mask:0xf bound_ctrl:1
	s_nop 1
	v_add_f32_dpp v3, v3, v3 row_shr:8 row_mask:0xf bank_mask:0xf bound_ctrl:1
	s_nop 1
	v_mov_b32_dpp v4, v3 row_bcast:15 row_mask:0xa bank_mask:0xf
	v_add_f32_e32 v3, v3, v4
	v_mov_b32_e32 v4, v1
	s_nop 1
	v_mov_b32_dpp v4, v3 row_bcast:31 row_mask:0xc bank_mask:0xf
	v_add_f32_e32 v3, v3, v4
	s_nop 0
	v_readlane_b32 s3, v3, 63
	s_and_saveexec_b64 s[0:1], vcc
	v_add_u32_e32 v3, 0xf8a8, v2
	v_mov_b32_e32 v4, s2
	v_mov_b32_e32 v5, s3
	ds_write2_b32 v3, v4, v5 offset1:1
	s_or_b64 exec, exec, s[0:1]
	v_add_f32_e32 v3, v30, v31
	v_mov_b32_e32 v4, v1
	s_nop 0
	v_add_f32_dpp v3, v3, v3 row_shr:1 row_mask:0xf bank_mask:0xf bound_ctrl:1
	s_nop 1
	v_add_f32_dpp v3, v3, v3 row_shr:2 row_mask:0xf bank_mask:0xf bound_ctrl:1
	s_nop 1
	v_add_f32_dpp v3, v3, v3 row_shr:4 row_mask:0xf bank_mask:0xf bound_ctrl:1
	s_nop 1
	v_add_f32_dpp v3, v3, v3 row_shr:8 row_mask:0xf bank_mask:0xf bound_ctrl:1
	s_nop 1
	v_mov_b32_dpp v4, v3 row_bcast:15 row_mask:0xa bank_mask:0xf
	v_add_f32_e32 v3, v3, v4
	v_mov_b32_e32 v4, v1
	s_nop 1
	v_mov_b32_dpp v4, v3 row_bcast:31 row_mask:0xc bank_mask:0xf
	v_add_f32_e32 v3, v3, v4
	v_mov_b32_e32 v4, v1
	v_readlane_b32 s2, v3, 63
	v_mul_f32_e32 v3, v31, v31
	v_fmac_f32_e32 v3, v30, v30
	s_nop 1
	v_add_f32_dpp v3, v3, v3 row_shr:1 row_mask:0xf bank_mask:0xf bound_ctrl:1
	s_nop 1
	v_add_f32_dpp v3, v3, v3 row_shr:2 row_mask:0xf bank_mask:0xf bound_ctrl:1
	s_nop 1
	v_add_f32_dpp v3, v3, v3 row_shr:4 row_mask:0xf bank_mask:0xf bound_ctrl:1
	s_nop 1
	v_add_f32_dpp v3, v3, v3 row_shr:8 row_mask:0xf bank_mask:0xf bound_ctrl:1
	s_nop 1
	v_mov_b32_dpp v4, v3 row_bcast:15 row_mask:0xa bank_mask:0xf
	v_add_f32_e32 v3, v3, v4
	v_mov_b32_e32 v4, v1
	s_nop 1
	v_mov_b32_dpp v4, v3 row_bcast:31 row_mask:0xc bank_mask:0xf
	v_add_f32_e32 v3, v3, v4
	s_nop 0
	v_readlane_b32 s3, v3, 63
	s_and_saveexec_b64 s[0:1], vcc
	v_add_u32_e32 v3, 0xf8b0, v2
	v_mov_b32_e32 v4, s2
	v_mov_b32_e32 v5, s3
	ds_write2_b32 v3, v4, v5 offset1:1
	s_or_b64 exec, exec, s[0:1]
	v_add_f32_e32 v3, v28, v29
	v_mov_b32_e32 v4, v1
	s_nop 0
	v_add_f32_dpp v3, v3, v3 row_shr:1 row_mask:0xf bank_mask:0xf bound_ctrl:1
	s_nop 1
	v_add_f32_dpp v3, v3, v3 row_shr:2 row_mask:0xf bank_mask:0xf bound_ctrl:1
	s_nop 1
	v_add_f32_dpp v3, v3, v3 row_shr:4 row_mask:0xf bank_mask:0xf bound_ctrl:1
	s_nop 1
	v_add_f32_dpp v3, v3, v3 row_shr:8 row_mask:0xf bank_mask:0xf bound_ctrl:1
	s_nop 1
	v_mov_b32_dpp v4, v3 row_bcast:15 row_mask:0xa bank_mask:0xf
	v_add_f32_e32 v3, v3, v4
	v_mov_b32_e32 v4, v1
	s_nop 1
	v_mov_b32_dpp v4, v3 row_bcast:31 row_mask:0xc bank_mask:0xf
	v_add_f32_e32 v3, v3, v4
	v_mov_b32_e32 v4, v1
	v_readlane_b32 s2, v3, 63
	v_mul_f32_e32 v3, v29, v29
	v_fmac_f32_e32 v3, v28, v28
	s_nop 1
	v_add_f32_dpp v3, v3, v3 row_shr:1 row_mask:0xf bank_mask:0xf bound_ctrl:1
	s_nop 1
	v_add_f32_dpp v3, v3, v3 row_shr:2 row_mask:0xf bank_mask:0xf bound_ctrl:1
	s_nop 1
	v_add_f32_dpp v3, v3, v3 row_shr:4 row_mask:0xf bank_mask:0xf bound_ctrl:1
	s_nop 1
	v_add_f32_dpp v3, v3, v3 row_shr:8 row_mask:0xf bank_mask:0xf bound_ctrl:1
	s_nop 1
	v_mov_b32_dpp v4, v3 row_bcast:15 row_mask:0xa bank_mask:0xf
	v_add_f32_e32 v3, v3, v4
	v_mov_b32_e32 v4, v1
	s_nop 1
	v_mov_b32_dpp v4, v3 row_bcast:31 row_mask:0xc bank_mask:0xf
	v_add_f32_e32 v3, v3, v4
	s_nop 0
	v_readlane_b32 s3, v3, 63
	s_and_saveexec_b64 s[0:1], vcc
	v_add_u32_e32 v3, 0xf8b8, v2
	v_mov_b32_e32 v4, s2
	v_mov_b32_e32 v5, s3
	ds_write2_b32 v3, v4, v5 offset1:1
	s_or_b64 exec, exec, s[0:1]
	v_add_f32_e32 v3, v26, v27
	v_mov_b32_e32 v4, v1
	s_nop 0
	v_add_f32_dpp v3, v3, v3 row_shr:1 row_mask:0xf bank_mask:0xf bound_ctrl:1
	s_nop 1
	v_add_f32_dpp v3, v3, v3 row_shr:2 row_mask:0xf bank_mask:0xf bound_ctrl:1
	s_nop 1
	v_add_f32_dpp v3, v3, v3 row_shr:4 row_mask:0xf bank_mask:0xf bound_ctrl:1
	s_nop 1
	v_add_f32_dpp v3, v3, v3 row_shr:8 row_mask:0xf bank_mask:0xf bound_ctrl:1
	s_nop 1
	v_mov_b32_dpp v4, v3 row_bcast:15 row_mask:0xa bank_mask:0xf
	v_add_f32_e32 v3, v3, v4
	v_mov_b32_e32 v4, v1
	s_nop 1
	v_mov_b32_dpp v4, v3 row_bcast:31 row_mask:0xc bank_mask:0xf
	v_add_f32_e32 v3, v3, v4
	v_mov_b32_e32 v4, v1
	v_readlane_b32 s2, v3, 63
	v_mul_f32_e32 v3, v27, v27
	v_fmac_f32_e32 v3, v26, v26
	s_nop 1
	v_add_f32_dpp v3, v3, v3 row_shr:1 row_mask:0xf bank_mask:0xf bound_ctrl:1
	s_nop 1
	v_add_f32_dpp v3, v3, v3 row_shr:2 row_mask:0xf bank_mask:0xf bound_ctrl:1
	s_nop 1
	v_add_f32_dpp v3, v3, v3 row_shr:4 row_mask:0xf bank_mask:0xf bound_ctrl:1
	s_nop 1
	v_add_f32_dpp v3, v3, v3 row_shr:8 row_mask:0xf bank_mask:0xf bound_ctrl:1
	s_nop 1
	v_mov_b32_dpp v4, v3 row_bcast:15 row_mask:0xa bank_mask:0xf
	v_add_f32_e32 v3, v3, v4
	v_mov_b32_e32 v4, v1
	s_nop 1
	v_mov_b32_dpp v4, v3 row_bcast:31 row_mask:0xc bank_mask:0xf
	v_add_f32_e32 v3, v3, v4
	s_nop 0
	v_readlane_b32 s3, v3, 63
	s_and_saveexec_b64 s[0:1], vcc
	v_add_u32_e32 v3, 0xf8c0, v2
	v_mov_b32_e32 v4, s2
	v_mov_b32_e32 v5, s3
	ds_write2_b32 v3, v4, v5 offset1:1
	s_or_b64 exec, exec, s[0:1]
	v_add_f32_e32 v3, v24, v25
	v_mov_b32_e32 v4, v1
	s_nop 0
	v_add_f32_dpp v3, v3, v3 row_shr:1 row_mask:0xf bank_mask:0xf bound_ctrl:1
	s_nop 1
	v_add_f32_dpp v3, v3, v3 row_shr:2 row_mask:0xf bank_mask:0xf bound_ctrl:1
	s_nop 1
	v_add_f32_dpp v3, v3, v3 row_shr:4 row_mask:0xf bank_mask:0xf bound_ctrl:1
	s_nop 1
	v_add_f32_dpp v3, v3, v3 row_shr:8 row_mask:0xf bank_mask:0xf bound_ctrl:1
	s_nop 1
	v_mov_b32_dpp v4, v3 row_bcast:15 row_mask:0xa bank_mask:0xf
	v_add_f32_e32 v3, v3, v4
	v_mov_b32_e32 v4, v1
	s_nop 1
	v_mov_b32_dpp v4, v3 row_bcast:31 row_mask:0xc bank_mask:0xf
	v_add_f32_e32 v3, v3, v4
	v_mov_b32_e32 v4, v1
	v_readlane_b32 s2, v3, 63
	v_mul_f32_e32 v3, v25, v25
	v_fmac_f32_e32 v3, v24, v24
	s_nop 1
	v_add_f32_dpp v3, v3, v3 row_shr:1 row_mask:0xf bank_mask:0xf bound_ctrl:1
	s_nop 1
	v_add_f32_dpp v3, v3, v3 row_shr:2 row_mask:0xf bank_mask:0xf bound_ctrl:1
	s_nop 1
	v_add_f32_dpp v3, v3, v3 row_shr:4 row_mask:0xf bank_mask:0xf bound_ctrl:1
	s_nop 1
	v_add_f32_dpp v3, v3, v3 row_shr:8 row_mask:0xf bank_mask:0xf bound_ctrl:1
	s_nop 1
	v_mov_b32_dpp v4, v3 row_bcast:15 row_mask:0xa bank_mask:0xf
	v_add_f32_e32 v3, v3, v4
	v_mov_b32_e32 v4, v1
	s_nop 1
	v_mov_b32_dpp v4, v3 row_bcast:31 row_mask:0xc bank_mask:0xf
	v_add_f32_e32 v3, v3, v4
	s_nop 0
	v_readlane_b32 s3, v3, 63
	s_and_saveexec_b64 s[0:1], vcc
	v_add_u32_e32 v3, 0xf8c8, v2
	v_mov_b32_e32 v4, s2
	v_mov_b32_e32 v5, s3
	ds_write2_b32 v3, v4, v5 offset1:1
	s_or_b64 exec, exec, s[0:1]
	v_add_f32_e32 v3, v22, v23
	v_mov_b32_e32 v4, v1
	s_nop 0
	v_add_f32_dpp v3, v3, v3 row_shr:1 row_mask:0xf bank_mask:0xf bound_ctrl:1
	s_nop 1
	v_add_f32_dpp v3, v3, v3 row_shr:2 row_mask:0xf bank_mask:0xf bound_ctrl:1
	s_nop 1
	v_add_f32_dpp v3, v3, v3 row_shr:4 row_mask:0xf bank_mask:0xf bound_ctrl:1
	s_nop 1
	v_add_f32_dpp v3, v3, v3 row_shr:8 row_mask:0xf bank_mask:0xf bound_ctrl:1
	s_nop 1
	v_mov_b32_dpp v4, v3 row_bcast:15 row_mask:0xa bank_mask:0xf
	v_add_f32_e32 v3, v3, v4
	v_mov_b32_e32 v4, v1
	s_nop 1
	v_mov_b32_dpp v4, v3 row_bcast:31 row_mask:0xc bank_mask:0xf
	v_add_f32_e32 v3, v3, v4
	v_mov_b32_e32 v4, v1
	v_readlane_b32 s2, v3, 63
	v_mul_f32_e32 v3, v23, v23
	v_fmac_f32_e32 v3, v22, v22
	s_nop 1
	v_add_f32_dpp v3, v3, v3 row_shr:1 row_mask:0xf bank_mask:0xf bound_ctrl:1
	s_nop 1
	v_add_f32_dpp v3, v3, v3 row_shr:2 row_mask:0xf bank_mask:0xf bound_ctrl:1
	s_nop 1
	v_add_f32_dpp v3, v3, v3 row_shr:4 row_mask:0xf bank_mask:0xf bound_ctrl:1
	s_nop 1
	v_add_f32_dpp v3, v3, v3 row_shr:8 row_mask:0xf bank_mask:0xf bound_ctrl:1
	s_nop 1
	v_mov_b32_dpp v4, v3 row_bcast:15 row_mask:0xa bank_mask:0xf
	v_add_f32_e32 v3, v3, v4
	v_mov_b32_e32 v4, v1
	s_nop 1
	v_mov_b32_dpp v4, v3 row_bcast:31 row_mask:0xc bank_mask:0xf
	v_add_f32_e32 v3, v3, v4
	s_nop 0
	v_readlane_b32 s3, v3, 63
	s_and_saveexec_b64 s[0:1], vcc
	v_add_u32_e32 v3, 0xf8d0, v2
	v_mov_b32_e32 v4, s2
	v_mov_b32_e32 v5, s3
	ds_write2_b32 v3, v4, v5 offset1:1
	s_or_b64 exec, exec, s[0:1]
	v_add_f32_e32 v3, v20, v21
	v_mov_b32_e32 v4, v1
	s_nop 0
	v_add_f32_dpp v3, v3, v3 row_shr:1 row_mask:0xf bank_mask:0xf bound_ctrl:1
	s_nop 1
	v_add_f32_dpp v3, v3, v3 row_shr:2 row_mask:0xf bank_mask:0xf bound_ctrl:1
	s_nop 1
	v_add_f32_dpp v3, v3, v3 row_shr:4 row_mask:0xf bank_mask:0xf bound_ctrl:1
	s_nop 1
	v_add_f32_dpp v3, v3, v3 row_shr:8 row_mask:0xf bank_mask:0xf bound_ctrl:1
	s_nop 1
	v_mov_b32_dpp v4, v3 row_bcast:15 row_mask:0xa bank_mask:0xf
	v_add_f32_e32 v3, v3, v4
	v_mov_b32_e32 v4, v1
	s_nop 1
	v_mov_b32_dpp v4, v3 row_bcast:31 row_mask:0xc bank_mask:0xf
	v_add_f32_e32 v3, v3, v4
	v_mov_b32_e32 v4, v1
	v_readlane_b32 s2, v3, 63
	v_mul_f32_e32 v3, v21, v21
	v_fmac_f32_e32 v3, v20, v20
	s_nop 1
	v_add_f32_dpp v3, v3, v3 row_shr:1 row_mask:0xf bank_mask:0xf bound_ctrl:1
	s_nop 1
	v_add_f32_dpp v3, v3, v3 row_shr:2 row_mask:0xf bank_mask:0xf bound_ctrl:1
	s_nop 1
	v_add_f32_dpp v3, v3, v3 row_shr:4 row_mask:0xf bank_mask:0xf bound_ctrl:1
	s_nop 1
	v_add_f32_dpp v3, v3, v3 row_shr:8 row_mask:0xf bank_mask:0xf bound_ctrl:1
	s_nop 1
	v_mov_b32_dpp v4, v3 row_bcast:15 row_mask:0xa bank_mask:0xf
	v_add_f32_e32 v3, v3, v4
	v_mov_b32_e32 v4, v1
	s_nop 1
	v_mov_b32_dpp v4, v3 row_bcast:31 row_mask:0xc bank_mask:0xf
	v_add_f32_e32 v3, v3, v4
	s_nop 0
	v_readlane_b32 s3, v3, 63
	s_and_saveexec_b64 s[0:1], vcc
	v_add_u32_e32 v3, 0xf8d8, v2
	v_mov_b32_e32 v4, s2
	v_mov_b32_e32 v5, s3
	ds_write2_b32 v3, v4, v5 offset1:1
	s_or_b64 exec, exec, s[0:1]
	v_add_f32_e32 v3, v18, v19
	v_mov_b32_e32 v4, v1
	s_nop 0
	v_add_f32_dpp v3, v3, v3 row_shr:1 row_mask:0xf bank_mask:0xf bound_ctrl:1
	s_nop 1
	v_add_f32_dpp v3, v3, v3 row_shr:2 row_mask:0xf bank_mask:0xf bound_ctrl:1
	s_nop 1
	v_add_f32_dpp v3, v3, v3 row_shr:4 row_mask:0xf bank_mask:0xf bound_ctrl:1
	s_nop 1
	v_add_f32_dpp v3, v3, v3 row_shr:8 row_mask:0xf bank_mask:0xf bound_ctrl:1
	s_nop 1
	v_mov_b32_dpp v4, v3 row_bcast:15 row_mask:0xa bank_mask:0xf
	v_add_f32_e32 v3, v3, v4
	v_mov_b32_e32 v4, v1
	s_nop 1
	v_mov_b32_dpp v4, v3 row_bcast:31 row_mask:0xc bank_mask:0xf
	v_add_f32_e32 v3, v3, v4
	v_mov_b32_e32 v4, v1
	v_readlane_b32 s2, v3, 63
	v_mul_f32_e32 v3, v19, v19
	v_fmac_f32_e32 v3, v18, v18
	s_nop 1
	v_add_f32_dpp v3, v3, v3 row_shr:1 row_mask:0xf bank_mask:0xf bound_ctrl:1
	s_nop 1
	v_add_f32_dpp v3, v3, v3 row_shr:2 row_mask:0xf bank_mask:0xf bound_ctrl:1
	s_nop 1
	v_add_f32_dpp v3, v3, v3 row_shr:4 row_mask:0xf bank_mask:0xf bound_ctrl:1
	s_nop 1
	v_add_f32_dpp v3, v3, v3 row_shr:8 row_mask:0xf bank_mask:0xf bound_ctrl:1
	s_nop 1
	v_mov_b32_dpp v4, v3 row_bcast:15 row_mask:0xa bank_mask:0xf
	v_add_f32_e32 v3, v3, v4
	v_mov_b32_e32 v4, v1
	s_nop 1
	v_mov_b32_dpp v4, v3 row_bcast:31 row_mask:0xc bank_mask:0xf
	v_add_f32_e32 v3, v3, v4
	s_nop 0
	v_readlane_b32 s3, v3, 63
	s_and_saveexec_b64 s[0:1], vcc
	v_add_u32_e32 v3, 0xf8e0, v2
	v_mov_b32_e32 v4, s2
	v_mov_b32_e32 v5, s3
	ds_write2_b32 v3, v4, v5 offset1:1
	s_or_b64 exec, exec, s[0:1]
	v_add_f32_e32 v3, v16, v17
	v_mov_b32_e32 v4, v1
	s_nop 0
	v_add_f32_dpp v3, v3, v3 row_shr:1 row_mask:0xf bank_mask:0xf bound_ctrl:1
	s_nop 1
	v_add_f32_dpp v3, v3, v3 row_shr:2 row_mask:0xf bank_mask:0xf bound_ctrl:1
	s_nop 1
	v_add_f32_dpp v3, v3, v3 row_shr:4 row_mask:0xf bank_mask:0xf bound_ctrl:1
	s_nop 1
	v_add_f32_dpp v3, v3, v3 row_shr:8 row_mask:0xf bank_mask:0xf bound_ctrl:1
	s_nop 1
	v_mov_b32_dpp v4, v3 row_bcast:15 row_mask:0xa bank_mask:0xf
	v_add_f32_e32 v3, v3, v4
	v_mov_b32_e32 v4, v1
	s_nop 1
	v_mov_b32_dpp v4, v3 row_bcast:31 row_mask:0xc bank_mask:0xf
	v_add_f32_e32 v3, v3, v4
	v_mov_b32_e32 v4, v1
	v_readlane_b32 s2, v3, 63
	v_mul_f32_e32 v3, v17, v17
	v_fmac_f32_e32 v3, v16, v16
	s_nop 1
	v_add_f32_dpp v3, v3, v3 row_shr:1 row_mask:0xf bank_mask:0xf bound_ctrl:1
	s_nop 1
	v_add_f32_dpp v3, v3, v3 row_shr:2 row_mask:0xf bank_mask:0xf bound_ctrl:1
	s_nop 1
	v_add_f32_dpp v3, v3, v3 row_shr:4 row_mask:0xf bank_mask:0xf bound_ctrl:1
	s_nop 1
	v_add_f32_dpp v3, v3, v3 row_shr:8 row_mask:0xf bank_mask:0xf bound_ctrl:1
	s_nop 1
	v_mov_b32_dpp v4, v3 row_bcast:15 row_mask:0xa bank_mask:0xf
	v_add_f32_e32 v3, v3, v4
	v_mov_b32_e32 v4, v1
	s_nop 1
	v_mov_b32_dpp v4, v3 row_bcast:31 row_mask:0xc bank_mask:0xf
	v_add_f32_e32 v3, v3, v4
	s_nop 0
	v_readlane_b32 s3, v3, 63
	s_and_saveexec_b64 s[0:1], vcc
	v_add_u32_e32 v3, 0xf8e8, v2
	v_mov_b32_e32 v4, s2
	v_mov_b32_e32 v5, s3
	ds_write2_b32 v3, v4, v5 offset1:1
	s_or_b64 exec, exec, s[0:1]
	v_add_f32_e32 v3, v14, v15
	v_mov_b32_e32 v4, v1
	s_nop 0
	v_add_f32_dpp v3, v3, v3 row_shr:1 row_mask:0xf bank_mask:0xf bound_ctrl:1
	s_nop 1
	v_add_f32_dpp v3, v3, v3 row_shr:2 row_mask:0xf bank_mask:0xf bound_ctrl:1
	s_nop 1
	v_add_f32_dpp v3, v3, v3 row_shr:4 row_mask:0xf bank_mask:0xf bound_ctrl:1
	s_nop 1
	v_add_f32_dpp v3, v3, v3 row_shr:8 row_mask:0xf bank_mask:0xf bound_ctrl:1
	s_nop 1
	v_mov_b32_dpp v4, v3 row_bcast:15 row_mask:0xa bank_mask:0xf
	v_add_f32_e32 v3, v3, v4
	v_mov_b32_e32 v4, v1
	s_nop 1
	v_mov_b32_dpp v4, v3 row_bcast:31 row_mask:0xc bank_mask:0xf
	v_add_f32_e32 v3, v3, v4
	v_mov_b32_e32 v4, v1
	v_readlane_b32 s2, v3, 63
	v_mul_f32_e32 v3, v15, v15
	v_fmac_f32_e32 v3, v14, v14
	s_nop 1
	v_add_f32_dpp v3, v3, v3 row_shr:1 row_mask:0xf bank_mask:0xf bound_ctrl:1
	s_nop 1
	v_add_f32_dpp v3, v3, v3 row_shr:2 row_mask:0xf bank_mask:0xf bound_ctrl:1
	s_nop 1
	v_add_f32_dpp v3, v3, v3 row_shr:4 row_mask:0xf bank_mask:0xf bound_ctrl:1
	s_nop 1
	v_add_f32_dpp v3, v3, v3 row_shr:8 row_mask:0xf bank_mask:0xf bound_ctrl:1
	s_nop 1
	v_mov_b32_dpp v4, v3 row_bcast:15 row_mask:0xa bank_mask:0xf
	v_add_f32_e32 v3, v3, v4
	v_mov_b32_e32 v4, v1
	s_nop 1
	v_mov_b32_dpp v4, v3 row_bcast:31 row_mask:0xc bank_mask:0xf
	v_add_f32_e32 v3, v3, v4
	s_nop 0
	v_readlane_b32 s3, v3, 63
	s_and_saveexec_b64 s[0:1], vcc
	v_add_u32_e32 v3, 0xf8f0, v2
	v_mov_b32_e32 v4, s2
	v_mov_b32_e32 v5, s3
	ds_write2_b32 v3, v4, v5 offset1:1
	s_or_b64 exec, exec, s[0:1]
	v_add_f32_e32 v3, v12, v13
	v_mov_b32_e32 v4, v1
	s_nop 0
	v_add_f32_dpp v3, v3, v3 row_shr:1 row_mask:0xf bank_mask:0xf bound_ctrl:1
	s_nop 1
	v_add_f32_dpp v3, v3, v3 row_shr:2 row_mask:0xf bank_mask:0xf bound_ctrl:1
	s_nop 1
	v_add_f32_dpp v3, v3, v3 row_shr:4 row_mask:0xf bank_mask:0xf bound_ctrl:1
	s_nop 1
	v_add_f32_dpp v3, v3, v3 row_shr:8 row_mask:0xf bank_mask:0xf bound_ctrl:1
	s_nop 1
	v_mov_b32_dpp v4, v3 row_bcast:15 row_mask:0xa bank_mask:0xf
	v_add_f32_e32 v3, v3, v4
	v_mov_b32_e32 v4, v1
	s_nop 1
	v_mov_b32_dpp v4, v3 row_bcast:31 row_mask:0xc bank_mask:0xf
	v_add_f32_e32 v3, v3, v4
	v_mov_b32_e32 v4, v1
	v_readlane_b32 s2, v3, 63
	v_mul_f32_e32 v3, v13, v13
	v_fmac_f32_e32 v3, v12, v12
	s_nop 1
	v_add_f32_dpp v3, v3, v3 row_shr:1 row_mask:0xf bank_mask:0xf bound_ctrl:1
	s_nop 1
	v_add_f32_dpp v3, v3, v3 row_shr:2 row_mask:0xf bank_mask:0xf bound_ctrl:1
	s_nop 1
	v_add_f32_dpp v3, v3, v3 row_shr:4 row_mask:0xf bank_mask:0xf bound_ctrl:1
	s_nop 1
	v_add_f32_dpp v3, v3, v3 row_shr:8 row_mask:0xf bank_mask:0xf bound_ctrl:1
	s_nop 1
	v_mov_b32_dpp v4, v3 row_bcast:15 row_mask:0xa bank_mask:0xf
	v_add_f32_e32 v3, v3, v4
	v_mov_b32_e32 v4, v1
	s_nop 1
	v_mov_b32_dpp v4, v3 row_bcast:31 row_mask:0xc bank_mask:0xf
	v_add_f32_e32 v3, v3, v4
	s_nop 0
	v_readlane_b32 s3, v3, 63
	s_and_saveexec_b64 s[0:1], vcc
	v_add_u32_e32 v2, 0xf8f8, v2
	v_mov_b32_e32 v3, s2
	v_mov_b32_e32 v4, s3
	ds_write2_b32 v2, v3, v4 offset1:1
	s_or_b64 exec, exec, s[0:1]
	v_readlane_b32 s0, v255, 21
	v_lshlrev_b32_e32 v2, 2, v0
	v_readlane_b32 s1, v255, 22
	s_waitcnt lgkmcnt(0)
	s_barrier
	v_lshlrev_b32_e32 v0, 1, v0
	v_ashrrev_i32_e32 v11, 31, v10
	s_nop 0
	global_load_dwordx2 v[34:35], v2, s[0:1]
	v_readlane_b32 s0, v255, 23
	v_readlane_b32 s1, v255, 24
	s_nop 4
	global_load_dwordx2 v[36:37], v2, s[0:1]
	ds_read_b128 v[84:87], v82 offset:63488
	ds_read_b128 v[6:9], v82 offset:63504
	ds_read_b128 v[2:5], v82 offset:63520
	ds_read_b128 v[88:91], v82 offset:63744
	ds_read_b128 v[92:95], v82 offset:64000
	ds_read_b128 v[96:99], v82 offset:64256
	s_waitcnt lgkmcnt(5)
	v_pk_add_f32 v[84:85], v[84:85], 0 op_sel_hi:[1,0]
	v_pk_add_f32 v[86:87], v[86:87], 0 op_sel_hi:[1,0]
	s_waitcnt lgkmcnt(2)
	v_pk_add_f32 v[84:85], v[84:85], v[88:89]
	v_pk_add_f32 v[86:87], v[86:87], v[90:91]
	s_waitcnt lgkmcnt(1)
	v_pk_add_f32 v[84:85], v[84:85], v[92:93]
	v_pk_add_f32 v[86:87], v[86:87], v[94:95]
	s_waitcnt lgkmcnt(0)
	v_pk_add_f32 v[84:85], v[84:85], v[96:97]
	v_pk_add_f32 v[86:87], v[86:87], v[98:99]
	v_pk_mul_f32 v[84:85], v[84:85], s[68:69] op_sel_hi:[1,0]
	v_pk_mul_f32 v[86:87], v[86:87], s[68:69] op_sel_hi:[1,0]
	v_pk_add_f32 v[80:81], v[80:81], v[84:85] op_sel_hi:[1,0] neg_lo:[0,1] neg_hi:[0,1]
	v_mov_b32_e32 v90, v86
	v_mov_b32_e32 v91, v84
	v_mov_b32_e32 v84, v87
	v_readlane_b32 s0, v254, 45
	v_pk_fma_f32 v[84:85], v[90:91], v[90:91], v[84:85] neg_lo:[1,0,0] neg_hi:[1,0,0]
	v_readlane_b32 s1, v254, 46
	v_pk_add_f32 v[84:85], v[84:85], s[86:87] op_sel_hi:[1,0]
	v_lshlrev_b64 v[88:89], 10, v[10:11]
	v_lshl_add_u64 v[32:33], s[0:1], 0, v[0:1]
	v_mul_f32_e32 v0, 0x4b800000, v85
	v_cmp_gt_f32_e64 s[0:1], s40, v85
	v_lshl_add_u64 v[88:89], v[32:33], 0, v[88:89]
	v_cmp_gt_f32_e32 vcc, s40, v84
	v_cndmask_b32_e64 v0, v85, v0, s[0:1]
	v_rsq_f32_e32 v0, v0
	v_pk_add_f32 v[78:79], v[78:79], v[86:87] op_sel_hi:[1,0] neg_lo:[0,1] neg_hi:[0,1]
	v_pk_add_f32 v[6:7], v[6:7], 0 op_sel_hi:[1,0]
	v_pk_add_f32 v[8:9], v[8:9], 0 op_sel_hi:[1,0]
	v_mul_f32_e32 v11, 0x45800000, v0
	v_cndmask_b32_e64 v0, v0, v11, s[0:1]
	v_pk_mul_f32 v[80:81], v[80:81], v[0:1] op_sel_hi:[1,0]
	v_pk_add_f32 v[2:3], v[2:3], 0 op_sel_hi:[1,0]
	v_pk_add_f32 v[4:5], v[4:5], 0 op_sel_hi:[1,0]
	s_waitcnt vmcnt(0)
	v_pk_fma_f32 v[80:81], v[34:35], v[80:81], v[36:37]
	s_nop 0
	v_mul_f32_e32 v0, 0xbfb8aa3b, v80
	v_exp_f32_e32 v0, v0
	s_nop 0
	v_add_f32_e32 v0, 1.0, v0
	v_rcp_f32_e32 v90, v0
	v_mul_f32_e32 v0, 0xbfb8aa3b, v81
	v_exp_f32_e32 v0, v0
	s_nop 0
	v_add_f32_e32 v0, 1.0, v0
	v_rcp_f32_e32 v91, v0
	s_nop 0
	v_pk_mul_f32 v[80:81], v[80:81], v[90:91]
	s_nop 0
	v_cvt_pk_bf16_f32 v0, v80, v81
	global_store_dword v[88:89], v0, off
	v_mul_f32_e32 v0, 0x4b800000, v84
	v_cndmask_b32_e32 v0, v84, v0, vcc
	v_rsq_f32_e32 v0, v0
	ds_read_b128 v[88:91], v82 offset:64272
	ds_read_b128 v[84:87], v82 offset:64016
	v_mul_f32_e32 v11, 0x45800000, v0
	v_cndmask_b32_e32 v0, v0, v11, vcc
	v_pk_mul_f32 v[78:79], v[78:79], v[0:1] op_sel_hi:[1,0]
	s_nop 0
	v_pk_fma_f32 v[78:79], v[34:35], v[78:79], v[36:37]
	s_nop 0
	v_mul_f32_e32 v0, 0xbfb8aa3b, v78
	v_exp_f32_e32 v0, v0
	s_nop 0
	v_add_f32_e32 v0, 1.0, v0
	v_rcp_f32_e32 v80, v0
	v_mul_f32_e32 v0, 0xbfb8aa3b, v79
	v_exp_f32_e32 v0, v0
	s_nop 0
	v_add_f32_e32 v0, 1.0, v0
	v_rcp_f32_e32 v81, v0
	s_nop 0
	v_pk_mul_f32 v[78:79], v[78:79], v[80:81]
	s_nop 0
	v_cvt_pk_bf16_f32 v0, v78, v79
	v_or_b32_e32 v78, 1, v10
	v_ashrrev_i32_e32 v79, 31, v78
	v_lshlrev_b64 v[78:79], 10, v[78:79]
	v_lshl_add_u64 v[78:79], v[32:33], 0, v[78:79]
	global_store_dword v[78:79], v0, off
	ds_read_b128 v[78:81], v82 offset:63760
	s_waitcnt lgkmcnt(0)
	v_pk_add_f32 v[6:7], v[6:7], v[78:79]
	v_pk_add_f32 v[8:9], v[8:9], v[80:81]
	v_pk_add_f32 v[6:7], v[6:7], v[84:85]
	v_pk_add_f32 v[8:9], v[8:9], v[86:87]
	v_pk_add_f32 v[6:7], v[6:7], v[88:89]
	v_pk_add_f32 v[8:9], v[8:9], v[90:91]
	v_pk_mul_f32 v[78:79], v[6:7], s[68:69] op_sel_hi:[1,0]
	v_pk_mul_f32 v[8:9], v[8:9], s[68:69] op_sel_hi:[1,0]
	v_pk_add_f32 v[6:7], v[76:77], v[78:79] op_sel_hi:[1,0] neg_lo:[0,1] neg_hi:[0,1]
	v_mov_b32_e32 v80, v8
	v_mov_b32_e32 v81, v78
	v_mov_b32_e32 v78, v9
	v_pk_fma_f32 v[78:79], v[80:81], v[80:81], v[78:79] neg_lo:[1,0,0] neg_hi:[1,0,0]
	v_or_b32_e32 v76, 2, v10
	v_pk_add_f32 v[78:79], v[78:79], s[86:87] op_sel_hi:[1,0]
	v_ashrrev_i32_e32 v77, 31, v76
	v_mul_f32_e32 v0, 0x4b800000, v79
	v_cmp_gt_f32_e64 s[0:1], s40, v79
	v_lshlrev_b64 v[76:77], 10, v[76:77]
	v_lshl_add_u64 v[76:77], v[32:33], 0, v[76:77]
	v_cndmask_b32_e64 v0, v79, v0, s[0:1]
	v_rsq_f32_e32 v0, v0
	v_cmp_gt_f32_e32 vcc, s40, v78
	v_mul_f32_e32 v11, 0x45800000, v0
	v_cndmask_b32_e64 v0, v0, v11, s[0:1]
	v_pk_mul_f32 v[6:7], v[6:7], v[0:1] op_sel_hi:[1,0]
	s_nop 0
	v_pk_fma_f32 v[6:7], v[34:35], v[6:7], v[36:37]
	s_nop 0
	v_mul_f32_e32 v0, 0xbfb8aa3b, v6
	v_exp_f32_e32 v0, v0
	s_nop 0
	v_add_f32_e32 v0, 1.0, v0
	v_rcp_f32_e32 v80, v0
	v_mul_f32_e32 v0, 0xbfb8aa3b, v7
	v_exp_f32_e32 v0, v0
	s_nop 0
	v_add_f32_e32 v0, 1.0, v0
	v_rcp_f32_e32 v81, v0
	s_nop 0
	v_pk_mul_f32 v[6:7], v[6:7], v[80:81]
	s_nop 0
	v_cvt_pk_bf16_f32 v0, v6, v7
	global_store_dword v[76:77], v0, off
	v_mul_f32_e32 v0, 0x4b800000, v78
	v_cndmask_b32_e32 v0, v78, v0, vcc
	v_rsq_f32_e32 v0, v0
	ds_read_b128 v[78:81], v82 offset:64288
	v_mul_f32_e32 v6, 0x45800000, v0
	v_cndmask_b32_e32 v0, v0, v6, vcc
	v_pk_add_f32 v[6:7], v[74:75], v[8:9] op_sel_hi:[1,0] neg_lo:[0,1] neg_hi:[0,1]
	ds_read_b128 v[74:77], v82 offset:64032
	v_pk_mul_f32 v[6:7], v[6:7], v[0:1] op_sel_hi:[1,0]
	s_nop 0
	v_pk_fma_f32 v[6:7], v[34:35], v[6:7], v[36:37]
	s_nop 0
	v_mul_f32_e32 v0, 0xbfb8aa3b, v6
	v_exp_f32_e32 v0, v0
	s_nop 0
	v_add_f32_e32 v0, 1.0, v0
	v_rcp_f32_e32 v8, v0
	v_mul_f32_e32 v0, 0xbfb8aa3b, v7
	v_exp_f32_e32 v0, v0
	s_nop 0
	v_add_f32_e32 v0, 1.0, v0
	v_rcp_f32_e32 v9, v0
	s_nop 0
	v_pk_mul_f32 v[6:7], v[6:7], v[8:9]
	s_nop 0
	v_cvt_pk_bf16_f32 v0, v6, v7
	v_or_b32_e32 v6, 3, v10
	v_ashrrev_i32_e32 v7, 31, v6
	v_lshlrev_b64 v[6:7], 10, v[6:7]
	v_lshl_add_u64 v[6:7], v[32:33], 0, v[6:7]
	global_store_dword v[6:7], v0, off
	ds_read_b128 v[6:9], v82 offset:63776
	s_waitcnt lgkmcnt(0)
	v_pk_add_f32 v[2:3], v[2:3], v[6:7]
	v_pk_add_f32 v[4:5], v[4:5], v[8:9]
	v_pk_add_f32 v[2:3], v[2:3], v[74:75]
	v_pk_add_f32 v[4:5], v[4:5], v[76:77]
	v_pk_add_f32 v[2:3], v[2:3], v[78:79]
	v_pk_add_f32 v[4:5], v[4:5], v[80:81]
	v_pk_mul_f32 v[2:3], v[2:3], s[68:69] op_sel_hi:[1,0]
	v_pk_mul_f32 v[4:5], v[4:5], s[68:69] op_sel_hi:[1,0]
	v_pk_add_f32 v[6:7], v[72:73], v[2:3] op_sel_hi:[1,0] neg_lo:[0,1] neg_hi:[0,1]
	v_mov_b32_e32 v8, v4
	v_mov_b32_e32 v9, v2
	v_mov_b32_e32 v2, v5
	v_pk_fma_f32 v[2:3], v[8:9], v[8:9], v[2:3] neg_lo:[1,0,0] neg_hi:[1,0,0]
	v_or_b32_e32 v72, 4, v10
	v_pk_add_f32 v[2:3], v[2:3], s[86:87] op_sel_hi:[1,0]
	v_ashrrev_i32_e32 v73, 31, v72
	v_mul_f32_e32 v0, 0x4b800000, v3
	v_cmp_gt_f32_e64 s[0:1], s40, v3
	v_lshlrev_b64 v[72:73], 10, v[72:73]
	v_lshl_add_u64 v[72:73], v[32:33], 0, v[72:73]
	v_cndmask_b32_e64 v0, v3, v0, s[0:1]
	v_rsq_f32_e32 v0, v0
	v_cmp_gt_f32_e32 vcc, s40, v2
	ds_read_b128 v[74:77], v82 offset:64304
	v_mul_f32_e32 v3, 0x45800000, v0
	v_cndmask_b32_e64 v0, v0, v3, s[0:1]
	v_pk_mul_f32 v[6:7], v[6:7], v[0:1] op_sel_hi:[1,0]
	s_nop 0
	v_pk_fma_f32 v[6:7], v[34:35], v[6:7], v[36:37]
	s_nop 0
	v_mul_f32_e32 v0, 0xbfb8aa3b, v6
	v_exp_f32_e32 v0, v0
	s_nop 0
	v_add_f32_e32 v0, 1.0, v0
	v_rcp_f32_e32 v8, v0
	v_mul_f32_e32 v0, 0xbfb8aa3b, v7
	v_exp_f32_e32 v0, v0
	s_nop 0
	v_add_f32_e32 v0, 1.0, v0
	v_rcp_f32_e32 v9, v0
	s_nop 0
	v_pk_mul_f32 v[6:7], v[6:7], v[8:9]
	s_nop 0
	v_cvt_pk_bf16_f32 v0, v6, v7
	global_store_dword v[72:73], v0, off
	v_mul_f32_e32 v0, 0x4b800000, v2
	v_cndmask_b32_e32 v0, v2, v0, vcc
	v_rsq_f32_e32 v0, v0
	ds_read_b128 v[6:9], v82 offset:63792
	v_mul_f32_e32 v2, 0x45800000, v0
	v_cndmask_b32_e32 v0, v0, v2, vcc
	v_pk_add_f32 v[2:3], v[70:71], v[4:5] op_sel_hi:[1,0] neg_lo:[0,1] neg_hi:[0,1]
	ds_read_b128 v[70:73], v82 offset:64048
	v_pk_mul_f32 v[2:3], v[2:3], v[0:1] op_sel_hi:[1,0]
	s_nop 0
	v_pk_fma_f32 v[2:3], v[34:35], v[2:3], v[36:37]
	s_nop 0
	v_mul_f32_e32 v0, 0xbfb8aa3b, v2
	v_exp_f32_e32 v0, v0
	s_nop 0
	v_add_f32_e32 v0, 1.0, v0
	v_rcp_f32_e32 v4, v0
	v_mul_f32_e32 v0, 0xbfb8aa3b, v3
	v_exp_f32_e32 v0, v0
	s_nop 0
	v_add_f32_e32 v0, 1.0, v0
	v_rcp_f32_e32 v5, v0
	s_nop 0
	v_pk_mul_f32 v[2:3], v[2:3], v[4:5]
	s_nop 0
	v_cvt_pk_bf16_f32 v0, v2, v3
	v_or_b32_e32 v2, 5, v10
	v_ashrrev_i32_e32 v3, 31, v2
	v_lshlrev_b64 v[2:3], 10, v[2:3]
	v_lshl_add_u64 v[2:3], v[32:33], 0, v[2:3]
	global_store_dword v[2:3], v0, off
	ds_read_b128 v[2:5], v82 offset:63536
	s_waitcnt lgkmcnt(0)
	v_pk_add_f32 v[2:3], v[2:3], 0 op_sel_hi:[1,0]
	v_pk_add_f32 v[4:5], v[4:5], 0 op_sel_hi:[1,0]
	v_pk_add_f32 v[2:3], v[2:3], v[6:7]
	v_pk_add_f32 v[4:5], v[4:5], v[8:9]
	v_pk_add_f32 v[2:3], v[2:3], v[70:71]
	v_pk_add_f32 v[4:5], v[4:5], v[72:73]
	v_pk_add_f32 v[2:3], v[2:3], v[74:75]
	v_pk_add_f32 v[4:5], v[4:5], v[76:77]
	v_pk_mul_f32 v[2:3], v[2:3], s[68:69] op_sel_hi:[1,0]
	v_pk_mul_f32 v[4:5], v[4:5], s[68:69] op_sel_hi:[1,0]
	v_pk_add_f32 v[6:7], v[68:69], v[2:3] op_sel_hi:[1,0] neg_lo:[0,1] neg_hi:[0,1]
	v_mov_b32_e32 v8, v4
	v_mov_b32_e32 v9, v2
	v_mov_b32_e32 v2, v5
	v_pk_fma_f32 v[2:3], v[8:9], v[8:9], v[2:3] neg_lo:[1,0,0] neg_hi:[1,0,0]
	v_or_b32_e32 v68, 6, v10
	v_pk_add_f32 v[2:3], v[2:3], s[86:87] op_sel_hi:[1,0]
	v_ashrrev_i32_e32 v69, 31, v68
	v_mul_f32_e32 v0, 0x4b800000, v3
	v_cmp_gt_f32_e64 s[0:1], s40, v3
	v_lshlrev_b64 v[68:69], 10, v[68:69]
	v_lshl_add_u64 v[68:69], v[32:33], 0, v[68:69]
	v_cndmask_b32_e64 v0, v3, v0, s[0:1]
	v_rsq_f32_e32 v0, v0
	v_cmp_gt_f32_e32 vcc, s40, v2
	ds_read_b128 v[70:73], v82 offset:64320
	v_mul_f32_e32 v3, 0x45800000, v0
	v_cndmask_b32_e64 v0, v0, v3, s[0:1]
	v_pk_mul_f32 v[6:7], v[6:7], v[0:1] op_sel_hi:[1,0]
	s_nop 0
	v_pk_fma_f32 v[6:7], v[34:35], v[6:7], v[36:37]
	s_nop 0
	v_mul_f32_e32 v0, 0xbfb8aa3b, v6
	v_exp_f32_e32 v0, v0
	s_nop 0
	v_add_f32_e32 v0, 1.0, v0
	v_rcp_f32_e32 v8, v0
	v_mul_f32_e32 v0, 0xbfb8aa3b, v7
	v_exp_f32_e32 v0, v0
	s_nop 0
	v_add_f32_e32 v0, 1.0, v0
	v_rcp_f32_e32 v9, v0
	s_nop 0
	v_pk_mul_f32 v[6:7], v[6:7], v[8:9]
	s_nop 0
	v_cvt_pk_bf16_f32 v0, v6, v7
	global_store_dword v[68:69], v0, off
	v_mul_f32_e32 v0, 0x4b800000, v2
	v_cndmask_b32_e32 v0, v2, v0, vcc
	v_rsq_f32_e32 v0, v0
	ds_read_b128 v[6:9], v82 offset:63808
	v_mul_f32_e32 v2, 0x45800000, v0
	v_cndmask_b32_e32 v0, v0, v2, vcc
	v_pk_add_f32 v[2:3], v[66:67], v[4:5] op_sel_hi:[1,0] neg_lo:[0,1] neg_hi:[0,1]
	ds_read_b128 v[66:69], v82 offset:64064
	v_pk_mul_f32 v[2:3], v[2:3], v[0:1] op_sel_hi:[1,0]
	s_nop 0
	v_pk_fma_f32 v[2:3], v[34:35], v[2:3], v[36:37]
	s_nop 0
	v_mul_f32_e32 v0, 0xbfb8aa3b, v2
	v_exp_f32_e32 v0, v0
	s_nop 0
	v_add_f32_e32 v0, 1.0, v0
	v_rcp_f32_e32 v4, v0
	v_mul_f32_e32 v0, 0xbfb8aa3b, v3
	v_exp_f32_e32 v0, v0
	s_nop 0
	v_add_f32_e32 v0, 1.0, v0
	v_rcp_f32_e32 v5, v0
	s_nop 0
	v_pk_mul_f32 v[2:3], v[2:3], v[4:5]
	s_nop 0
	v_cvt_pk_bf16_f32 v0, v2, v3
	v_or_b32_e32 v2, 7, v10
	v_ashrrev_i32_e32 v3, 31, v2
	v_lshlrev_b64 v[2:3], 10, v[2:3]
	v_lshl_add_u64 v[2:3], v[32:33], 0, v[2:3]
	global_store_dword v[2:3], v0, off
	ds_read_b128 v[2:5], v82 offset:63552
	s_waitcnt lgkmcnt(0)
	v_pk_add_f32 v[2:3], v[2:3], 0 op_sel_hi:[1,0]
	v_pk_add_f32 v[4:5], v[4:5], 0 op_sel_hi:[1,0]
	v_pk_add_f32 v[2:3], v[2:3], v[6:7]
	v_pk_add_f32 v[4:5], v[4:5], v[8:9]
	v_pk_add_f32 v[2:3], v[2:3], v[66:67]
	v_pk_add_f32 v[4:5], v[4:5], v[68:69]
	v_pk_add_f32 v[2:3], v[2:3], v[70:71]
	v_pk_add_f32 v[4:5], v[4:5], v[72:73]
	v_pk_mul_f32 v[2:3], v[2:3], s[68:69] op_sel_hi:[1,0]
	v_pk_mul_f32 v[4:5], v[4:5], s[68:69] op_sel_hi:[1,0]
	v_pk_add_f32 v[6:7], v[64:65], v[2:3] op_sel_hi:[1,0] neg_lo:[0,1] neg_hi:[0,1]
	v_mov_b32_e32 v8, v4
	v_mov_b32_e32 v9, v2
	v_mov_b32_e32 v2, v5
	v_pk_fma_f32 v[2:3], v[8:9], v[8:9], v[2:3] neg_lo:[1,0,0] neg_hi:[1,0,0]
	v_or_b32_e32 v64, 8, v10
	v_pk_add_f32 v[2:3], v[2:3], s[86:87] op_sel_hi:[1,0]
	v_ashrrev_i32_e32 v65, 31, v64
	v_mul_f32_e32 v0, 0x4b800000, v3
	v_cmp_gt_f32_e64 s[0:1], s40, v3
	v_lshlrev_b64 v[64:65], 10, v[64:65]
	v_lshl_add_u64 v[64:65], v[32:33], 0, v[64:65]
	v_cndmask_b32_e64 v0, v3, v0, s[0:1]
	v_rsq_f32_e32 v0, v0
	v_cmp_gt_f32_e32 vcc, s40, v2
	ds_read_b128 v[66:69], v82 offset:64336
	v_mul_f32_e32 v3, 0x45800000, v0
	v_cndmask_b32_e64 v0, v0, v3, s[0:1]
	v_pk_mul_f32 v[6:7], v[6:7], v[0:1] op_sel_hi:[1,0]
	s_nop 0
	v_pk_fma_f32 v[6:7], v[34:35], v[6:7], v[36:37]
	s_nop 0
	v_mul_f32_e32 v0, 0xbfb8aa3b, v6
	v_exp_f32_e32 v0, v0
	s_nop 0
	v_add_f32_e32 v0, 1.0, v0
	v_rcp_f32_e32 v8, v0
	v_mul_f32_e32 v0, 0xbfb8aa3b, v7
	v_exp_f32_e32 v0, v0
	s_nop 0
	v_add_f32_e32 v0, 1.0, v0
	v_rcp_f32_e32 v9, v0
	s_nop 0
	v_pk_mul_f32 v[6:7], v[6:7], v[8:9]
	s_nop 0
	v_cvt_pk_bf16_f32 v0, v6, v7
	global_store_dword v[64:65], v0, off
	v_mul_f32_e32 v0, 0x4b800000, v2
	v_cndmask_b32_e32 v0, v2, v0, vcc
	v_rsq_f32_e32 v0, v0
	ds_read_b128 v[6:9], v82 offset:63824
	v_mul_f32_e32 v2, 0x45800000, v0
	v_cndmask_b32_e32 v0, v0, v2, vcc
	v_pk_add_f32 v[2:3], v[62:63], v[4:5] op_sel_hi:[1,0] neg_lo:[0,1] neg_hi:[0,1]
	ds_read_b128 v[62:65], v82 offset:64080
	v_pk_mul_f32 v[2:3], v[2:3], v[0:1] op_sel_hi:[1,0]
	s_nop 0
	v_pk_fma_f32 v[2:3], v[34:35], v[2:3], v[36:37]
	s_nop 0
	v_mul_f32_e32 v0, 0xbfb8aa3b, v2
	v_exp_f32_e32 v0, v0
	s_nop 0
	v_add_f32_e32 v0, 1.0, v0
	v_rcp_f32_e32 v4, v0
	v_mul_f32_e32 v0, 0xbfb8aa3b, v3
	v_exp_f32_e32 v0, v0
	s_nop 0
	v_add_f32_e32 v0, 1.0, v0
	v_rcp_f32_e32 v5, v0
	s_nop 0
	v_pk_mul_f32 v[2:3], v[2:3], v[4:5]
	s_nop 0
	v_cvt_pk_bf16_f32 v0, v2, v3
	v_or_b32_e32 v2, 9, v10
	v_ashrrev_i32_e32 v3, 31, v2
	v_lshlrev_b64 v[2:3], 10, v[2:3]
	v_lshl_add_u64 v[2:3], v[32:33], 0, v[2:3]
	global_store_dword v[2:3], v0, off
	ds_read_b128 v[2:5], v82 offset:63568
	s_waitcnt lgkmcnt(0)
	v_pk_add_f32 v[2:3], v[2:3], 0 op_sel_hi:[1,0]
	v_pk_add_f32 v[4:5], v[4:5], 0 op_sel_hi:[1,0]
	v_pk_add_f32 v[2:3], v[2:3], v[6:7]
	v_pk_add_f32 v[4:5], v[4:5], v[8:9]
	v_pk_add_f32 v[2:3], v[2:3], v[62:63]
	v_pk_add_f32 v[4:5], v[4:5], v[64:65]
	v_pk_add_f32 v[2:3], v[2:3], v[66:67]
	v_pk_add_f32 v[4:5], v[4:5], v[68:69]
	v_pk_mul_f32 v[2:3], v[2:3], s[68:69] op_sel_hi:[1,0]
	v_pk_mul_f32 v[4:5], v[4:5], s[68:69] op_sel_hi:[1,0]
	v_pk_add_f32 v[6:7], v[60:61], v[2:3] op_sel_hi:[1,0] neg_lo:[0,1] neg_hi:[0,1]
	v_mov_b32_e32 v8, v4
	v_mov_b32_e32 v9, v2
	v_mov_b32_e32 v2, v5
	v_pk_fma_f32 v[2:3], v[8:9], v[8:9], v[2:3] neg_lo:[1,0,0] neg_hi:[1,0,0]
	v_or_b32_e32 v60, 10, v10
	v_pk_add_f32 v[2:3], v[2:3], s[86:87] op_sel_hi:[1,0]
	v_ashrrev_i32_e32 v61, 31, v60
	v_mul_f32_e32 v0, 0x4b800000, v3
	v_cmp_gt_f32_e64 s[0:1], s40, v3
	v_lshlrev_b64 v[60:61], 10, v[60:61]
	v_lshl_add_u64 v[60:61], v[32:33], 0, v[60:61]
	v_cndmask_b32_e64 v0, v3, v0, s[0:1]
	v_rsq_f32_e32 v0, v0
	v_cmp_gt_f32_e32 vcc, s40, v2
	ds_read_b128 v[62:65], v82 offset:64352
	v_mul_f32_e32 v3, 0x45800000, v0
	v_cndmask_b32_e64 v0, v0, v3, s[0:1]
	v_pk_mul_f32 v[6:7], v[6:7], v[0:1] op_sel_hi:[1,0]
	s_nop 0
	v_pk_fma_f32 v[6:7], v[34:35], v[6:7], v[36:37]
	s_nop 0
	v_mul_f32_e32 v0, 0xbfb8aa3b, v6
	v_exp_f32_e32 v0, v0
	s_nop 0
	v_add_f32_e32 v0, 1.0, v0
	v_rcp_f32_e32 v8, v0
	v_mul_f32_e32 v0, 0xbfb8aa3b, v7
	v_exp_f32_e32 v0, v0
	s_nop 0
	v_add_f32_e32 v0, 1.0, v0
	v_rcp_f32_e32 v9, v0
	s_nop 0
	v_pk_mul_f32 v[6:7], v[6:7], v[8:9]
	s_nop 0
	v_cvt_pk_bf16_f32 v0, v6, v7
	global_store_dword v[60:61], v0, off
	v_mul_f32_e32 v0, 0x4b800000, v2
	v_cndmask_b32_e32 v0, v2, v0, vcc
	v_rsq_f32_e32 v0, v0
	ds_read_b128 v[6:9], v82 offset:63840
	v_mul_f32_e32 v2, 0x45800000, v0
	v_cndmask_b32_e32 v0, v0, v2, vcc
	v_pk_add_f32 v[2:3], v[58:59], v[4:5] op_sel_hi:[1,0] neg_lo:[0,1] neg_hi:[0,1]
	ds_read_b128 v[58:61], v82 offset:64096
	v_pk_mul_f32 v[2:3], v[2:3], v[0:1] op_sel_hi:[1,0]
	s_nop 0
	v_pk_fma_f32 v[2:3], v[34:35], v[2:3], v[36:37]
	s_nop 0
	v_mul_f32_e32 v0, 0xbfb8aa3b, v2
	v_exp_f32_e32 v0, v0
	s_nop 0
	v_add_f32_e32 v0, 1.0, v0
	v_rcp_f32_e32 v4, v0
	v_mul_f32_e32 v0, 0xbfb8aa3b, v3
	v_exp_f32_e32 v0, v0
	s_nop 0
	v_add_f32_e32 v0, 1.0, v0
	v_rcp_f32_e32 v5, v0
	s_nop 0
	v_pk_mul_f32 v[2:3], v[2:3], v[4:5]
	s_nop 0
	v_cvt_pk_bf16_f32 v0, v2, v3
	v_or_b32_e32 v2, 11, v10
	v_ashrrev_i32_e32 v3, 31, v2
	v_lshlrev_b64 v[2:3], 10, v[2:3]
	v_lshl_add_u64 v[2:3], v[32:33], 0, v[2:3]
	global_store_dword v[2:3], v0, off
	ds_read_b128 v[2:5], v82 offset:63584
	s_waitcnt lgkmcnt(0)
	v_pk_add_f32 v[2:3], v[2:3], 0 op_sel_hi:[1,0]
	v_pk_add_f32 v[4:5], v[4:5], 0 op_sel_hi:[1,0]
	v_pk_add_f32 v[2:3], v[2:3], v[6:7]
	v_pk_add_f32 v[4:5], v[4:5], v[8:9]
	v_pk_add_f32 v[2:3], v[2:3], v[58:59]
	v_pk_add_f32 v[4:5], v[4:5], v[60:61]
	v_pk_add_f32 v[2:3], v[2:3], v[62:63]
	v_pk_add_f32 v[4:5], v[4:5], v[64:65]
	v_pk_mul_f32 v[2:3], v[2:3], s[68:69] op_sel_hi:[1,0]
	v_pk_mul_f32 v[4:5], v[4:5], s[68:69] op_sel_hi:[1,0]
	v_pk_add_f32 v[6:7], v[56:57], v[2:3] op_sel_hi:[1,0] neg_lo:[0,1] neg_hi:[0,1]
	v_mov_b32_e32 v8, v4
	v_mov_b32_e32 v9, v2
	v_mov_b32_e32 v2, v5
	v_pk_fma_f32 v[2:3], v[8:9], v[8:9], v[2:3] neg_lo:[1,0,0] neg_hi:[1,0,0]
	v_or_b32_e32 v56, 12, v10
	v_pk_add_f32 v[2:3], v[2:3], s[86:87] op_sel_hi:[1,0]
	v_ashrrev_i32_e32 v57, 31, v56
	v_mul_f32_e32 v0, 0x4b800000, v3
	v_cmp_gt_f32_e64 s[0:1], s40, v3
	v_lshlrev_b64 v[56:57], 10, v[56:57]
	v_lshl_add_u64 v[56:57], v[32:33], 0, v[56:57]
	v_cndmask_b32_e64 v0, v3, v0, s[0:1]
	v_rsq_f32_e32 v0, v0
	v_cmp_gt_f32_e32 vcc, s40, v2
	ds_read_b128 v[58:61], v82 offset:64368
	v_mul_f32_e32 v3, 0x45800000, v0
	v_cndmask_b32_e64 v0, v0, v3, s[0:1]
	v_pk_mul_f32 v[6:7], v[6:7], v[0:1] op_sel_hi:[1,0]
	s_nop 0
	v_pk_fma_f32 v[6:7], v[34:35], v[6:7], v[36:37]
	s_nop 0
	v_mul_f32_e32 v0, 0xbfb8aa3b, v6
	v_exp_f32_e32 v0, v0
	s_nop 0
	v_add_f32_e32 v0, 1.0, v0
	v_rcp_f32_e32 v8, v0
	v_mul_f32_e32 v0, 0xbfb8aa3b, v7
	v_exp_f32_e32 v0, v0
	s_nop 0
	v_add_f32_e32 v0, 1.0, v0
	v_rcp_f32_e32 v9, v0
	s_nop 0
	v_pk_mul_f32 v[6:7], v[6:7], v[8:9]
	s_nop 0
	v_cvt_pk_bf16_f32 v0, v6, v7
	global_store_dword v[56:57], v0, off
	v_mul_f32_e32 v0, 0x4b800000, v2
	v_cndmask_b32_e32 v0, v2, v0, vcc
	v_rsq_f32_e32 v0, v0
	ds_read_b128 v[6:9], v82 offset:63856
	v_mul_f32_e32 v2, 0x45800000, v0
	v_cndmask_b32_e32 v0, v0, v2, vcc
	v_pk_add_f32 v[2:3], v[54:55], v[4:5] op_sel_hi:[1,0] neg_lo:[0,1] neg_hi:[0,1]
	ds_read_b128 v[54:57], v82 offset:64112
	v_pk_mul_f32 v[2:3], v[2:3], v[0:1] op_sel_hi:[1,0]
	s_nop 0
	v_pk_fma_f32 v[2:3], v[34:35], v[2:3], v[36:37]
	s_nop 0
	v_mul_f32_e32 v0, 0xbfb8aa3b, v2
	v_exp_f32_e32 v0, v0
	s_nop 0
	v_add_f32_e32 v0, 1.0, v0
	v_rcp_f32_e32 v4, v0
	v_mul_f32_e32 v0, 0xbfb8aa3b, v3
	v_exp_f32_e32 v0, v0
	s_nop 0
	v_add_f32_e32 v0, 1.0, v0
	v_rcp_f32_e32 v5, v0
	s_nop 0
	v_pk_mul_f32 v[2:3], v[2:3], v[4:5]
	s_nop 0
	v_cvt_pk_bf16_f32 v0, v2, v3
	v_or_b32_e32 v2, 13, v10
	v_ashrrev_i32_e32 v3, 31, v2
	v_lshlrev_b64 v[2:3], 10, v[2:3]
	v_lshl_add_u64 v[2:3], v[32:33], 0, v[2:3]
	global_store_dword v[2:3], v0, off
	ds_read_b128 v[2:5], v82 offset:63600
	s_waitcnt lgkmcnt(0)
	v_pk_add_f32 v[2:3], v[2:3], 0 op_sel_hi:[1,0]
	v_pk_add_f32 v[4:5], v[4:5], 0 op_sel_hi:[1,0]
	v_pk_add_f32 v[2:3], v[2:3], v[6:7]
	v_pk_add_f32 v[4:5], v[4:5], v[8:9]
	v_pk_add_f32 v[2:3], v[2:3], v[54:55]
	v_pk_add_f32 v[4:5], v[4:5], v[56:57]
	v_pk_add_f32 v[2:3], v[2:3], v[58:59]
	v_pk_add_f32 v[4:5], v[4:5], v[60:61]
	v_pk_mul_f32 v[2:3], v[2:3], s[68:69] op_sel_hi:[1,0]
	v_pk_mul_f32 v[4:5], v[4:5], s[68:69] op_sel_hi:[1,0]
	v_pk_add_f32 v[6:7], v[52:53], v[2:3] op_sel_hi:[1,0] neg_lo:[0,1] neg_hi:[0,1]
	v_mov_b32_e32 v8, v4
	v_mov_b32_e32 v9, v2
	v_mov_b32_e32 v2, v5
	v_pk_fma_f32 v[2:3], v[8:9], v[8:9], v[2:3] neg_lo:[1,0,0] neg_hi:[1,0,0]
	v_or_b32_e32 v52, 14, v10
	v_pk_add_f32 v[2:3], v[2:3], s[86:87] op_sel_hi:[1,0]
	v_ashrrev_i32_e32 v53, 31, v52
	v_mul_f32_e32 v0, 0x4b800000, v3
	v_cmp_gt_f32_e64 s[0:1], s40, v3
	v_lshlrev_b64 v[52:53], 10, v[52:53]
	v_lshl_add_u64 v[52:53], v[32:33], 0, v[52:53]
	v_cndmask_b32_e64 v0, v3, v0, s[0:1]
	v_rsq_f32_e32 v0, v0
	v_cmp_gt_f32_e32 vcc, s40, v2
	ds_read_b128 v[54:57], v82 offset:64384
	v_mul_f32_e32 v3, 0x45800000, v0
	v_cndmask_b32_e64 v0, v0, v3, s[0:1]
	v_pk_mul_f32 v[6:7], v[6:7], v[0:1] op_sel_hi:[1,0]
	s_nop 0
	v_pk_fma_f32 v[6:7], v[34:35], v[6:7], v[36:37]
	s_nop 0
	v_mul_f32_e32 v0, 0xbfb8aa3b, v6
	v_exp_f32_e32 v0, v0
	s_nop 0
	v_add_f32_e32 v0, 1.0, v0
	v_rcp_f32_e32 v8, v0
	v_mul_f32_e32 v0, 0xbfb8aa3b, v7
	v_exp_f32_e32 v0, v0
	s_nop 0
	v_add_f32_e32 v0, 1.0, v0
	v_rcp_f32_e32 v9, v0
	s_nop 0
	v_pk_mul_f32 v[6:7], v[6:7], v[8:9]
	s_nop 0
	v_cvt_pk_bf16_f32 v0, v6, v7
	global_store_dword v[52:53], v0, off
	v_mul_f32_e32 v0, 0x4b800000, v2
	v_cndmask_b32_e32 v0, v2, v0, vcc
	v_rsq_f32_e32 v0, v0
	ds_read_b128 v[6:9], v82 offset:63872
	v_mul_f32_e32 v2, 0x45800000, v0
	v_cndmask_b32_e32 v0, v0, v2, vcc
	v_pk_add_f32 v[2:3], v[50:51], v[4:5] op_sel_hi:[1,0] neg_lo:[0,1] neg_hi:[0,1]
	ds_read_b128 v[50:53], v82 offset:64128
	v_pk_mul_f32 v[2:3], v[2:3], v[0:1] op_sel_hi:[1,0]
	s_nop 0
	v_pk_fma_f32 v[2:3], v[34:35], v[2:3], v[36:37]
	s_nop 0
	v_mul_f32_e32 v0, 0xbfb8aa3b, v2
	v_exp_f32_e32 v0, v0
	s_nop 0
	v_add_f32_e32 v0, 1.0, v0
	v_rcp_f32_e32 v4, v0
	v_mul_f32_e32 v0, 0xbfb8aa3b, v3
	v_exp_f32_e32 v0, v0
	s_nop 0
	v_add_f32_e32 v0, 1.0, v0
	v_rcp_f32_e32 v5, v0
	s_nop 0
	v_pk_mul_f32 v[2:3], v[2:3], v[4:5]
	s_nop 0
	v_cvt_pk_bf16_f32 v0, v2, v3
	v_or_b32_e32 v2, 15, v10
	v_ashrrev_i32_e32 v3, 31, v2
	v_lshlrev_b64 v[2:3], 10, v[2:3]
	v_lshl_add_u64 v[2:3], v[32:33], 0, v[2:3]
	global_store_dword v[2:3], v0, off
	ds_read_b128 v[2:5], v82 offset:63616
	s_waitcnt lgkmcnt(0)
	v_pk_add_f32 v[2:3], v[2:3], 0 op_sel_hi:[1,0]
	v_pk_add_f32 v[4:5], v[4:5], 0 op_sel_hi:[1,0]
	v_pk_add_f32 v[2:3], v[2:3], v[6:7]
	v_pk_add_f32 v[4:5], v[4:5], v[8:9]
	v_pk_add_f32 v[2:3], v[2:3], v[50:51]
	v_pk_add_f32 v[4:5], v[4:5], v[52:53]
	v_pk_add_f32 v[2:3], v[2:3], v[54:55]
	v_pk_add_f32 v[4:5], v[4:5], v[56:57]
	v_pk_mul_f32 v[2:3], v[2:3], s[68:69] op_sel_hi:[1,0]
	v_pk_mul_f32 v[4:5], v[4:5], s[68:69] op_sel_hi:[1,0]
	v_pk_add_f32 v[6:7], v[48:49], v[2:3] op_sel_hi:[1,0] neg_lo:[0,1] neg_hi:[0,1]
	v_mov_b32_e32 v8, v4
	v_mov_b32_e32 v9, v2
	v_mov_b32_e32 v2, v5
	v_pk_fma_f32 v[2:3], v[8:9], v[8:9], v[2:3] neg_lo:[1,0,0] neg_hi:[1,0,0]
	v_or_b32_e32 v48, 16, v10
	v_pk_add_f32 v[2:3], v[2:3], s[86:87] op_sel_hi:[1,0]
	v_ashrrev_i32_e32 v49, 31, v48
	v_mul_f32_e32 v0, 0x4b800000, v3
	v_cmp_gt_f32_e64 s[0:1], s40, v3
	v_lshlrev_b64 v[48:49], 10, v[48:49]
	v_lshl_add_u64 v[48:49], v[32:33], 0, v[48:49]
	v_cndmask_b32_e64 v0, v3, v0, s[0:1]
	v_rsq_f32_e32 v0, v0
	v_cmp_gt_f32_e32 vcc, s40, v2
	ds_read_b128 v[50:53], v82 offset:64400
	v_mul_f32_e32 v3, 0x45800000, v0
	v_cndmask_b32_e64 v0, v0, v3, s[0:1]
	v_pk_mul_f32 v[6:7], v[6:7], v[0:1] op_sel_hi:[1,0]
	s_nop 0
	v_pk_fma_f32 v[6:7], v[34:35], v[6:7], v[36:37]
	s_nop 0
	v_mul_f32_e32 v0, 0xbfb8aa3b, v6
	v_exp_f32_e32 v0, v0
	s_nop 0
	v_add_f32_e32 v0, 1.0, v0
	v_rcp_f32_e32 v8, v0
	v_mul_f32_e32 v0, 0xbfb8aa3b, v7
	v_exp_f32_e32 v0, v0
	s_nop 0
	v_add_f32_e32 v0, 1.0, v0
	v_rcp_f32_e32 v9, v0
	s_nop 0
	v_pk_mul_f32 v[6:7], v[6:7], v[8:9]
	s_nop 0
	v_cvt_pk_bf16_f32 v0, v6, v7
	global_store_dword v[48:49], v0, off
	v_mul_f32_e32 v0, 0x4b800000, v2
	v_cndmask_b32_e32 v0, v2, v0, vcc
	v_rsq_f32_e32 v0, v0
	ds_read_b128 v[6:9], v82 offset:63888
	v_mul_f32_e32 v2, 0x45800000, v0
	v_cndmask_b32_e32 v0, v0, v2, vcc
	v_pk_add_f32 v[2:3], v[46:47], v[4:5] op_sel_hi:[1,0] neg_lo:[0,1] neg_hi:[0,1]
	ds_read_b128 v[46:49], v82 offset:64144
	v_pk_mul_f32 v[2:3], v[2:3], v[0:1] op_sel_hi:[1,0]
	s_nop 0
	v_pk_fma_f32 v[2:3], v[34:35], v[2:3], v[36:37]
	s_nop 0
	v_mul_f32_e32 v0, 0xbfb8aa3b, v2
	v_exp_f32_e32 v0, v0
	s_nop 0
	v_add_f32_e32 v0, 1.0, v0
	v_rcp_f32_e32 v4, v0
	v_mul_f32_e32 v0, 0xbfb8aa3b, v3
	v_exp_f32_e32 v0, v0
	s_nop 0
	v_add_f32_e32 v0, 1.0, v0
	v_rcp_f32_e32 v5, v0
	s_nop 0
	v_pk_mul_f32 v[2:3], v[2:3], v[4:5]
	s_nop 0
	v_cvt_pk_bf16_f32 v0, v2, v3
	v_or_b32_e32 v2, 17, v10
	v_ashrrev_i32_e32 v3, 31, v2
	v_lshlrev_b64 v[2:3], 10, v[2:3]
	v_lshl_add_u64 v[2:3], v[32:33], 0, v[2:3]
	global_store_dword v[2:3], v0, off
	ds_read_b128 v[2:5], v82 offset:63632
	s_waitcnt lgkmcnt(0)
	v_pk_add_f32 v[2:3], v[2:3], 0 op_sel_hi:[1,0]
	v_pk_add_f32 v[4:5], v[4:5], 0 op_sel_hi:[1,0]
	v_pk_add_f32 v[2:3], v[2:3], v[6:7]
	v_pk_add_f32 v[4:5], v[4:5], v[8:9]
	v_pk_add_f32 v[2:3], v[2:3], v[46:47]
	v_pk_add_f32 v[4:5], v[4:5], v[48:49]
	v_pk_add_f32 v[2:3], v[2:3], v[50:51]
	v_pk_add_f32 v[4:5], v[4:5], v[52:53]
	v_pk_mul_f32 v[2:3], v[2:3], s[68:69] op_sel_hi:[1,0]
	v_pk_mul_f32 v[4:5], v[4:5], s[68:69] op_sel_hi:[1,0]
	v_pk_add_f32 v[6:7], v[44:45], v[2:3] op_sel_hi:[1,0] neg_lo:[0,1] neg_hi:[0,1]
	v_mov_b32_e32 v8, v4
	v_mov_b32_e32 v9, v2
	v_mov_b32_e32 v2, v5
	v_pk_fma_f32 v[2:3], v[8:9], v[8:9], v[2:3] neg_lo:[1,0,0] neg_hi:[1,0,0]
	v_or_b32_e32 v44, 18, v10
	v_pk_add_f32 v[2:3], v[2:3], s[86:87] op_sel_hi:[1,0]
	v_ashrrev_i32_e32 v45, 31, v44
	v_mul_f32_e32 v0, 0x4b800000, v3
	v_cmp_gt_f32_e64 s[0:1], s40, v3
	v_lshlrev_b64 v[44:45], 10, v[44:45]
	v_lshl_add_u64 v[44:45], v[32:33], 0, v[44:45]
	v_cndmask_b32_e64 v0, v3, v0, s[0:1]
	v_rsq_f32_e32 v0, v0
	v_cmp_gt_f32_e32 vcc, s40, v2
	ds_read_b128 v[46:49], v82 offset:64416
	v_mul_f32_e32 v3, 0x45800000, v0
	v_cndmask_b32_e64 v0, v0, v3, s[0:1]
	v_pk_mul_f32 v[6:7], v[6:7], v[0:1] op_sel_hi:[1,0]
	s_nop 0
	v_pk_fma_f32 v[6:7], v[34:35], v[6:7], v[36:37]
	s_nop 0
	v_mul_f32_e32 v0, 0xbfb8aa3b, v6
	v_exp_f32_e32 v0, v0
	s_nop 0
	v_add_f32_e32 v0, 1.0, v0
	v_rcp_f32_e32 v8, v0
	v_mul_f32_e32 v0, 0xbfb8aa3b, v7
	v_exp_f32_e32 v0, v0
	s_nop 0
	v_add_f32_e32 v0, 1.0, v0
	v_rcp_f32_e32 v9, v0
	s_nop 0
	v_pk_mul_f32 v[6:7], v[6:7], v[8:9]
	s_nop 0
	v_cvt_pk_bf16_f32 v0, v6, v7
	global_store_dword v[44:45], v0, off
	v_mul_f32_e32 v0, 0x4b800000, v2
	v_cndmask_b32_e32 v0, v2, v0, vcc
	v_rsq_f32_e32 v0, v0
	ds_read_b128 v[6:9], v82 offset:63904
	v_mul_f32_e32 v2, 0x45800000, v0
	v_cndmask_b32_e32 v0, v0, v2, vcc
	v_pk_add_f32 v[2:3], v[42:43], v[4:5] op_sel_hi:[1,0] neg_lo:[0,1] neg_hi:[0,1]
	ds_read_b128 v[42:45], v82 offset:64160
	v_pk_mul_f32 v[2:3], v[2:3], v[0:1] op_sel_hi:[1,0]
	s_nop 0
	v_pk_fma_f32 v[2:3], v[34:35], v[2:3], v[36:37]
	s_nop 0
	v_mul_f32_e32 v0, 0xbfb8aa3b, v2
	v_exp_f32_e32 v0, v0
	s_nop 0
	v_add_f32_e32 v0, 1.0, v0
	v_rcp_f32_e32 v4, v0
	v_mul_f32_e32 v0, 0xbfb8aa3b, v3
	v_exp_f32_e32 v0, v0
	s_nop 0
	v_add_f32_e32 v0, 1.0, v0
	v_rcp_f32_e32 v5, v0
	s_nop 0
	v_pk_mul_f32 v[2:3], v[2:3], v[4:5]
	s_nop 0
	v_cvt_pk_bf16_f32 v0, v2, v3
	v_or_b32_e32 v2, 19, v10
	v_ashrrev_i32_e32 v3, 31, v2
	v_lshlrev_b64 v[2:3], 10, v[2:3]
	v_lshl_add_u64 v[2:3], v[32:33], 0, v[2:3]
	global_store_dword v[2:3], v0, off
	ds_read_b128 v[2:5], v82 offset:63648
	s_waitcnt lgkmcnt(0)
	v_pk_add_f32 v[2:3], v[2:3], 0 op_sel_hi:[1,0]
	v_pk_add_f32 v[4:5], v[4:5], 0 op_sel_hi:[1,0]
	v_pk_add_f32 v[2:3], v[2:3], v[6:7]
	v_pk_add_f32 v[4:5], v[4:5], v[8:9]
	v_pk_add_f32 v[2:3], v[2:3], v[42:43]
	v_pk_add_f32 v[4:5], v[4:5], v[44:45]
	v_pk_add_f32 v[2:3], v[2:3], v[46:47]
	v_pk_add_f32 v[4:5], v[4:5], v[48:49]
	v_pk_mul_f32 v[2:3], v[2:3], s[68:69] op_sel_hi:[1,0]
	v_pk_mul_f32 v[4:5], v[4:5], s[68:69] op_sel_hi:[1,0]
	v_pk_add_f32 v[6:7], v[40:41], v[2:3] op_sel_hi:[1,0] neg_lo:[0,1] neg_hi:[0,1]
	v_mov_b32_e32 v8, v4
	v_mov_b32_e32 v9, v2
	v_mov_b32_e32 v2, v5
	v_pk_fma_f32 v[2:3], v[8:9], v[8:9], v[2:3] neg_lo:[1,0,0] neg_hi:[1,0,0]
	v_or_b32_e32 v40, 20, v10
	v_pk_add_f32 v[2:3], v[2:3], s[86:87] op_sel_hi:[1,0]
	v_ashrrev_i32_e32 v41, 31, v40
	v_mul_f32_e32 v0, 0x4b800000, v3
	v_cmp_gt_f32_e64 s[0:1], s40, v3
	v_lshlrev_b64 v[40:41], 10, v[40:41]
	v_lshl_add_u64 v[40:41], v[32:33], 0, v[40:41]
	v_cndmask_b32_e64 v0, v3, v0, s[0:1]
	v_rsq_f32_e32 v0, v0
	v_cmp_gt_f32_e32 vcc, s40, v2
	ds_read_b128 v[42:45], v82 offset:64432
	v_mul_f32_e32 v3, 0x45800000, v0
	v_cndmask_b32_e64 v0, v0, v3, s[0:1]
	v_pk_mul_f32 v[6:7], v[6:7], v[0:1] op_sel_hi:[1,0]
	s_nop 0
	v_pk_fma_f32 v[6:7], v[34:35], v[6:7], v[36:37]
	s_nop 0
	v_mul_f32_e32 v0, 0xbfb8aa3b, v6
	v_exp_f32_e32 v0, v0
	s_nop 0
	v_add_f32_e32 v0, 1.0, v0
	v_rcp_f32_e32 v8, v0
	v_mul_f32_e32 v0, 0xbfb8aa3b, v7
	v_exp_f32_e32 v0, v0
	s_nop 0
	v_add_f32_e32 v0, 1.0, v0
	v_rcp_f32_e32 v9, v0
	s_nop 0
	v_pk_mul_f32 v[6:7], v[6:7], v[8:9]
	s_nop 0
	v_cvt_pk_bf16_f32 v0, v6, v7
	global_store_dword v[40:41], v0, off
	v_mul_f32_e32 v0, 0x4b800000, v2
	v_cndmask_b32_e32 v0, v2, v0, vcc
	v_rsq_f32_e32 v0, v0
	ds_read_b128 v[6:9], v82 offset:63920
	v_mul_f32_e32 v2, 0x45800000, v0
	v_cndmask_b32_e32 v0, v0, v2, vcc
	v_pk_add_f32 v[2:3], v[38:39], v[4:5] op_sel_hi:[1,0] neg_lo:[0,1] neg_hi:[0,1]
	ds_read_b128 v[38:41], v82 offset:64176
	v_pk_mul_f32 v[2:3], v[2:3], v[0:1] op_sel_hi:[1,0]
	s_nop 0
	v_pk_fma_f32 v[2:3], v[34:35], v[2:3], v[36:37]
	s_nop 0
	v_mul_f32_e32 v0, 0xbfb8aa3b, v2
	v_exp_f32_e32 v0, v0
	s_nop 0
	v_add_f32_e32 v0, 1.0, v0
	v_rcp_f32_e32 v4, v0
	v_mul_f32_e32 v0, 0xbfb8aa3b, v3
	v_exp_f32_e32 v0, v0
	s_nop 0
	v_add_f32_e32 v0, 1.0, v0
	v_rcp_f32_e32 v5, v0
	s_nop 0
	v_pk_mul_f32 v[2:3], v[2:3], v[4:5]
	s_nop 0
	v_cvt_pk_bf16_f32 v0, v2, v3
	v_or_b32_e32 v2, 21, v10
	v_ashrrev_i32_e32 v3, 31, v2
	v_lshlrev_b64 v[2:3], 10, v[2:3]
	v_lshl_add_u64 v[2:3], v[32:33], 0, v[2:3]
	global_store_dword v[2:3], v0, off
	ds_read_b128 v[2:5], v82 offset:63664
	s_waitcnt lgkmcnt(0)
	v_pk_add_f32 v[2:3], v[2:3], 0 op_sel_hi:[1,0]
	v_pk_add_f32 v[4:5], v[4:5], 0 op_sel_hi:[1,0]
	v_pk_add_f32 v[2:3], v[2:3], v[6:7]
	v_pk_add_f32 v[4:5], v[4:5], v[8:9]
	v_pk_add_f32 v[2:3], v[2:3], v[38:39]
	v_pk_add_f32 v[4:5], v[4:5], v[40:41]
	v_pk_add_f32 v[2:3], v[2:3], v[42:43]
	v_pk_add_f32 v[4:5], v[4:5], v[44:45]
	v_pk_mul_f32 v[2:3], v[2:3], s[68:69] op_sel_hi:[1,0]
	v_pk_mul_f32 v[4:5], v[4:5], s[68:69] op_sel_hi:[1,0]
	v_pk_add_f32 v[6:7], v[30:31], v[2:3] op_sel_hi:[1,0] neg_lo:[0,1] neg_hi:[0,1]
	v_mov_b32_e32 v8, v4
	v_mov_b32_e32 v9, v2
	v_mov_b32_e32 v2, v5
	v_pk_fma_f32 v[2:3], v[8:9], v[8:9], v[2:3] neg_lo:[1,0,0] neg_hi:[1,0,0]
	v_or_b32_e32 v30, 22, v10
	v_pk_add_f32 v[2:3], v[2:3], s[86:87] op_sel_hi:[1,0]
	v_ashrrev_i32_e32 v31, 31, v30
	v_mul_f32_e32 v0, 0x4b800000, v3
	v_cmp_gt_f32_e64 s[0:1], s40, v3
	v_lshlrev_b64 v[30:31], 10, v[30:31]
	v_lshl_add_u64 v[30:31], v[32:33], 0, v[30:31]
	v_cndmask_b32_e64 v0, v3, v0, s[0:1]
	v_rsq_f32_e32 v0, v0
	v_cmp_gt_f32_e32 vcc, s40, v2
	ds_read_b128 v[38:41], v82 offset:64448
	v_mul_f32_e32 v3, 0x45800000, v0
	v_cndmask_b32_e64 v0, v0, v3, s[0:1]
	v_pk_mul_f32 v[6:7], v[6:7], v[0:1] op_sel_hi:[1,0]
	s_nop 0
	v_pk_fma_f32 v[6:7], v[34:35], v[6:7], v[36:37]
	s_nop 0
	v_mul_f32_e32 v0, 0xbfb8aa3b, v6
	v_exp_f32_e32 v0, v0
	s_nop 0
	v_add_f32_e32 v0, 1.0, v0
	v_rcp_f32_e32 v8, v0
	v_mul_f32_e32 v0, 0xbfb8aa3b, v7
	v_exp_f32_e32 v0, v0
	s_nop 0
	v_add_f32_e32 v0, 1.0, v0
	v_rcp_f32_e32 v9, v0
	s_nop 0
	v_pk_mul_f32 v[6:7], v[6:7], v[8:9]
	s_nop 0
	v_cvt_pk_bf16_f32 v0, v6, v7
	global_store_dword v[30:31], v0, off
	v_mul_f32_e32 v0, 0x4b800000, v2
	v_cndmask_b32_e32 v0, v2, v0, vcc
	v_rsq_f32_e32 v0, v0
	ds_read_b128 v[6:9], v82 offset:63936
	v_mul_f32_e32 v2, 0x45800000, v0
	v_cndmask_b32_e32 v0, v0, v2, vcc
	v_pk_add_f32 v[2:3], v[28:29], v[4:5] op_sel_hi:[1,0] neg_lo:[0,1] neg_hi:[0,1]
	ds_read_b128 v[28:31], v82 offset:64192
	v_pk_mul_f32 v[2:3], v[2:3], v[0:1] op_sel_hi:[1,0]
	s_nop 0
	v_pk_fma_f32 v[2:3], v[34:35], v[2:3], v[36:37]
	s_nop 0
	v_mul_f32_e32 v0, 0xbfb8aa3b, v2
	v_exp_f32_e32 v0, v0
	s_nop 0
	v_add_f32_e32 v0, 1.0, v0
	v_rcp_f32_e32 v4, v0
	v_mul_f32_e32 v0, 0xbfb8aa3b, v3
	v_exp_f32_e32 v0, v0
	s_nop 0
	v_add_f32_e32 v0, 1.0, v0
	v_rcp_f32_e32 v5, v0
	s_nop 0
	v_pk_mul_f32 v[2:3], v[2:3], v[4:5]
	s_nop 0
	v_cvt_pk_bf16_f32 v0, v2, v3
	v_or_b32_e32 v2, 23, v10
	v_ashrrev_i32_e32 v3, 31, v2
	v_lshlrev_b64 v[2:3], 10, v[2:3]
	v_lshl_add_u64 v[2:3], v[32:33], 0, v[2:3]
	global_store_dword v[2:3], v0, off
	ds_read_b128 v[2:5], v82 offset:63680
	s_waitcnt lgkmcnt(0)
	v_pk_add_f32 v[2:3], v[2:3], 0 op_sel_hi:[1,0]
	v_pk_add_f32 v[4:5], v[4:5], 0 op_sel_hi:[1,0]
	v_pk_add_f32 v[2:3], v[2:3], v[6:7]
	v_pk_add_f32 v[4:5], v[4:5], v[8:9]
	v_pk_add_f32 v[2:3], v[2:3], v[28:29]
	v_pk_add_f32 v[4:5], v[4:5], v[30:31]
	v_pk_add_f32 v[2:3], v[2:3], v[38:39]
	v_pk_add_f32 v[4:5], v[4:5], v[40:41]
	v_pk_mul_f32 v[2:3], v[2:3], s[68:69] op_sel_hi:[1,0]
	v_pk_mul_f32 v[4:5], v[4:5], s[68:69] op_sel_hi:[1,0]
	v_pk_add_f32 v[6:7], v[26:27], v[2:3] op_sel_hi:[1,0] neg_lo:[0,1] neg_hi:[0,1]
	v_mov_b32_e32 v8, v4
	v_mov_b32_e32 v9, v2
	v_mov_b32_e32 v2, v5
	v_pk_fma_f32 v[2:3], v[8:9], v[8:9], v[2:3] neg_lo:[1,0,0] neg_hi:[1,0,0]
	v_or_b32_e32 v26, 24, v10
	v_pk_add_f32 v[2:3], v[2:3], s[86:87] op_sel_hi:[1,0]
	v_ashrrev_i32_e32 v27, 31, v26
	v_mul_f32_e32 v0, 0x4b800000, v3
	v_cmp_gt_f32_e64 s[0:1], s40, v3
	v_lshlrev_b64 v[26:27], 10, v[26:27]
	v_lshl_add_u64 v[26:27], v[32:33], 0, v[26:27]
	v_cndmask_b32_e64 v0, v3, v0, s[0:1]
	v_rsq_f32_e32 v0, v0
	v_cmp_gt_f32_e32 vcc, s40, v2
	ds_read_b128 v[28:31], v82 offset:64464
	v_mul_f32_e32 v3, 0x45800000, v0
	v_cndmask_b32_e64 v0, v0, v3, s[0:1]
	v_pk_mul_f32 v[6:7], v[6:7], v[0:1] op_sel_hi:[1,0]
	s_nop 0
	v_pk_fma_f32 v[6:7], v[34:35], v[6:7], v[36:37]
	s_nop 0
	v_mul_f32_e32 v0, 0xbfb8aa3b, v6
	v_exp_f32_e32 v0, v0
	s_nop 0
	v_add_f32_e32 v0, 1.0, v0
	v_rcp_f32_e32 v8, v0
	v_mul_f32_e32 v0, 0xbfb8aa3b, v7
	v_exp_f32_e32 v0, v0
	s_nop 0
	v_add_f32_e32 v0, 1.0, v0
	v_rcp_f32_e32 v9, v0
	s_nop 0
	v_pk_mul_f32 v[6:7], v[6:7], v[8:9]
	s_nop 0
	v_cvt_pk_bf16_f32 v0, v6, v7
	global_store_dword v[26:27], v0, off
	v_mul_f32_e32 v0, 0x4b800000, v2
	v_cndmask_b32_e32 v0, v2, v0, vcc
	v_rsq_f32_e32 v0, v0
	ds_read_b128 v[6:9], v82 offset:63952
	v_mul_f32_e32 v2, 0x45800000, v0
	v_cndmask_b32_e32 v0, v0, v2, vcc
	v_pk_add_f32 v[2:3], v[24:25], v[4:5] op_sel_hi:[1,0] neg_lo:[0,1] neg_hi:[0,1]
	ds_read_b128 v[24:27], v82 offset:64208
	v_pk_mul_f32 v[2:3], v[2:3], v[0:1] op_sel_hi:[1,0]
	s_nop 0
	v_pk_fma_f32 v[2:3], v[34:35], v[2:3], v[36:37]
	s_nop 0
	v_mul_f32_e32 v0, 0xbfb8aa3b, v2
	v_exp_f32_e32 v0, v0
	s_nop 0
	v_add_f32_e32 v0, 1.0, v0
	v_rcp_f32_e32 v4, v0
	v_mul_f32_e32 v0, 0xbfb8aa3b, v3
	v_exp_f32_e32 v0, v0
	s_nop 0
	v_add_f32_e32 v0, 1.0, v0
	v_rcp_f32_e32 v5, v0
	s_nop 0
	v_pk_mul_f32 v[2:3], v[2:3], v[4:5]
	s_nop 0
	v_cvt_pk_bf16_f32 v0, v2, v3
	v_or_b32_e32 v2, 25, v10
	v_ashrrev_i32_e32 v3, 31, v2
	v_lshlrev_b64 v[2:3], 10, v[2:3]
	v_lshl_add_u64 v[2:3], v[32:33], 0, v[2:3]
	global_store_dword v[2:3], v0, off
	ds_read_b128 v[2:5], v82 offset:63696
	s_waitcnt lgkmcnt(0)
	v_pk_add_f32 v[2:3], v[2:3], 0 op_sel_hi:[1,0]
	v_pk_add_f32 v[4:5], v[4:5], 0 op_sel_hi:[1,0]
	v_pk_add_f32 v[2:3], v[2:3], v[6:7]
	v_pk_add_f32 v[4:5], v[4:5], v[8:9]
	v_pk_add_f32 v[2:3], v[2:3], v[24:25]
	v_pk_add_f32 v[4:5], v[4:5], v[26:27]
	v_pk_add_f32 v[2:3], v[2:3], v[28:29]
	v_pk_add_f32 v[4:5], v[4:5], v[30:31]
	v_pk_mul_f32 v[2:3], v[2:3], s[68:69] op_sel_hi:[1,0]
	v_pk_mul_f32 v[4:5], v[4:5], s[68:69] op_sel_hi:[1,0]
	v_pk_add_f32 v[6:7], v[22:23], v[2:3] op_sel_hi:[1,0] neg_lo:[0,1] neg_hi:[0,1]
	v_mov_b32_e32 v8, v4
	v_mov_b32_e32 v9, v2
	v_mov_b32_e32 v2, v5
	v_pk_fma_f32 v[2:3], v[8:9], v[8:9], v[2:3] neg_lo:[1,0,0] neg_hi:[1,0,0]
	v_or_b32_e32 v22, 26, v10
	v_pk_add_f32 v[2:3], v[2:3], s[86:87] op_sel_hi:[1,0]
	v_ashrrev_i32_e32 v23, 31, v22
	v_mul_f32_e32 v0, 0x4b800000, v3
	v_cmp_gt_f32_e64 s[0:1], s40, v3
	v_lshlrev_b64 v[22:23], 10, v[22:23]
	v_lshl_add_u64 v[22:23], v[32:33], 0, v[22:23]
	v_cndmask_b32_e64 v0, v3, v0, s[0:1]
	v_rsq_f32_e32 v0, v0
	v_cmp_gt_f32_e32 vcc, s40, v2
	ds_read_b128 v[24:27], v82 offset:64480
	v_mul_f32_e32 v3, 0x45800000, v0
	v_cndmask_b32_e64 v0, v0, v3, s[0:1]
	v_pk_mul_f32 v[6:7], v[6:7], v[0:1] op_sel_hi:[1,0]
	s_nop 0
	v_pk_fma_f32 v[6:7], v[34:35], v[6:7], v[36:37]
	s_nop 0
	v_mul_f32_e32 v0, 0xbfb8aa3b, v6
	v_exp_f32_e32 v0, v0
	s_nop 0
	v_add_f32_e32 v0, 1.0, v0
	v_rcp_f32_e32 v8, v0
	v_mul_f32_e32 v0, 0xbfb8aa3b, v7
	v_exp_f32_e32 v0, v0
	s_nop 0
	v_add_f32_e32 v0, 1.0, v0
	v_rcp_f32_e32 v9, v0
	s_nop 0
	v_pk_mul_f32 v[6:7], v[6:7], v[8:9]
	s_nop 0
	v_cvt_pk_bf16_f32 v0, v6, v7
	global_store_dword v[22:23], v0, off
	v_mul_f32_e32 v0, 0x4b800000, v2
	v_cndmask_b32_e32 v0, v2, v0, vcc
	v_rsq_f32_e32 v0, v0
	ds_read_b128 v[6:9], v82 offset:63968
	v_mul_f32_e32 v2, 0x45800000, v0
	v_cndmask_b32_e32 v0, v0, v2, vcc
	v_pk_add_f32 v[2:3], v[20:21], v[4:5] op_sel_hi:[1,0] neg_lo:[0,1] neg_hi:[0,1]
	ds_read_b128 v[20:23], v82 offset:64224
	v_pk_mul_f32 v[2:3], v[2:3], v[0:1] op_sel_hi:[1,0]
	s_nop 0
	v_pk_fma_f32 v[2:3], v[34:35], v[2:3], v[36:37]
	s_nop 0
	v_mul_f32_e32 v0, 0xbfb8aa3b, v2
	v_exp_f32_e32 v0, v0
	s_nop 0
	v_add_f32_e32 v0, 1.0, v0
	v_rcp_f32_e32 v4, v0
	v_mul_f32_e32 v0, 0xbfb8aa3b, v3
	v_exp_f32_e32 v0, v0
	s_nop 0
	v_add_f32_e32 v0, 1.0, v0
	v_rcp_f32_e32 v5, v0
	s_nop 0
	v_pk_mul_f32 v[2:3], v[2:3], v[4:5]
	s_nop 0
	v_cvt_pk_bf16_f32 v0, v2, v3
	v_or_b32_e32 v2, 27, v10
	v_ashrrev_i32_e32 v3, 31, v2
	v_lshlrev_b64 v[2:3], 10, v[2:3]
	v_lshl_add_u64 v[2:3], v[32:33], 0, v[2:3]
	global_store_dword v[2:3], v0, off
	ds_read_b128 v[2:5], v82 offset:63712
	s_waitcnt lgkmcnt(0)
	v_pk_add_f32 v[2:3], v[2:3], 0 op_sel_hi:[1,0]
	v_pk_add_f32 v[4:5], v[4:5], 0 op_sel_hi:[1,0]
	v_pk_add_f32 v[2:3], v[2:3], v[6:7]
	v_pk_add_f32 v[4:5], v[4:5], v[8:9]
	v_pk_add_f32 v[2:3], v[2:3], v[20:21]
	v_pk_add_f32 v[4:5], v[4:5], v[22:23]
	v_pk_add_f32 v[2:3], v[2:3], v[24:25]
	v_pk_add_f32 v[4:5], v[4:5], v[26:27]
	v_pk_mul_f32 v[2:3], v[2:3], s[68:69] op_sel_hi:[1,0]
	v_pk_mul_f32 v[4:5], v[4:5], s[68:69] op_sel_hi:[1,0]
	v_pk_add_f32 v[6:7], v[18:19], v[2:3] op_sel_hi:[1,0] neg_lo:[0,1] neg_hi:[0,1]
	v_mov_b32_e32 v8, v4
	v_mov_b32_e32 v9, v2
	v_mov_b32_e32 v2, v5
	v_pk_fma_f32 v[2:3], v[8:9], v[8:9], v[2:3] neg_lo:[1,0,0] neg_hi:[1,0,0]
	v_or_b32_e32 v18, 28, v10
	v_pk_add_f32 v[2:3], v[2:3], s[86:87] op_sel_hi:[1,0]
	v_ashrrev_i32_e32 v19, 31, v18
	v_mul_f32_e32 v0, 0x4b800000, v3
	v_cmp_gt_f32_e64 s[0:1], s40, v3
	v_lshlrev_b64 v[18:19], 10, v[18:19]
	v_lshl_add_u64 v[18:19], v[32:33], 0, v[18:19]
	v_cndmask_b32_e64 v0, v3, v0, s[0:1]
	v_rsq_f32_e32 v0, v0
	v_cmp_gt_f32_e32 vcc, s40, v2
	ds_read_b128 v[20:23], v82 offset:64496
	v_mul_f32_e32 v3, 0x45800000, v0
	v_cndmask_b32_e64 v0, v0, v3, s[0:1]
	v_pk_mul_f32 v[6:7], v[6:7], v[0:1] op_sel_hi:[1,0]
	s_nop 0
	v_pk_fma_f32 v[6:7], v[34:35], v[6:7], v[36:37]
	s_nop 0
	v_mul_f32_e32 v0, 0xbfb8aa3b, v6
	v_exp_f32_e32 v0, v0
	s_nop 0
	v_add_f32_e32 v0, 1.0, v0
	v_rcp_f32_e32 v8, v0
	v_mul_f32_e32 v0, 0xbfb8aa3b, v7
	v_exp_f32_e32 v0, v0
	s_nop 0
	v_add_f32_e32 v0, 1.0, v0
	v_rcp_f32_e32 v9, v0
	s_nop 0
	v_pk_mul_f32 v[6:7], v[6:7], v[8:9]
	s_nop 0
	v_cvt_pk_bf16_f32 v0, v6, v7
	global_store_dword v[18:19], v0, off
	v_mul_f32_e32 v0, 0x4b800000, v2
	v_cndmask_b32_e32 v0, v2, v0, vcc
	v_rsq_f32_e32 v0, v0
	ds_read_b128 v[6:9], v82 offset:63984
	v_mul_f32_e32 v2, 0x45800000, v0
	v_cndmask_b32_e32 v0, v0, v2, vcc
	v_pk_add_f32 v[2:3], v[16:17], v[4:5] op_sel_hi:[1,0] neg_lo:[0,1] neg_hi:[0,1]
	ds_read_b128 v[16:19], v82 offset:64240
	v_pk_mul_f32 v[2:3], v[2:3], v[0:1] op_sel_hi:[1,0]
	s_nop 0
	v_pk_fma_f32 v[2:3], v[34:35], v[2:3], v[36:37]
	s_nop 0
	v_mul_f32_e32 v0, 0xbfb8aa3b, v2
	v_exp_f32_e32 v0, v0
	s_nop 0
	v_add_f32_e32 v0, 1.0, v0
	v_rcp_f32_e32 v4, v0
	v_mul_f32_e32 v0, 0xbfb8aa3b, v3
	v_exp_f32_e32 v0, v0
	s_nop 0
	v_add_f32_e32 v0, 1.0, v0
	v_rcp_f32_e32 v5, v0
	s_nop 0
	v_pk_mul_f32 v[2:3], v[2:3], v[4:5]
	s_nop 0
	v_cvt_pk_bf16_f32 v0, v2, v3
	v_or_b32_e32 v2, 29, v10
	v_ashrrev_i32_e32 v3, 31, v2
	v_lshlrev_b64 v[2:3], 10, v[2:3]
	v_lshl_add_u64 v[2:3], v[32:33], 0, v[2:3]
	global_store_dword v[2:3], v0, off
	ds_read_b128 v[2:5], v82 offset:63728
	s_waitcnt lgkmcnt(0)
	v_pk_add_f32 v[2:3], v[2:3], 0 op_sel_hi:[1,0]
	v_pk_add_f32 v[4:5], v[4:5], 0 op_sel_hi:[1,0]
	v_pk_add_f32 v[2:3], v[2:3], v[6:7]
	v_pk_add_f32 v[4:5], v[4:5], v[8:9]
	v_pk_add_f32 v[2:3], v[2:3], v[16:17]
	v_pk_add_f32 v[4:5], v[4:5], v[18:19]
	v_pk_add_f32 v[2:3], v[2:3], v[20:21]
	v_pk_add_f32 v[4:5], v[4:5], v[22:23]
	v_pk_mul_f32 v[2:3], v[2:3], s[68:69] op_sel_hi:[1,0]
	v_pk_mul_f32 v[4:5], v[4:5], s[68:69] op_sel_hi:[1,0]
	v_pk_add_f32 v[6:7], v[14:15], v[2:3] op_sel_hi:[1,0] neg_lo:[0,1] neg_hi:[0,1]
	v_mov_b32_e32 v8, v4
	v_mov_b32_e32 v9, v2
	v_mov_b32_e32 v2, v5
	v_pk_fma_f32 v[2:3], v[8:9], v[8:9], v[2:3] neg_lo:[1,0,0] neg_hi:[1,0,0]
	v_or_b32_e32 v14, 30, v10
	v_pk_add_f32 v[2:3], v[2:3], s[86:87] op_sel_hi:[1,0]
	v_ashrrev_i32_e32 v15, 31, v14
	v_mul_f32_e32 v0, 0x4b800000, v3
	v_cmp_gt_f32_e64 s[0:1], s40, v3
	v_lshlrev_b64 v[14:15], 10, v[14:15]
	v_lshl_add_u64 v[14:15], v[32:33], 0, v[14:15]
	v_cndmask_b32_e64 v0, v3, v0, s[0:1]
	v_rsq_f32_e32 v0, v0
	v_cmp_gt_f32_e32 vcc, s40, v2
	v_mul_f32_e32 v3, 0x45800000, v0
	v_cndmask_b32_e64 v0, v0, v3, s[0:1]
	v_pk_mul_f32 v[6:7], v[6:7], v[0:1] op_sel_hi:[1,0]
	s_nop 0
	v_pk_fma_f32 v[6:7], v[34:35], v[6:7], v[36:37]
	s_nop 0
	v_mul_f32_e32 v0, 0xbfb8aa3b, v6
	v_exp_f32_e32 v0, v0
	s_nop 0
	v_add_f32_e32 v0, 1.0, v0
	v_rcp_f32_e32 v8, v0
	v_mul_f32_e32 v0, 0xbfb8aa3b, v7
	v_exp_f32_e32 v0, v0
	s_nop 0
	v_add_f32_e32 v0, 1.0, v0
	v_rcp_f32_e32 v9, v0
	s_nop 0
	v_pk_mul_f32 v[6:7], v[6:7], v[8:9]
	s_nop 0
	v_cvt_pk_bf16_f32 v0, v6, v7
	global_store_dword v[14:15], v0, off
	v_mul_f32_e32 v0, 0x4b800000, v2
	v_cndmask_b32_e32 v0, v2, v0, vcc
	v_rsq_f32_e32 v0, v0
	s_nop 0
	v_mul_f32_e32 v2, 0x45800000, v0
	v_cndmask_b32_e32 v0, v0, v2, vcc
	v_pk_add_f32 v[2:3], v[12:13], v[4:5] op_sel_hi:[1,0] neg_lo:[0,1] neg_hi:[0,1]
	s_nop 0
	v_pk_mul_f32 v[2:3], v[2:3], v[0:1] op_sel_hi:[1,0]
	s_nop 0
	v_pk_fma_f32 v[2:3], v[34:35], v[2:3], v[36:37]
	s_nop 0
	v_mul_f32_e32 v0, 0xbfb8aa3b, v2
	v_exp_f32_e32 v0, v0
	s_nop 0
	v_add_f32_e32 v0, 1.0, v0
	v_rcp_f32_e32 v4, v0
	v_mul_f32_e32 v0, 0xbfb8aa3b, v3
	v_exp_f32_e32 v0, v0
	s_nop 0
	v_add_f32_e32 v0, 1.0, v0
	v_rcp_f32_e32 v5, v0
	s_nop 0
	v_pk_mul_f32 v[2:3], v[2:3], v[4:5]
	s_nop 0
	v_cvt_pk_bf16_f32 v0, v2, v3
	v_or_b32_e32 v2, 31, v10
	v_ashrrev_i32_e32 v3, 31, v2
	v_lshlrev_b64 v[2:3], 10, v[2:3]
	v_lshl_add_u64 v[2:3], v[32:33], 0, v[2:3]
	global_store_dword v[2:3], v0, off

	.amdhsa_kernel _Z14fwd_megakernel6Params
		.amdhsa_group_segment_fixed_size 16
		.amdhsa_private_segment_fixed_size 0
		.amdhsa_kernarg_size 456
		.amdhsa_user_sgpr_count 2
		.amdhsa_user_sgpr_dispatch_ptr 0
		.amdhsa_user_sgpr_queue_ptr 0
		.amdhsa_user_sgpr_kernarg_segment_ptr 1
		.amdhsa_user_sgpr_dispatch_id 0
		.amdhsa_user_sgpr_kernarg_preload_length 0
		.amdhsa_user_sgpr_kernarg_preload_offset 0
		.amdhsa_user_sgpr_private_segment_size 0
		.amdhsa_uses_dynamic_stack 0
		.amdhsa_enable_private_segment 0
		.amdhsa_system_sgpr_workgroup_id_x 1
		.amdhsa_system_sgpr_workgroup_id_y 0
		.amdhsa_system_sgpr_workgroup_id_z 0
		.amdhsa_system_sgpr_workgroup_info 0
		.amdhsa_system_vgpr_workitem_id 2
		.amdhsa_next_free_vgpr 256
		.amdhsa_next_free_sgpr 100
		.amdhsa_accum_offset 256
		.amdhsa_reserve_vcc 1
		.amdhsa_float_round_mode_32 0
		.amdhsa_float_round_mode_16_64 0
		.amdhsa_float_denorm_mode_32 3
		.amdhsa_float_denorm_mode_16_64 3
		.amdhsa_dx10_clamp 1
		.amdhsa_ieee_mode 1
		.amdhsa_fp16_overflow 0
		.amdhsa_tg_split 0
		.amdhsa_exception_fp_ieee_invalid_op 0
		.amdhsa_exception_fp_denorm_src 0
		.amdhsa_exception_fp_ieee_div_zero 0
		.amdhsa_exception_fp_ieee_overflow 0
		.amdhsa_exception_fp_ieee_underflow 0
		.amdhsa_exception_fp_ieee_inexact 0
		.amdhsa_exception_int_div_zero 0
	.end_amdhsa_kernel

amdhsa.kernels:
  - .agpr_count:     0
    .args:
      - .offset:         0
        .size:           200
        .value_kind:     by_value
      - .offset:         200
        .size:           4
        .value_kind:     hidden_block_count_x
      - .offset:         204
        .size:           4
        .value_kind:     hidden_block_count_y
      - .offset:         208
        .size:           4
        .value_kind:     hidden_block_count_z
      - .offset:         212
        .size:           2
        .value_kind:     hidden_group_size_x
      - .offset:         214
        .size:           2
        .value_kind:     hidden_group_size_y
      - .offset:         216
        .size:           2
        .value_kind:     hidden_group_size_z
      - .offset:         218
        .size:           2
        .value_kind:     hidden_remainder_x
      - .offset:         220
        .size:           2
        .value_kind:     hidden_remainder_y
      - .offset:         222
        .size:           2
        .value_kind:     hidden_remainder_z
      - .offset:         240
        .size:           8
        .value_kind:     hidden_global_offset_x
      - .offset:         248
        .size:           8
        .value_kind:     hidden_global_offset_y
      - .offset:         256
        .size:           8
        .value_kind:     hidden_global_offset_z
      - .offset:         264
        .size:           2
        .value_kind:     hidden_grid_dims
      - .offset:         288
        .size:           8
        .value_kind:     hidden_multigrid_sync_arg
      - .offset:         320
        .size:           4
        .value_kind:     hidden_dynamic_lds_size
    .group_segment_fixed_size: 16
    .kernarg_segment_align: 8
    .kernarg_segment_size: 456
    .language:       OpenCL C
    .language_version:
      - 2
      - 0
    .max_flat_workgroup_size: 512
    .name:           _Z14fwd_megakernel6Params
    .private_segment_fixed_size: 0
    .sgpr_count:     106
    .sgpr_spill_count: 118
    .symbol:         _Z14fwd_megakernel6Params.kd
    .uniform_work_group_size: 1
    .uses_dynamic_stack: false
    .vgpr_count:     256
    .vgpr_spill_count: 0
    .wavefront_size: 64
